# first grid barrier: the 16 registration-counter loads issued in front of the P0 store drain / workgroup barrier and checked behind it (fallback = original loop)
# speedup vs baseline: 1.0051x; 1.0051x over previous
; __device__ __forceinline__ unsigned xb_ld(unsigned* p)              { return __hip_atomic_load(p, __ATOMIC_RELAXED, __HIP_MEMORY_SCOPE_AGENT); }
; __device__ __forceinline__ void xcd_barrier_complete(unsigned* bar, unsigned x, unsigned& nloc, unsigned& nx) {
;     const unsigned G = gridDim.x * gridDim.y * gridDim.z;
;     unsigned sum, cnt, mine, sp = 0u;
;     for (;;) {
;         sum = 0u; cnt = 0u; mine = 0u;
; #pragma unroll
;         for (unsigned j = 0; j < 16; ++j) { const unsigned c = xb_ld(&bar[XB_XCNT(j)]); sum += c; cnt += (c > 0u) ? 1u : 0u; mine = (j == x) ? c : mine; }
;         if (sum == G) break;
;         __builtin_amdgcn_s_sleep(1);
;         if ((++sp & 255u) == 0u) { if (xb_ld(&bar[XB_TMO])) break; if (sp > XB_SPIN_CAP) { atomicAdd(&bar[XB_TMO], 1u); break; } }
;     }
;     nloc = mine > 0u ? mine : 1u; nx = cnt > 0u ? cnt : 1u;
; }
; __device__ __forceinline__ void xcd_barrier(const XcdBarrier& b) {
;     asm volatile("s_waitcnt vmcnt(0)" ::: "memory");
;     __syncthreads();
;     if (threadIdx.x == 0) {
;         unsigned* bar = b.bar;
;         __builtin_amdgcn_s_waitcnt(0);
;         unsigned nloc = b.st[0], nx = b.st[1];
;         if (nloc == 0u) { xcd_barrier_complete(bar, b.x, nloc, nx); b.st[0] = nloc; b.st[1] = nx; }
.LBB0_32:
	s_mov_b64 s[100:101], exec
	s_and_b64 exec, exec, s[62:63]
	s_cbranch_execz .Lcensus_pf_skip
	v_mov_b32_e32 v254, 0
	v_mov_b32_e32 v255, 0x1000
	global_load_dword v236, v254, s[90:91] offset:1024 sc1
	global_load_dword v237, v254, s[90:91] offset:1280 sc1
	global_load_dword v238, v254, s[90:91] offset:1536 sc1
	global_load_dword v239, v254, s[90:91] offset:1792 sc1
	global_load_dword v240, v254, s[90:91] offset:2048 sc1
	global_load_dword v241, v254, s[90:91] offset:2304 sc1
	global_load_dword v242, v254, s[90:91] offset:2560 sc1
	global_load_dword v243, v254, s[90:91] offset:2816 sc1
	global_load_dword v244, v254, s[90:91] offset:3072 sc1
	global_load_dword v245, v254, s[90:91] offset:3328 sc1
	global_load_dword v246, v254, s[90:91] offset:3584 sc1
	global_load_dword v247, v254, s[90:91] offset:3840 sc1
	global_load_dword v248, v255, s[90:91] sc1
	global_load_dword v249, v255, s[90:91] offset:256 sc1
	global_load_dword v250, v255, s[90:91] offset:512 sc1
	global_load_dword v251, v255, s[90:91] offset:768 sc1
.Lcensus_pf_skip:
	s_mov_b64 exec, s[100:101]
	s_waitcnt vmcnt(0)
	s_barrier
	s_and_saveexec_b64 s[0:1], s[62:63]
	s_cbranch_execz .LBB0_99
	s_add_i32 s3, 0, 0x20160
	v_mov_b32_e32 v1, s3
	s_waitcnt vmcnt(0) expcnt(0) lgkmcnt(0)
	ds_read_b32 v3, v1
	s_add_i32 s3, 0, 0x20164
	v_mov_b32_e32 v1, s3
	ds_read_b32 v2, v1
	s_waitcnt lgkmcnt(1)
	v_cmp_ne_u32_e32 vcc, 0, v3
	s_cbranch_vccnz .LBB0_48
	s_load_dwordx2 s[10:11], s[52:53], 0x4
	s_add_u32 s4, s90, 0x1000
	s_addc_u32 s5, s91, 0
	s_add_u32 s8, s90, 0x1100
	s_addc_u32 s9, s91, 0
	s_waitcnt lgkmcnt(0)
	s_mul_i32 s3, s10, s33
	s_add_u32 s10, s90, 0x1200
	s_mul_i32 s3, s3, s11
	s_addc_u32 s11, s91, 0
	s_add_u32 s12, s90, 0x1300
	s_addc_u32 s13, s91, 0
	s_mov_b32 s20, 1
	v_mov_b32_e32 v17, 0
	s_branch .Lcensus_first
.Lcensus_first:
	s_waitcnt vmcnt(0)
	v_add3_u32 v18, v236, v237, v238
	v_add3_u32 v18, v18, v239, v240
	v_add3_u32 v18, v18, v241, v242
	v_add3_u32 v18, v18, v243, v244
	v_add3_u32 v18, v18, v245, v246
	v_add3_u32 v18, v18, v247, v248
	v_add3_u32 v18, v18, v249, v250
	v_add_u32_e32 v18, v18, v251
	v_cmp_eq_u32_e32 vcc, s3, v18
	s_cbranch_vccz .LBB0_36
	v_mov_b32_e32 v16, v236
	v_mov_b32_e32 v1, v237
	v_mov_b32_e32 v2, v238
	v_mov_b32_e32 v3, v239
	v_mov_b32_e32 v4, v240
	v_mov_b32_e32 v5, v241
	v_mov_b32_e32 v6, v242
	v_mov_b32_e32 v7, v243
	v_mov_b32_e32 v8, v244
	v_mov_b32_e32 v9, v245
	v_mov_b32_e32 v10, v246
	v_mov_b32_e32 v11, v247
	v_mov_b32_e32 v12, v248
	v_mov_b32_e32 v13, v249
	v_mov_b32_e32 v14, v250
	v_mov_b32_e32 v15, v251
	s_mov_b64 s[14:15], -1
	s_mov_b64 s[16:17], -1
	s_branch .LBB0_35

; #define LAS __attribute__((address_space(3)))
; #define MFMA32(a, b, c) __builtin_amdgcn_mfma_f32_32x32x16_bf16((a), (b), (c), 0, 0, 0)
; __device__ __forceinline__ void route_task(int task, int tl0, const bf16* QP  , const LAS bf16* KHL, LAS unsigned short* EL, LAS float* GL, int lane) {
;     ...
;     { unsigned qo = (unsigned)t * (unsigned)D + (unsigned)(head * 128 + 8 * hi); asm volatile("" : "+v"(qo)); const bf16* qp = QP + qo;
; #pragma unroll
;       for (int hf = 0; hf < 2; ++hf)
; #pragma unroll
;         for (int ks = 0; ks < 4; ++ks) qa[hf][ks] = ldg8(qp + 64 * hf + 16 * ks); }
; #pragma unroll
;     for (int half = 0; half < 2; ++half) {
;         int cur[16];
; #pragma unroll
;         for (int kt = 0; kt < 4; ++kt) {
;             f32x16 X;
; #pragma unroll
;             for (int i = 0; i < 16; ++i) X[i] = 8.f;
;             const LAS bf16* khp = KHL + (half * 128 + 32 * kt + r) * 72 + 8 * hi;
; #pragma unroll
;             for (int ks = 0; ks < 4; ++ks) {
;                 const bf16x8 kh = lds8(khp + 16 * ks);
;                 X = MFMA32(kh, qa[half][ks], X);
;             }
;             int grp[16];
; #pragma unroll
;             for (int i = 0; i < 16; ++i) grp[i] = (int)((__float_as_uint(X[i]) | 127u) - (unsigned)(32 * kt + (i & 3) + 8 * (i >> 2)));
;             sort16_desc(grp);
; __global__ void __launch_bounds__(NTHR, 2) k_main(Args a) {
;     ...
;             for (int i = tid; i < 2 * 128 * 8; i += NTHR) {
;                 const int pc = i & 7, key = (i >> 3) & 127, hf = (i >> 10) & 1, hl = i >> 11;
;                 *(LAS v4u*)(KHL + ((hl * 2 + hf) * 128 + key) * 72 + pc * 8) = *(const v4u*)((hl ? KL : KH) + (size_t)(hf * 128 + key) * 64 + pc * 8);
;             }
;             __syncthreads();
.LBB0_665:
	v_mov_b32_e32 v20, s53
	v_mov_b32_e32 v21, s49
	v_mov_b32_e32 v22, s52
	v_mov_b32_e32 v23, s48
	v_lshlrev_b32_e32 v24, 4, v19
	v_cmp_gt_u32_e32 vcc, s54, v19
	v_lshlrev_b32_e32 v25, 1, v18
	v_and_b32_e32 v82, 0x7f80, v24
	v_cndmask_b32_e32 v21, v20, v21, vcc
	v_cndmask_b32_e32 v20, v22, v23, vcc
	v_lshl_add_u64 v[20:21], v[20:21], 0, v[82:83]
	v_and_b32_e32 v82, 0x70, v25
	v_lshl_add_u64 v[20:21], v[20:21], 0, v[82:83]
	global_load_dwordx4 v[162:165], v[20:21], off
	v_lshrrev_b32_e32 v24, 3, v19
	v_mul_lo_u32 v24, v24, s56
	v_add3_u32 v178, 0, v24, v82
	v_add_u32_e32 v19, 0x200, v19
	v_add_u32_e32 v18, 0x1000, v18
	v_mov_b32_e32 v20, s53
	v_mov_b32_e32 v21, s49
	v_mov_b32_e32 v22, s52
	v_mov_b32_e32 v23, s48
	v_lshlrev_b32_e32 v24, 4, v19
	v_cmp_gt_u32_e32 vcc, s54, v19
	v_lshlrev_b32_e32 v25, 1, v18
	v_and_b32_e32 v82, 0x7f80, v24
	v_cndmask_b32_e32 v21, v20, v21, vcc
	v_cndmask_b32_e32 v20, v22, v23, vcc
	v_lshl_add_u64 v[20:21], v[20:21], 0, v[82:83]
	v_and_b32_e32 v82, 0x70, v25
	v_lshl_add_u64 v[20:21], v[20:21], 0, v[82:83]
	global_load_dwordx4 v[166:169], v[20:21], off
	v_lshrrev_b32_e32 v24, 3, v19
	v_mul_lo_u32 v24, v24, s56
	v_add3_u32 v179, 0, v24, v82
	v_add_u32_e32 v19, 0x200, v19
	v_add_u32_e32 v18, 0x1000, v18
	v_mov_b32_e32 v20, s53
	v_mov_b32_e32 v21, s49
	v_mov_b32_e32 v22, s52
	v_mov_b32_e32 v23, s48
	v_lshlrev_b32_e32 v24, 4, v19
	v_cmp_gt_u32_e32 vcc, s54, v19
	v_lshlrev_b32_e32 v25, 1, v18
	v_and_b32_e32 v82, 0x7f80, v24
	v_cndmask_b32_e32 v21, v20, v21, vcc
	v_cndmask_b32_e32 v20, v22, v23, vcc
	v_lshl_add_u64 v[20:21], v[20:21], 0, v[82:83]
	v_and_b32_e32 v82, 0x70, v25
	v_lshl_add_u64 v[20:21], v[20:21], 0, v[82:83]
	global_load_dwordx4 v[170:173], v[20:21], off
	v_lshrrev_b32_e32 v24, 3, v19
	v_mul_lo_u32 v24, v24, s56
	v_add3_u32 v180, 0, v24, v82
	v_add_u32_e32 v19, 0x200, v19
	v_add_u32_e32 v18, 0x1000, v18
	v_mov_b32_e32 v20, s53
	v_mov_b32_e32 v21, s49
	v_mov_b32_e32 v22, s52
	v_mov_b32_e32 v23, s48
	v_lshlrev_b32_e32 v24, 4, v19
	v_cmp_gt_u32_e32 vcc, s54, v19
	v_lshlrev_b32_e32 v25, 1, v18
	v_and_b32_e32 v82, 0x7f80, v24
	v_cndmask_b32_e32 v21, v20, v21, vcc
	v_cndmask_b32_e32 v20, v22, v23, vcc
	v_lshl_add_u64 v[20:21], v[20:21], 0, v[82:83]
	v_and_b32_e32 v82, 0x70, v25
	v_lshl_add_u64 v[20:21], v[20:21], 0, v[82:83]
	global_load_dwordx4 v[174:177], v[20:21], off
	v_lshrrev_b32_e32 v24, 3, v19
	v_mul_lo_u32 v24, v24, s56
	v_add3_u32 v181, 0, v24, v82
	v_add_u32_e32 v19, 0x200, v19
	v_add_u32_e32 v18, 0x1000, v18
	s_waitcnt vmcnt(0)
	ds_write_b128 v178, v[162:165]
	ds_write_b128 v179, v[166:169]
	ds_write_b128 v180, v[170:173]
	ds_write_b128 v181, v[174:177]
	s_nop 0
	s_nop 0
	s_nop 0
	s_nop 0
	s_nop 0
	s_nop 0
	s_nop 0
	s_nop 0
	s_nop 0
	s_nop 0
	s_nop 0
	s_nop 0
	s_nop 0
	s_nop 0
	s_nop 0
.LBB0_666:
	s_or_b64 exec, exec, s[10:11]
	s_lshl_b32 s10, s2, 4
	s_add_i32 s10, s10, s95
	s_lshl_b32 s10, s10, 12
	v_or_b32_e32 v82, s10, v88
	s_waitcnt lgkmcnt(0)
	s_barrier
	s_add_i32 s11, 0, 0x12000
	v_lshl_add_u64 v[70:71], v[82:83], 1, s[80:81]
	global_load_dwordx4 v[62:65], v[70:71], off
	global_load_dwordx4 v[54:57], v[70:71], off offset:32
	global_load_dwordx4 v[58:61], v[70:71], off offset:64
	global_load_dwordx4 v[50:53], v[70:71], off offset:96
	ds_read_b128 v[34:37], v94
	ds_read_b128 v[38:41], v94 offset:32
	s_add_i32 s10, s10, 0x8000
	s_mov_b32 s41, 0
	s_waitcnt vmcnt(3) lgkmcnt(1)
	v_mfma_f32_32x32x16_bf16 v[18:33], v[34:37], v[62:65], v[2:17]
	ds_read_b128 v[34:37], v94 offset:64
	ds_read_b128 v[66:69], v94 offset:96
	s_waitcnt vmcnt(2) lgkmcnt(2)
	v_mfma_f32_32x32x16_bf16 v[18:33], v[38:41], v[54:57], v[18:33]
	v_and_b32_e32 v38, 64, v112
	v_add_u32_e32 v122, 64, v38
	v_cmp_lt_i32_e32 vcc, v113, v122
	s_waitcnt vmcnt(1) lgkmcnt(1)
	v_mfma_f32_32x32x16_bf16 v[18:33], v[34:37], v[58:61], v[18:33]
	v_cndmask_b32_e32 v34, v112, v113, vcc
	v_lshlrev_b32_e32 v123, 2, v34
	global_load_dwordx4 v[46:49], v[70:71], off offset:128
	global_load_dwordx4 v[42:45], v[70:71], off offset:160
	global_load_dwordx4 v[38:41], v[70:71], off offset:192
	global_load_dwordx4 v[34:37], v[70:71], off offset:224
	s_waitcnt vmcnt(4) lgkmcnt(0)
	v_mfma_f32_32x32x16_bf16 v[18:33], v[66:69], v[50:53], v[18:33]
	s_nop 11
	s_movk_i32 s42, 0x7f
	s_movk_i32 s43, 0xff80
	v_bitop3_b32 v21, v21, s42, 3 bitop3:0x56
	v_bitop3_b32 v32, v32, s42, 26 bitop3:0x56
	v_bitop3_b32 v22, v22, s42, 8 bitop3:0x56
	v_bitop3_b32 v26, v26, s42, 16 bitop3:0x56
	v_bitop3_b32 v31, v31, s42, 25 bitop3:0x56
	v_bitop3_b32 v23, v23, s42, 9 bitop3:0x56
	v_bitop3_b32 v24, v24, s42, 10 bitop3:0x56
	v_bitop3_b32 v27, v27, s42, 17 bitop3:0x56
	v_bitop3_b32 v28, v28, s42, 18 bitop3:0x56
	v_bitop3_b32 v20, v20, s42, 2 bitop3:0x56
	v_bitop3_b32 v33, v33, s42, 27 bitop3:0x56
	v_bitop3_b32 v25, v25, s42, 11 bitop3:0x56
	v_bitop3_b32 v29, v29, s42, 19 bitop3:0x56
	v_bitop3_b32 v19, v19, s42, 1 bitop3:0x56
	v_bitop3_b32 v30, v30, s42, 24 bitop3:0x56
	v_or_b32_e32 v18, 0x7f, v18
	v_max_i32_e32 v66, v21, v32
	v_max_i32_e32 v67, v22, v26
	v_max_i32_e32 v68, v18, v31
	v_max_i32_e32 v69, v23, v24
	v_min_i32_e32 v70, v27, v28
	v_min_i32_e32 v71, v20, v33
	v_min_i32_e32 v72, v25, v29
	v_min_i32_e32 v73, v19, v30
	v_min_i32_e32 v23, v23, v24
	v_min_i32_e32 v18, v18, v31
	v_min_i32_e32 v22, v22, v26
	v_min_i32_e32 v21, v21, v32
	v_max_i32_e32 v19, v19, v30
	v_max_i32_e32 v24, v25, v29
	v_max_i32_e32 v20, v20, v33
	v_max_i32_e32 v25, v27, v28
	v_min_i32_e32 v26, v66, v67
	v_min_i32_e32 v27, v68, v69
	v_max_i32_e32 v28, v70, v71
	v_max_i32_e32 v29, v72, v73
	v_max_i32_e32 v30, v23, v18
	v_max_i32_e32 v31, v22, v21
	v_min_i32_e32 v32, v19, v24
	v_min_i32_e32 v33, v20, v25
; #define LAS __attribute__((address_space(3)))
; #define MFMA32(a, b, c) __builtin_amdgcn_mfma_f32_32x32x16_bf16((a), (b), (c), 0, 0, 0)
; #define CE_(a, b) ce_desc(v[a], v[b])
; __device__ __forceinline__ void sort16_desc(int (&v)[16]) {
;     ...
;     CE_(0,13); CE_(1,12); CE_(2,15); CE_(3,14); CE_(4,8); CE_(5,6); CE_(7,11); CE_(9,10);
;     CE_(0,5); CE_(1,7); CE_(2,9); CE_(3,4); CE_(6,13); CE_(8,14); CE_(10,15); CE_(11,12);
;     CE_(0,1); CE_(2,3); CE_(4,5); CE_(6,8); CE_(7,9); CE_(10,11); CE_(12,13); CE_(14,15);
;     CE_(0,2); CE_(1,3); CE_(4,10); CE_(5,11); CE_(6,7); CE_(8,9); CE_(12,14); CE_(13,15);
;     CE_(1,2); CE_(3,12); CE_(4,6); CE_(5,7); CE_(8,10); CE_(9,11); CE_(13,14);
;     CE_(1,4); CE_(2,6); CE_(5,8); CE_(7,10); CE_(9,13); CE_(11,14);
;     CE_(2,4); CE_(3,6); CE_(9,12); CE_(11,13);
;     CE_(3,5); CE_(6,8); CE_(7,9); CE_(10,12);
;     CE_(3,4); CE_(5,6); CE_(7,8); CE_(9,10); CE_(11,12);
;     CE_(6,7); CE_(8,9);
;     ...
; }
; __device__ __forceinline__ void route_task(int task, int tl0, const bf16* QP  , const LAS bf16* KHL, LAS unsigned short* EL, LAS float* GL, int lane) {
;     ...
;         for (int kt = 0; kt < 4; ++kt) {
;             f32x16 X;
; #pragma unroll
;             for (int i = 0; i < 16; ++i) X[i] = 8.f;
;             const LAS bf16* khp = KHL + (half * 128 + 32 * kt + r) * 72 + 8 * hi;
; #pragma unroll
;             for (int ks = 0; ks < 4; ++ks) {
;                 const bf16x8 kh = lds8(khp + 16 * ks);
;                 X = MFMA32(kh, qa[half][ks], X);
;             }
;             int grp[16];
; #pragma unroll
;             for (int i = 0; i < 16; ++i) grp[i] = (int)((__float_as_uint(X[i]) | 127u) - (unsigned)(32 * kt + (i & 3) + 8 * (i >> 2)));
;             sort16_desc(grp);
;             if (kt == 0) {
; #pragma unroll
;                 for (int i = 0; i < 16; ++i) cur[i] = grp[i];
;             } else merge16_desc(cur, grp);
	v_min_i32_e32 v18, v23, v18
	v_min_i32_e32 v21, v22, v21
	v_min_i32_e32 v22, v70, v71
	v_max_i32_e32 v23, v68, v69
	v_max_i32_e32 v19, v19, v24
	v_max_i32_e32 v20, v20, v25
	v_max_i32_e32 v24, v66, v67
	v_min_i32_e32 v25, v26, v27
	v_max_i32_e32 v67, v30, v31
	v_min_i32_e32 v30, v30, v31
	v_min_i32_e32 v31, v32, v33
	v_max_i32_e32 v26, v26, v27
	v_max_i32_e32 v27, v28, v29
	v_min_i32_e32 v66, v28, v29
	v_max_i32_e32 v68, v32, v33
	v_min_i32_e32 v75, v21, v22
	v_max_i32_e32 v21, v21, v22
	v_min_i32_e32 v22, v23, v19
	v_min_i32_e32 v28, v20, v24
	v_max_i32_e32 v33, v30, v31
	v_min_i32_e32 v69, v26, v27
	v_max_i32_e32 v29, v25, v66
	v_min_i32_e32 v32, v67, v68
	v_min_i32_e32 v77, v25, v66
	v_min_i32_e32 v25, v22, v28
	v_max_i32_e32 v80, v22, v28
	v_min_i32_e32 v22, v33, v69
	v_max_i32_e32 v125, v20, v24
	v_max_i32_e32 v129, v67, v68
	v_max_i32_e32 v24, v33, v69
	ds_read_b128 v[66:69], v95
	v_min_i32_e32 v72, v72, v73
	v_min_i32_e32 v74, v72, v18
	v_max_i32_e32 v18, v72, v18
	v_max_i32_e32 v124, v23, v19
	v_min_i32_e32 v76, v30, v31
	v_max_i32_e32 v78, v74, v75
	v_min_i32_e32 v79, v18, v21
	v_min_i32_e32 v126, v124, v125
	v_max_i32_e32 v128, v26, v27
	v_max_i32_e32 v18, v18, v21
	v_max_i32_e32 v81, v76, v77
	v_max_i32_e32 v82, v78, v79
	v_min_i32_e32 v127, v80, v126
	v_min_i32_e32 v130, v128, v129
	v_min_i32_e32 v21, v29, v32
	v_min_i32_e32 v28, v25, v18
	v_max_i32_e32 v18, v25, v18
	v_max_i32_e32 v30, v81, v82
	v_min_i32_e32 v19, v127, v130
	v_max_i32_e32 v23, v29, v32
	v_max_i32_e32 v25, v21, v22
	v_max_i32_e32 v31, v30, v28
	v_min_i32_e32 v20, v18, v19
	v_min_i32_e32 v26, v23, v24
	v_max_i32_e32 v70, v25, v31
	v_min_i32_e32 v27, v20, v26
	v_min_i32_e32 v131, v70, v27
	v_max_i32_e32 v143, v70, v27
	ds_read_b128 v[70:73], v95 offset:32
	v_min_i32_e32 v132, v25, v31
	v_min_i32_e32 v133, v21, v22
	v_min_i32_e32 v134, v30, v28
	v_max_i32_e32 v138, v18, v19
	v_max_i32_e32 v139, v23, v24
	v_max_i32_e32 v141, v20, v26
	s_waitcnt lgkmcnt(1)
	v_mfma_f32_32x32x16_bf16 v[18:33], v[66:69], v[62:65], v[2:17]
	ds_read_b128 v[66:69], v95 offset:64
	v_max_i32_e32 v135, v133, v134
	v_max_i32_e32 v136, v132, v135
	v_min_i32_e32 v76, v76, v77
	v_min_i32_e32 v77, v78, v79
	v_min_i32_e32 v132, v132, v135
	v_max_i32_e32 v127, v127, v130
	s_waitcnt lgkmcnt(1)
	v_mfma_f32_32x32x16_bf16 v[18:33], v[70:73], v[54:57], v[18:33]
	ds_read_b128 v[70:73], v95 offset:96
	v_max_i32_e32 v80, v80, v126
	v_min_i32_e32 v74, v74, v75
	v_min_i32_e32 v140, v138, v139
	v_max_i32_e32 v78, v76, v77
	v_min_i32_e32 v79, v81, v82
	v_min_i32_e32 v82, v133, v134
	s_waitcnt lgkmcnt(1)
	v_mfma_f32_32x32x16_bf16 v[18:33], v[66:69], v[58:61], v[18:33]
	v_max_i32_e32 v66, v128, v129
	v_max_i32_e32 v134, v138, v139
	v_min_i32_e32 v76, v76, v77
	v_max_i32_e32 v81, v78, v79
	v_min_i32_e32 v78, v78, v79
	v_min_i32_e32 v67, v80, v66
	v_min_i32_e32 v142, v140, v141
	s_waitcnt lgkmcnt(0)
	v_mfma_f32_32x32x16_bf16 v[18:33], v[70:73], v[50:53], v[18:33]
	v_min_i32_e32 v68, v127, v67
	v_min_i32_e32 v137, v131, v136
	v_min_i32_e32 v144, v142, v143
	v_min_i32_e32 v133, v81, v82
	v_min_i32_e32 v69, v134, v68
	s_nop 6
	v_bitop3_b32 v21, v21, s42, 35 bitop3:0x56
	v_bitop3_b32 v32, v32, s42, 58 bitop3:0x56
	v_bitop3_b32 v22, v22, s42, 40 bitop3:0x56
	v_bitop3_b32 v26, v26, s42, 48 bitop3:0x56
	v_bitop3_b32 v18, v18, s42, 32 bitop3:0x56
	v_bitop3_b32 v31, v31, s42, 57 bitop3:0x56
	v_bitop3_b32 v23, v23, s42, 41 bitop3:0x56
	v_bitop3_b32 v24, v24, s42, 42 bitop3:0x56
	v_bitop3_b32 v27, v27, s42, 49 bitop3:0x56
	v_bitop3_b32 v28, v28, s42, 50 bitop3:0x56
	v_bitop3_b32 v20, v20, s42, 34 bitop3:0x56
	v_bitop3_b32 v33, v33, s42, 59 bitop3:0x56
	v_bitop3_b32 v25, v25, s42, 43 bitop3:0x56
	v_bitop3_b32 v29, v29, s42, 51 bitop3:0x56
	v_bitop3_b32 v19, v19, s42, 33 bitop3:0x56
	v_bitop3_b32 v30, v30, s42, 56 bitop3:0x56
	v_max_i32_e32 v70, v21, v32
	v_max_i32_e32 v71, v22, v26
	v_max_i32_e32 v73, v18, v31
	v_max_i32_e32 v75, v23, v24
	v_min_i32_e32 v126, v27, v28
	v_min_i32_e32 v128, v20, v33
	v_min_i32_e32 v130, v25, v29
	v_min_i32_e32 v135, v19, v30
	v_min_i32_e32 v23, v23, v24
	v_min_i32_e32 v18, v18, v31
	v_min_i32_e32 v22, v22, v26
	v_min_i32_e32 v21, v21, v32
	v_max_i32_e32 v19, v19, v30
	v_max_i32_e32 v25, v25, v29
	v_max_i32_e32 v20, v20, v33
	v_max_i32_e32 v27, v27, v28
	v_min_i32_e32 v72, v70, v71
	v_min_i32_e32 v77, v73, v75
	v_max_i32_e32 v129, v126, v128
	v_max_i32_e32 v138, v130, v135
	v_max_i32_e32 v24, v23, v18
	v_max_i32_e32 v26, v22, v21
	v_min_i32_e32 v29, v19, v25
	v_min_i32_e32 v28, v20, v27
	v_min_i32_e32 v130, v130, v135
	v_min_i32_e32 v18, v23, v18
	v_min_i32_e32 v21, v22, v21
	v_min_i32_e32 v22, v126, v128
	v_max_i32_e32 v73, v73, v75
	v_max_i32_e32 v19, v19, v25
	v_max_i32_e32 v20, v20, v27
	v_max_i32_e32 v27, v70, v71
	v_min_i32_e32 v79, v72, v77
	v_min_i32_e32 v139, v129, v138
	v_max_i32_e32 v31, v24, v26
	v_max_i32_e32 v30, v29, v28
	v_min_i32_e32 v24, v24, v26
	v_min_i32_e32 v26, v29, v28
	v_max_i32_e32 v29, v72, v77
	v_max_i32_e32 v72, v129, v138
	v_min_i32_e32 v23, v130, v18
	v_min_i32_e32 v126, v21, v22
	v_max_i32_e32 v18, v130, v18
	v_max_i32_e32 v21, v21, v22
	v_min_i32_e32 v25, v73, v19
	v_min_i32_e32 v70, v20, v27
	v_max_i32_e32 v19, v73, v19
	v_max_i32_e32 v20, v20, v27
	v_min_i32_e32 v32, v31, v30
	v_max_i32_e32 v28, v24, v26
	v_min_i32_e32 v77, v29, v72
	v_min_i32_e32 v24, v24, v26
	v_min_i32_e32 v26, v79, v139
	v_max_i32_e32 v128, v23, v126
	v_min_i32_e32 v22, v18, v21
	v_min_i32_e32 v71, v25, v70
	v_max_i32_e32 v25, v25, v70
	v_min_i32_e32 v27, v19, v20
	v_max_i32_e32 v29, v29, v72
	v_max_i32_e32 v30, v31, v30
	v_max_i32_e32 v145, v79, v139
	v_max_i32_e32 v79, v24, v26
; #define LAS __attribute__((address_space(3)))
; #define MFMA32(a, b, c) __builtin_amdgcn_mfma_f32_32x32x16_bf16((a), (b), (c), 0, 0, 0)
; #define CE_(a, b) ce_desc(v[a], v[b])
; __device__ __forceinline__ void sort16_desc(int (&v)[16]) {
;     ...
;     CE_(0,13); CE_(1,12); CE_(2,15); CE_(3,14); CE_(4,8); CE_(5,6); CE_(7,11); CE_(9,10);
;     CE_(0,5); CE_(1,7); CE_(2,9); CE_(3,4); CE_(6,13); CE_(8,14); CE_(10,15); CE_(11,12);
;     CE_(0,1); CE_(2,3); CE_(4,5); CE_(6,8); CE_(7,9); CE_(10,11); CE_(12,13); CE_(14,15);
;     CE_(0,2); CE_(1,3); CE_(4,10); CE_(5,11); CE_(6,7); CE_(8,9); CE_(12,14); CE_(13,15);
;     CE_(1,2); CE_(3,12); CE_(4,6); CE_(5,7); CE_(8,10); CE_(9,11); CE_(13,14);
;     CE_(1,4); CE_(2,6); CE_(5,8); CE_(7,10); CE_(9,13); CE_(11,14);
;     CE_(2,4); CE_(3,6); CE_(9,12); CE_(11,13);
;     CE_(3,5); CE_(6,8); CE_(7,9); CE_(10,12);
;     CE_(3,4); CE_(5,6); CE_(7,8); CE_(9,10); CE_(11,12);
;     CE_(6,7); CE_(8,9);
;     ...
; }
; __device__ __forceinline__ void merge16_desc(int (&a)[16], const int (&b)[16]) {
; #pragma unroll
;     for (int i = 0; i < 16; ++i) a[i] = a[i] > b[15 - i] ? a[i] : b[15 - i];
; #pragma unroll
;     for (int j = 8; j > 0; j >>= 1)
; #pragma unroll
;         for (int i = 0; i < 16; ++i) { const int l = i ^ j; if (l > i) ce_desc(a[i], a[l]); }
; }
; __device__ __forceinline__ void route_task(int task, int tl0, const bf16* QP  , const LAS bf16* KHL, LAS unsigned short* EL, LAS float* GL, int lane) {
;     ...
;         for (int kt = 0; kt < 4; ++kt) {
;             f32x16 X;
; #pragma unroll
;             for (int i = 0; i < 16; ++i) X[i] = 8.f;
;             const LAS bf16* khp = KHL + (half * 128 + 32 * kt + r) * 72 + 8 * hi;
; #pragma unroll
;             for (int ks = 0; ks < 4; ++ks) {
;                 const bf16x8 kh = lds8(khp + 16 * ks);
;                 X = MFMA32(kh, qa[half][ks], X);
;             }
;             int grp[16];
; #pragma unroll
;             for (int i = 0; i < 16; ++i) grp[i] = (int)((__float_as_uint(X[i]) | 127u) - (unsigned)(32 * kt + (i & 3) + 8 * (i >> 2)));
;             sort16_desc(grp);
;             if (kt == 0) {
; #pragma unroll
;                 for (int i = 0; i < 16; ++i) cur[i] = grp[i];
;             } else merge16_desc(cur, grp);
	v_max_i32_e32 v130, v128, v22
	v_max_i32_e32 v18, v18, v21
	v_min_i32_e32 v70, v25, v27
	v_min_i32_e32 v31, v29, v30
	v_min_i32_e32 v33, v145, v32
	v_min_i32_e32 v129, v28, v77
	v_max_i32_e32 v135, v79, v130
	v_min_i32_e32 v21, v71, v18
	v_max_i32_e32 v18, v71, v18
	v_min_i32_e32 v71, v70, v31
	v_max_i32_e32 v32, v145, v32
	v_max_i32_e32 v28, v28, v77
	v_max_i32_e32 v138, v33, v129
	v_max_i32_e32 v75, v135, v21
	v_min_i32_e32 v72, v18, v71
	v_min_i32_e32 v73, v32, v28
	v_min_i32_e32 v33, v33, v129
	v_min_i32_e32 v21, v135, v21
	v_max_i32_e32 v18, v18, v71
	v_max_i32_e32 v28, v32, v28
	v_min_i32_e32 v24, v24, v26
	v_min_i32_e32 v22, v128, v22
	v_max_i32_e32 v25, v25, v27
	v_max_i32_e32 v27, v29, v30
	v_max_i32_e32 v139, v138, v75
	v_min_i32_e32 v77, v72, v73
	v_min_i32_e32 v75, v138, v75
	v_max_i32_e32 v129, v33, v21
	v_min_i32_e32 v32, v18, v28
	v_max_i32_e32 v71, v72, v73
	v_max_i32_e32 v26, v24, v22
	v_min_i32_e32 v79, v79, v130
	v_max_i32_e32 v18, v18, v28
	v_max_i32_e32 v28, v70, v31
	v_min_i32_e32 v29, v25, v27
	v_min_i32_e32 v145, v139, v77
	v_max_i32_e32 v135, v75, v129
	v_min_i32_e32 v72, v32, v71
	v_max_i32_e32 v73, v139, v77
	v_max_i32_e32 v128, v26, v79
	v_min_i32_e32 v21, v33, v21
	v_min_i32_e32 v30, v28, v29
	v_min_i32_e32 v138, v145, v135
	v_min_i32_e32 v77, v72, v73
	v_min_i32_e32 v33, v128, v21
	v_min_i32_e32 v75, v75, v129
	v_min_i32_e32 v31, v18, v30
	v_min_i32_e32 v26, v26, v79
	v_min_i32_e32 v22, v24, v22
	v_min_i32_e32 v23, v23, v126
	v_max3_i32 v23, v124, v125, v23
	v_max3_i32 v22, v80, v66, v22
	v_max3_i32 v24, v127, v67, v26
	v_max3_i32 v26, v134, v68, v33
	v_max3_i32 v21, v69, v128, v21
	v_max3_i32 v33, v140, v141, v75
	v_max3_i32 v66, v142, v143, v138
	v_max3_i32 v67, v144, v145, v135
	v_max3_i32 v68, v131, v136, v77
	v_max3_i32 v69, v137, v72, v73
	v_max3_i32 v32, v132, v32, v71
	v_max3_i32 v31, v81, v82, v31
	v_max3_i32 v18, v133, v18, v30
	v_max3_i32 v28, v78, v28, v29
	v_max3_i32 v25, v76, v25, v27
	v_max3_i32 v19, v74, v19, v20
	v_max_i32_e32 v20, v23, v68
	v_min_i32_e32 v23, v23, v68
	v_max_i32_e32 v27, v22, v69
	v_min_i32_e32 v22, v22, v69
	v_max_i32_e32 v29, v24, v32
	v_min_i32_e32 v24, v24, v32
	v_max_i32_e32 v30, v26, v31
	v_min_i32_e32 v26, v26, v31
	v_max_i32_e32 v31, v21, v18
	v_min_i32_e32 v18, v21, v18
	v_max_i32_e32 v21, v33, v28
	v_min_i32_e32 v28, v33, v28
	v_max_i32_e32 v32, v66, v25
	v_min_i32_e32 v25, v66, v25
	v_max_i32_e32 v33, v67, v19
	v_min_i32_e32 v19, v67, v19
	ds_read_b128 v[66:69], v94 offset:9216
	v_max_i32_e32 v70, v20, v31
	v_min_i32_e32 v74, v20, v31
	v_max_i32_e32 v20, v27, v21
	v_min_i32_e32 v75, v27, v21
	v_max_i32_e32 v21, v29, v32
	v_max_i32_e32 v27, v30, v33
	v_max_i32_e32 v127, v70, v21
	v_min_i32_e32 v128, v70, v21
	ds_read_b128 v[70:73], v94 offset:9248
	v_min_i32_e32 v76, v29, v32
	v_min_i32_e32 v77, v30, v33
	v_max_i32_e32 v78, v23, v18
	v_min_i32_e32 v79, v23, v18
	v_max_i32_e32 v80, v22, v28
	v_min_i32_e32 v81, v22, v28
	v_max_i32_e32 v82, v24, v25
	v_min_i32_e32 v124, v24, v25
	v_max_i32_e32 v125, v26, v19
	v_min_i32_e32 v126, v26, v19
	v_max_i32_e32 v129, v20, v27
	v_min_i32_e32 v130, v20, v27
	s_waitcnt lgkmcnt(1)
	v_mfma_f32_32x32x16_bf16 v[18:33], v[66:69], v[62:65], v[2:17]
	ds_read_b128 v[66:69], v94 offset:9280
	v_max_i32_e32 v131, v74, v76
	v_min_i32_e32 v74, v74, v76
	v_max_i32_e32 v76, v75, v77
	v_min_i32_e32 v75, v75, v77
	v_max_i32_e32 v77, v78, v82
	v_min_i32_e32 v78, v78, v82
	s_waitcnt lgkmcnt(1)
	v_mfma_f32_32x32x16_bf16 v[18:33], v[70:73], v[54:57], v[18:33]
	ds_read_b128 v[70:73], v94 offset:9312
	v_max_i32_e32 v82, v80, v125
	v_min_i32_e32 v80, v80, v125
	v_max_i32_e32 v125, v79, v124
	v_min_i32_e32 v79, v79, v124
	v_max_i32_e32 v124, v81, v126
	v_min_i32_e32 v81, v81, v126
	s_waitcnt lgkmcnt(1)
	v_mfma_f32_32x32x16_bf16 v[18:33], v[66:69], v[58:61], v[18:33]
	v_min_i32_e32 v126, v127, v129
	v_min_i32_e32 v66, v128, v130
	v_min_i32_e32 v67, v131, v76
	v_min_i32_e32 v69, v77, v82
	v_min_i32_e32 v132, v78, v80
	v_min_i32_e32 v133, v125, v124
	v_min_i32_e32 v68, v74, v75
	s_waitcnt lgkmcnt(0)
	v_mfma_f32_32x32x16_bf16 v[18:33], v[70:73], v[50:53], v[18:33]
	v_min_i32_e32 v134, v79, v81
	s_nop 10
	v_and_or_b32 v21, v21, s43, 60
	v_and_or_b32 v32, v32, s43, 37
	v_and_or_b32 v22, v22, s43, 55
	v_and_or_b32 v26, v26, s43, 47
	v_bitop3_b32 v18, v18, s42, 64 bitop3:0x56
	v_and_or_b32 v31, v31, s43, 38
	v_and_or_b32 v23, v23, s43, 54
	v_and_or_b32 v24, v24, s43, 53
	v_and_or_b32 v27, v27, s43, 46
	v_and_or_b32 v28, v28, s43, 45
	v_and_or_b32 v20, v20, s43, 61
	v_and_or_b32 v33, v33, s43, 36
	v_and_or_b32 v25, v25, s43, 52
	v_and_or_b32 v29, v29, s43, 44
	v_and_or_b32 v19, v19, s43, 62
	v_and_or_b32 v30, v30, s43, 39
	v_max_i32_e32 v70, v21, v32
	v_max_i32_e32 v71, v22, v26
	v_max_i32_e32 v73, v18, v31
	v_max_i32_e32 v135, v23, v24
	v_min_i32_e32 v138, v27, v28
	v_min_i32_e32 v139, v20, v33
	v_min_i32_e32 v141, v25, v29
	v_min_i32_e32 v142, v19, v30
	v_min_i32_e32 v23, v23, v24
	v_min_i32_e32 v18, v18, v31
	v_min_i32_e32 v22, v22, v26
	v_min_i32_e32 v21, v21, v32
	v_max_i32_e32 v19, v19, v30
	v_max_i32_e32 v25, v25, v29
	v_max_i32_e32 v20, v20, v33
	v_max_i32_e32 v27, v27, v28
	v_min_i32_e32 v72, v70, v71
	v_min_i32_e32 v136, v73, v135
	v_max_i32_e32 v140, v138, v139
	v_max_i32_e32 v143, v141, v142
	v_max_i32_e32 v24, v23, v18
	v_max_i32_e32 v26, v22, v21
	v_min_i32_e32 v29, v19, v25
	v_min_i32_e32 v28, v20, v27
	v_min_i32_e32 v141, v141, v142
	v_min_i32_e32 v18, v23, v18
	v_min_i32_e32 v21, v22, v21
	v_min_i32_e32 v22, v138, v139
	v_max_i32_e32 v73, v73, v135
	v_max_i32_e32 v19, v19, v25
	v_max_i32_e32 v20, v20, v27
	v_max_i32_e32 v27, v70, v71
; #define LAS __attribute__((address_space(3)))
; #define MFMA32(a, b, c) __builtin_amdgcn_mfma_f32_32x32x16_bf16((a), (b), (c), 0, 0, 0)
; #define CE_(a, b) ce_desc(v[a], v[b])
; __device__ __forceinline__ void sort16_desc(int (&v)[16]) {
;     ...
;     CE_(0,13); CE_(1,12); CE_(2,15); CE_(3,14); CE_(4,8); CE_(5,6); CE_(7,11); CE_(9,10);
;     CE_(0,5); CE_(1,7); CE_(2,9); CE_(3,4); CE_(6,13); CE_(8,14); CE_(10,15); CE_(11,12);
;     CE_(0,1); CE_(2,3); CE_(4,5); CE_(6,8); CE_(7,9); CE_(10,11); CE_(12,13); CE_(14,15);
;     CE_(0,2); CE_(1,3); CE_(4,10); CE_(5,11); CE_(6,7); CE_(8,9); CE_(12,14); CE_(13,15);
;     CE_(1,2); CE_(3,12); CE_(4,6); CE_(5,7); CE_(8,10); CE_(9,11); CE_(13,14);
;     CE_(1,4); CE_(2,6); CE_(5,8); CE_(7,10); CE_(9,13); CE_(11,14);
;     CE_(2,4); CE_(3,6); CE_(9,12); CE_(11,13);
;     CE_(3,5); CE_(6,8); CE_(7,9); CE_(10,12);
;     CE_(3,4); CE_(5,6); CE_(7,8); CE_(9,10); CE_(11,12);
;     CE_(6,7); CE_(8,9);
;     ...
; }
; __device__ __forceinline__ void merge16_desc(int (&a)[16], const int (&b)[16]) {
; #pragma unroll
;     for (int i = 0; i < 16; ++i) a[i] = a[i] > b[15 - i] ? a[i] : b[15 - i];
; #pragma unroll
;     for (int j = 8; j > 0; j >>= 1)
; #pragma unroll
;         for (int i = 0; i < 16; ++i) { const int l = i ^ j; if (l > i) ce_desc(a[i], a[l]); }
; }
; __device__ __forceinline__ void route_task(int task, int tl0, const bf16* QP  , const LAS bf16* KHL, LAS unsigned short* EL, LAS float* GL, int lane) {
;     ...
;         for (int kt = 0; kt < 4; ++kt) {
;             f32x16 X;
; #pragma unroll
;             for (int i = 0; i < 16; ++i) X[i] = 8.f;
;             const LAS bf16* khp = KHL + (half * 128 + 32 * kt + r) * 72 + 8 * hi;
; #pragma unroll
;             for (int ks = 0; ks < 4; ++ks) {
;                 const bf16x8 kh = lds8(khp + 16 * ks);
;                 X = MFMA32(kh, qa[half][ks], X);
;             }
;             int grp[16];
; #pragma unroll
;             for (int i = 0; i < 16; ++i) grp[i] = (int)((__float_as_uint(X[i]) | 127u) - (unsigned)(32 * kt + (i & 3) + 8 * (i >> 2)));
;             sort16_desc(grp);
;             if (kt == 0) {
; #pragma unroll
;                 for (int i = 0; i < 16; ++i) cur[i] = grp[i];
;             } else merge16_desc(cur, grp);
	v_min_i32_e32 v137, v72, v136
	v_min_i32_e32 v144, v140, v143
	v_max_i32_e32 v31, v24, v26
	v_max_i32_e32 v30, v29, v28
	v_min_i32_e32 v24, v24, v26
	v_min_i32_e32 v26, v29, v28
	v_max_i32_e32 v29, v72, v136
	v_max_i32_e32 v72, v140, v143
	v_min_i32_e32 v23, v141, v18
	v_min_i32_e32 v138, v21, v22
	v_max_i32_e32 v18, v141, v18
	v_max_i32_e32 v21, v21, v22
	v_min_i32_e32 v25, v73, v19
	v_min_i32_e32 v70, v20, v27
	v_max_i32_e32 v19, v73, v19
	v_max_i32_e32 v20, v20, v27
	v_min_i32_e32 v32, v31, v30
	v_max_i32_e32 v28, v24, v26
	v_min_i32_e32 v136, v29, v72
	v_min_i32_e32 v24, v24, v26
	v_min_i32_e32 v26, v137, v144
	v_max_i32_e32 v139, v23, v138
	v_min_i32_e32 v22, v18, v21
	v_min_i32_e32 v71, v25, v70
	v_max_i32_e32 v25, v25, v70
	v_min_i32_e32 v27, v19, v20
	v_max_i32_e32 v29, v29, v72
	v_max_i32_e32 v30, v31, v30
	v_max_i32_e32 v145, v137, v144
	v_max_i32_e32 v137, v24, v26
	v_max_i32_e32 v141, v139, v22
	v_max_i32_e32 v18, v18, v21
	v_min_i32_e32 v70, v25, v27
	v_min_i32_e32 v31, v29, v30
	v_min_i32_e32 v33, v145, v32
	v_min_i32_e32 v140, v28, v136
	v_max_i32_e32 v142, v137, v141
	v_min_i32_e32 v21, v71, v18
	v_max_i32_e32 v18, v71, v18
	v_min_i32_e32 v71, v70, v31
	v_max_i32_e32 v32, v145, v32
	v_max_i32_e32 v28, v28, v136
	v_max_i32_e32 v143, v33, v140
	v_max_i32_e32 v135, v142, v21
	v_min_i32_e32 v72, v18, v71
	v_min_i32_e32 v73, v32, v28
	v_min_i32_e32 v33, v33, v140
	v_min_i32_e32 v21, v142, v21
	v_max_i32_e32 v18, v18, v71
	v_max_i32_e32 v28, v32, v28
	v_min_i32_e32 v24, v24, v26
	v_min_i32_e32 v22, v139, v22
	v_max_i32_e32 v25, v25, v27
	v_max_i32_e32 v27, v29, v30
	v_max_i32_e32 v144, v143, v135
	v_min_i32_e32 v136, v72, v73
	v_min_i32_e32 v135, v143, v135
	v_max_i32_e32 v140, v33, v21
	v_min_i32_e32 v32, v18, v28
	v_max_i32_e32 v71, v72, v73
	v_max_i32_e32 v26, v24, v22
	v_min_i32_e32 v137, v137, v141
	v_max_i32_e32 v18, v18, v28
	v_max_i32_e32 v28, v70, v31
	v_min_i32_e32 v29, v25, v27
	v_min_i32_e32 v145, v144, v136
	v_max_i32_e32 v142, v135, v140
	v_min_i32_e32 v72, v32, v71
	v_max_i32_e32 v73, v144, v136
	v_max_i32_e32 v139, v26, v137
	v_min_i32_e32 v21, v33, v21
	v_min_i32_e32 v30, v28, v29
	v_min_i32_e32 v143, v145, v142
	v_min_i32_e32 v136, v72, v73
	v_min_i32_e32 v33, v139, v21
	v_max_i32_e32 v21, v139, v21
	v_min_i32_e32 v135, v135, v140
	v_max_i32_e32 v32, v32, v71
	v_min_i32_e32 v31, v18, v30
	v_max_i32_e32 v18, v18, v30
	v_min_i32_e32 v26, v26, v137
	v_min_i32_e32 v22, v24, v22
	v_max_i32_e32 v24, v25, v27
	v_min_i32_e32 v23, v23, v138
	v_max3_i32 v23, v127, v129, v23
	v_max_i32_e32 v22, v126, v22
	v_max3_i32 v25, v128, v130, v26
	v_max_i32_e32 v26, v66, v33
	v_max3_i32 v21, v131, v76, v21
	v_max_i32_e32 v27, v67, v135
	v_max3_i32 v30, v74, v75, v143
	v_max3_i32 v66, v77, v82, v136
	v_max3_i32 v67, v69, v72, v73
	v_max3_i32 v32, v78, v80, v32
	v_max_i32_e32 v31, v132, v31
	v_max3_i32 v18, v125, v124, v18
	v_max3_i32 v28, v133, v28, v29
	v_max3_i32 v24, v79, v81, v24
	v_max3_i32 v33, v68, v145, v142
	v_max3_i32 v19, v134, v19, v20
	v_max_i32_e32 v20, v23, v66
	v_min_i32_e32 v23, v23, v66
	v_max_i32_e32 v29, v22, v67
	v_max_i32_e32 v66, v25, v32
	v_min_i32_e32 v25, v25, v32
	v_max_i32_e32 v32, v26, v31
	v_min_i32_e32 v26, v26, v31
	v_max_i32_e32 v31, v21, v18
	v_min_i32_e32 v18, v21, v18
	v_max_i32_e32 v21, v27, v28
	v_min_i32_e32 v27, v27, v28
	v_max_i32_e32 v28, v30, v24
	v_min_i32_e32 v22, v22, v67
	v_min_i32_e32 v24, v30, v24
	v_max_i32_e32 v30, v33, v19
	v_min_i32_e32 v19, v33, v19
	v_max_i32_e32 v33, v20, v31
	v_min_i32_e32 v74, v20, v31
	v_max_i32_e32 v20, v29, v21
	v_min_i32_e32 v75, v29, v21
	v_max_i32_e32 v21, v66, v28
	v_min_i32_e32 v76, v66, v28
	ds_read_b128 v[66:69], v96
	ds_read_b128 v[70:73], v96 offset:32
	v_max_i32_e32 v28, v32, v30
	v_min_i32_e32 v77, v32, v30
	v_max_i32_e32 v78, v23, v18
	v_min_i32_e32 v79, v23, v18
	v_max_i32_e32 v80, v22, v27
	v_min_i32_e32 v81, v22, v27
	v_max_i32_e32 v82, v25, v24
	v_min_i32_e32 v124, v25, v24
	v_max_i32_e32 v125, v26, v19
	v_min_i32_e32 v126, v26, v19
	v_max_i32_e32 v127, v33, v21
	v_min_i32_e32 v128, v33, v21
	v_max_i32_e32 v129, v20, v28
	v_min_i32_e32 v130, v20, v28
	s_waitcnt lgkmcnt(1)
	v_mfma_f32_32x32x16_bf16 v[18:33], v[66:69], v[62:65], v[2:17]
	ds_read_b128 v[62:65], v96 offset:64
	v_max_i32_e32 v67, v75, v77
	v_min_i32_e32 v68, v75, v77
	v_max_i32_e32 v75, v80, v125
	v_max_i32_e32 v131, v74, v76
	v_min_i32_e32 v66, v74, v76
	v_max_i32_e32 v69, v78, v82
	s_waitcnt lgkmcnt(1)
	v_mfma_f32_32x32x16_bf16 v[18:33], v[70:73], v[54:57], v[18:33]
	ds_read_b128 v[54:57], v96 offset:96
	v_min_i32_e32 v70, v80, v125
	v_max_i32_e32 v71, v79, v124
	v_min_i32_e32 v72, v79, v124
	v_min_i32_e32 v74, v78, v82
	v_max_i32_e32 v73, v81, v126
	v_min_i32_e32 v76, v81, v126
	s_waitcnt lgkmcnt(1)
	v_mfma_f32_32x32x16_bf16 v[18:33], v[62:65], v[58:61], v[18:33]
	v_min_i32_e32 v77, v127, v129
	v_min_i32_e32 v58, v128, v130
	v_min_i32_e32 v59, v131, v67
	v_min_i32_e32 v60, v66, v68
	v_min_i32_e32 v61, v69, v75
	v_min_i32_e32 v62, v74, v70
	v_min_i32_e32 v63, v71, v73
	s_waitcnt lgkmcnt(0)
; #define LAS __attribute__((address_space(3)))
; #define MFMA32(a, b, c) __builtin_amdgcn_mfma_f32_32x32x16_bf16((a), (b), (c), 0, 0, 0)
; #define CE_(a, b) ce_desc(v[a], v[b])
; __device__ __forceinline__ void sort16_desc(int (&v)[16]) {
;     ...
;     CE_(0,13); CE_(1,12); CE_(2,15); CE_(3,14); CE_(4,8); CE_(5,6); CE_(7,11); CE_(9,10);
;     CE_(0,5); CE_(1,7); CE_(2,9); CE_(3,4); CE_(6,13); CE_(8,14); CE_(10,15); CE_(11,12);
;     CE_(0,1); CE_(2,3); CE_(4,5); CE_(6,8); CE_(7,9); CE_(10,11); CE_(12,13); CE_(14,15);
;     CE_(0,2); CE_(1,3); CE_(4,10); CE_(5,11); CE_(6,7); CE_(8,9); CE_(12,14); CE_(13,15);
;     CE_(1,2); CE_(3,12); CE_(4,6); CE_(5,7); CE_(8,10); CE_(9,11); CE_(13,14);
;     CE_(1,4); CE_(2,6); CE_(5,8); CE_(7,10); CE_(9,13); CE_(11,14);
;     CE_(2,4); CE_(3,6); CE_(9,12); CE_(11,13);
;     CE_(3,5); CE_(6,8); CE_(7,9); CE_(10,12);
;     CE_(3,4); CE_(5,6); CE_(7,8); CE_(9,10); CE_(11,12);
;     CE_(6,7); CE_(8,9);
;     ...
; }
; __device__ __forceinline__ void merge16_desc(int (&a)[16], const int (&b)[16]) {
; #pragma unroll
;     for (int i = 0; i < 16; ++i) a[i] = a[i] > b[15 - i] ? a[i] : b[15 - i];
; #pragma unroll
;     for (int j = 8; j > 0; j >>= 1)
; #pragma unroll
;         for (int i = 0; i < 16; ++i) { const int l = i ^ j; if (l > i) ce_desc(a[i], a[l]); }
; }
; __device__ __forceinline__ void route_task(int task, int tl0, const bf16* QP  , const LAS bf16* KHL, LAS unsigned short* EL, LAS float* GL, int lane) {
;     ...
;         for (int kt = 0; kt < 4; ++kt) {
;             f32x16 X;
; #pragma unroll
;             for (int i = 0; i < 16; ++i) X[i] = 8.f;
;             const LAS bf16* khp = KHL + (half * 128 + 32 * kt + r) * 72 + 8 * hi;
; #pragma unroll
;             for (int ks = 0; ks < 4; ++ks) {
;                 const bf16x8 kh = lds8(khp + 16 * ks);
;                 X = MFMA32(kh, qa[half][ks], X);
;             }
;             int grp[16];
; #pragma unroll
;             for (int i = 0; i < 16; ++i) grp[i] = (int)((__float_as_uint(X[i]) | 127u) - (unsigned)(32 * kt + (i & 3) + 8 * (i >> 2)));
;             sort16_desc(grp);
;             if (kt == 0) {
; #pragma unroll
;                 for (int i = 0; i < 16; ++i) cur[i] = grp[i];
;             } else merge16_desc(cur, grp);
;         }
;         { const unsigned h4 = 4u * (unsigned)hi;
; #pragma unroll
;           for (int i = 0; i < 16; ++i) cur[i] -= (int)h4; }
	v_mfma_f32_32x32x16_bf16 v[18:33], v[54:57], v[50:53], v[18:33]
	v_min_i32_e32 v64, v72, v76
	s_nop 10
	v_and_or_b32 v25, v25, s43, 20
	v_and_or_b32 v29, v29, s43, 12
	v_and_or_b32 v19, v19, s43, 30
	v_and_or_b32 v30, v30, s43, 7
	v_and_or_b32 v23, v23, s43, 22
	v_and_or_b32 v24, v24, s43, 21
	v_and_or_b32 v18, v18, s43, 31
	v_and_or_b32 v31, v31, s43, 6
	v_and_or_b32 v22, v22, s43, 23
	v_and_or_b32 v26, v26, s43, 15
	v_and_or_b32 v21, v21, s43, 28
	v_and_or_b32 v32, v32, s43, 5
	v_and_or_b32 v27, v27, s43, 14
	v_and_or_b32 v28, v28, s43, 13
	v_and_or_b32 v20, v20, s43, 29
	v_and_or_b32 v33, v33, s43, 4
	v_min_i32_e32 v50, v25, v29
	v_min_i32_e32 v51, v19, v30
	v_min_i32_e32 v53, v23, v24
	v_min_i32_e32 v54, v18, v31
	v_min_i32_e32 v57, v22, v26
	v_min_i32_e32 v65, v21, v32
	v_min_i32_e32 v79, v27, v28
	v_min_i32_e32 v80, v20, v33
	v_max_i32_e32 v18, v18, v31
	v_max_i32_e32 v23, v23, v24
	v_max_i32_e32 v19, v19, v30
	v_max_i32_e32 v25, v25, v29
	v_max_i32_e32 v20, v20, v33
	v_max_i32_e32 v27, v27, v28
	v_max_i32_e32 v21, v21, v32
	v_max_i32_e32 v22, v22, v26
	v_max_i32_e32 v24, v18, v23
	v_max_i32_e32 v29, v19, v25
	v_max_i32_e32 v28, v20, v27
	v_max_i32_e32 v26, v21, v22
	v_min_i32_e32 v30, v24, v29
	v_min_i32_e32 v31, v28, v26
	v_min_i32_e32 v55, v53, v54
	v_min_i32_e32 v32, v30, v31
	v_max_i32_e32 v30, v30, v31
	v_min_i32_e32 v21, v21, v22
	v_min_i32_e32 v18, v18, v23
	v_max_i32_e32 v23, v79, v80
	v_max_i32_e32 v31, v50, v51
	v_max_i32_e32 v53, v53, v54
	v_max_i32_e32 v54, v57, v65
	v_min_i32_e32 v19, v19, v25
	v_min_i32_e32 v20, v20, v27
	v_min_i32_e32 v52, v50, v51
	v_min_i32_e32 v78, v57, v65
	v_min_i32_e32 v81, v79, v80
	v_max_i32_e32 v22, v21, v18
	v_max_i32_e32 v57, v53, v54
	v_max_i32_e32 v25, v19, v20
	v_min_i32_e32 v18, v21, v18
	v_min_i32_e32 v21, v23, v31
	v_min_i32_e32 v56, v52, v55
	v_min_i32_e32 v82, v78, v81
	v_max_i32_e32 v33, v52, v55
	v_max_i32_e32 v52, v78, v81
	v_max_i32_e32 v24, v24, v29
	v_max_i32_e32 v26, v28, v26
	v_max_i32_e32 v50, v23, v31
	v_max_i32_e32 v27, v57, v25
	v_max_i32_e32 v23, v18, v21
	v_min_i32_e32 v25, v57, v25
	v_min_i32_e32 v53, v53, v54
	v_min_i32_e32 v19, v19, v20
	v_max_i32_e32 v55, v33, v52
	v_min_i32_e32 v28, v24, v26
	v_max_i32_e32 v51, v22, v50
	v_max_i32_e32 v31, v23, v25
	v_max_i32_e32 v20, v53, v19
	v_min_i32_e32 v23, v23, v25
	v_min_i32_e32 v19, v53, v19
	v_min_i32_e32 v18, v18, v21
	v_max_i32_e32 v25, v56, v82
	v_min_i32_e32 v33, v33, v52
	v_min_i32_e32 v29, v30, v28
	v_min_i32_e32 v65, v51, v27
	v_min_i32_e32 v22, v22, v50
	v_max_i32_e32 v21, v19, v18
	v_max_i32_e32 v52, v25, v33
	v_max_i32_e32 v78, v32, v55
	v_min_i32_e32 v79, v29, v65
	v_max_i32_e32 v50, v20, v22
	v_min_i32_e32 v20, v20, v22
	v_max_i32_e32 v53, v21, v52
	v_min_i32_e32 v32, v32, v55
	v_max_i32_e32 v80, v78, v79
	v_max_i32_e32 v54, v31, v50
	v_min_i32_e32 v78, v78, v79
	v_min_i32_e32 v31, v31, v50
	v_max_i32_e32 v22, v23, v20
	v_max_i32_e32 v55, v53, v32
	v_min_i32_e32 v18, v19, v18
	v_min_i32_e32 v19, v25, v33
	v_min_i32_e32 v20, v23, v20
	v_min_i32_e32 v23, v53, v32
	v_max_i32_e32 v28, v30, v28
	v_max_i32_e32 v27, v51, v27
	v_min_i32_e32 v124, v56, v82
	v_min_i32_e32 v57, v80, v54
	v_max_i32_e32 v50, v78, v31
	v_max_i32_e32 v56, v22, v55
	v_min_i32_e32 v31, v78, v31
	v_max_i32_e32 v25, v18, v19
	v_min_i32_e32 v21, v21, v52
	v_min_i32_e32 v32, v20, v23
	v_max_i32_e32 v29, v29, v65
	v_min_i32_e32 v30, v28, v27
	v_min_i32_e32 v22, v22, v55
	v_max_i32_e32 v20, v20, v23
	v_min_i32_e32 v79, v57, v50
	v_max_i32_e32 v78, v56, v31
	v_max_i32_e32 v33, v25, v21
	v_max_i32_e32 v53, v80, v54
	v_min_i32_e32 v51, v29, v30
	v_min_i32_e32 v31, v56, v31
	v_max_i32_e32 v23, v22, v20
	v_min_i32_e32 v81, v79, v78
	v_max_i32_e32 v52, v33, v32
	v_max_i32_e32 v54, v53, v51
	v_min_i32_e32 v21, v25, v21
	v_max_i32_e32 v25, v57, v50
	v_min_i32_e32 v55, v31, v23
	v_max_i32_e32 v27, v28, v27
	v_min_i32_e32 v18, v18, v19
	v_min_i32_e32 v20, v22, v20
	v_min_i32_e32 v32, v33, v32
	v_min_i32_e32 v33, v53, v51
	v_max3_i32 v124, v127, v129, v124
	v_max3_i32 v69, v69, v75, v81
	v_max3_i32 v52, v131, v67, v52
	v_max3_i32 v54, v71, v73, v54
	v_max3_i32 v21, v128, v130, v21
	v_max3_i32 v25, v74, v70, v25
	v_max3_i32 v55, v66, v68, v55
	v_max3_i32 v27, v72, v76, v27
	v_max_i32_e32 v18, v77, v18
	v_max3_i32 v19, v61, v79, v78
	v_max_i32_e32 v20, v59, v20
	v_max3_i32 v22, v63, v29, v30
	v_max_i32_e32 v32, v58, v32
	v_max_i32_e32 v33, v62, v33
	v_max3_i32 v23, v60, v31, v23
	v_max3_i32 v24, v64, v24, v26
	v_min_i32_e32 v65, v52, v54
	v_min_i32_e32 v50, v21, v25
	v_min_i32_e32 v61, v18, v19
	v_min_i32_e32 v29, v20, v22
	v_min_i32_e32 v26, v23, v24
	v_max_i32_e32 v59, v124, v69
	v_max_i32_e32 v52, v52, v54
	v_max_i32_e32 v21, v21, v25
	v_max_i32_e32 v25, v55, v27
	v_max_i32_e32 v18, v18, v19
	v_max_i32_e32 v19, v20, v22
	v_max_i32_e32 v22, v32, v33
	v_max_i32_e32 v23, v23, v24
	v_min_i32_e32 v28, v55, v27
	v_max_i32_e32 v54, v59, v52
	v_max_i32_e32 v27, v21, v25
	v_max_i32_e32 v20, v18, v19
	v_max_i32_e32 v24, v22, v23
	v_min_i32_e32 v51, v32, v33
	v_max_i32_e32 v55, v54, v27
	v_max_i32_e32 v32, v20, v24
	v_min_i32_e32 v27, v54, v27
	v_min_i32_e32 v20, v20, v24
	v_max_i32_e32 v24, v27, v20
	v_min_i32_e32 v20, v27, v20
	v_min_i32_e32 v27, v59, v52
	v_min_i32_e32 v21, v21, v25
	v_min_i32_e32 v18, v18, v19
	v_min_i32_e32 v19, v22, v23
	v_min_i32_e32 v75, v124, v69
	v_max_i32_e32 v25, v27, v21
	v_max_i32_e32 v22, v18, v19
	v_min_i32_e32 v21, v27, v21
	v_min_i32_e32 v18, v18, v19
	v_min_i32_e32 v56, v50, v28
	v_min_i32_e32 v31, v51, v26
	v_max_i32_e32 v23, v25, v22
	v_min_i32_e32 v22, v25, v22
	v_max_i32_e32 v19, v21, v18
	v_min_i32_e32 v18, v21, v18
; #define LAS __attribute__((address_space(3)))
; #define MFMA32(a, b, c) __builtin_amdgcn_mfma_f32_32x32x16_bf16((a), (b), (c), 0, 0, 0)
; __device__ __forceinline__ void route_task(int task, int tl0, const bf16* QP  , const LAS bf16* KHL, LAS unsigned short* EL, LAS float* GL, int lane) {
;     ...
;         for (int kt = 0; kt < 4; ++kt) {
;             f32x16 X;
; #pragma unroll
;             for (int i = 0; i < 16; ++i) X[i] = 8.f;
;             const LAS bf16* khp = KHL + (half * 128 + 32 * kt + r) * 72 + 8 * hi;
; #pragma unroll
;             for (int ks = 0; ks < 4; ++ks) {
;                 const bf16x8 kh = lds8(khp + 16 * ks);
;                 X = MFMA32(kh, qa[half][ks], X);
;     ...
;         { const unsigned h4 = 4u * (unsigned)hi;
; #pragma unroll
;           for (int i = 0; i < 16; ++i) cur[i] -= (int)h4; }
;         int oth[16];
; #pragma unroll
;         for (int i = 0; i < 16; ++i) oth[i] = __shfl_xor(cur[i], 32);
;         merge16_desc(cur, oth);
; #pragma unroll
;         for (int i = 0; i < 16; ++i) top[half][i] = cur[i];
	v_max_i32_e32 v21, v75, v65
	v_max_i32_e32 v25, v50, v28
	v_max_i32_e32 v28, v61, v29
	v_max_i32_e32 v26, v51, v26
	v_min_i32_e32 v67, v75, v65
	v_min_i32_e32 v30, v61, v29
	v_max_i32_e32 v27, v21, v25
	v_min_i32_e32 v21, v21, v25
	v_min_i32_e32 v25, v28, v26
	v_min_i32_e32 v57, v67, v56
	v_min_i32_e32 v53, v30, v31
	v_max_i32_e32 v29, v28, v26
	v_max_i32_e32 v26, v21, v25
	v_min_i32_e32 v21, v21, v25
	v_max_i32_e32 v25, v67, v56
	v_max_i32_e32 v28, v30, v31
	v_min_i32_e32 v58, v57, v53
	v_max_i32_e32 v33, v55, v32
	v_min_i32_e32 v32, v55, v32
	v_max_i32_e32 v50, v27, v29
	v_min_i32_e32 v27, v27, v29
	v_max_i32_e32 v29, v25, v28
	v_min_i32_e32 v25, v25, v28
	v_max_i32_e32 v28, v57, v53
	v_sub_u32_e32 v30, v33, v87
	v_sub_u32_e32 v31, v32, v87
	v_sub_u32_e32 v24, v24, v87
	v_sub_u32_e32 v20, v20, v87
	v_sub_u32_e32 v23, v23, v87
	v_sub_u32_e32 v22, v22, v87
	v_sub_u32_e32 v19, v19, v87
	v_sub_u32_e32 v18, v18, v87
	v_sub_u32_e32 v32, v50, v87
	v_sub_u32_e32 v27, v27, v87
	v_sub_u32_e32 v26, v26, v87
	v_sub_u32_e32 v21, v21, v87
	v_sub_u32_e32 v29, v29, v87
	v_sub_u32_e32 v25, v25, v87
	v_sub_u32_e32 v28, v28, v87
	v_sub_u32_e32 v33, v58, v87
	ds_bpermute_b32 v50, v123, v30
	ds_bpermute_b32 v51, v123, v31
	ds_bpermute_b32 v52, v123, v24
	ds_bpermute_b32 v53, v123, v20
	ds_bpermute_b32 v54, v123, v23
	ds_bpermute_b32 v55, v123, v22
	ds_bpermute_b32 v56, v123, v19
	ds_bpermute_b32 v57, v123, v18
	ds_bpermute_b32 v58, v123, v32
	ds_bpermute_b32 v59, v123, v27
	ds_bpermute_b32 v60, v123, v26
	ds_bpermute_b32 v61, v123, v33
	ds_bpermute_b32 v62, v123, v28
	ds_bpermute_b32 v63, v123, v25
	ds_bpermute_b32 v64, v123, v29
	ds_bpermute_b32 v65, v123, v21
	s_waitcnt lgkmcnt(4)
	v_max_i32_e32 v30, v30, v61
	s_waitcnt lgkmcnt(3)
	v_max_i32_e32 v31, v31, v62
	s_waitcnt lgkmcnt(2)
	v_max_i32_e32 v24, v24, v63
	s_waitcnt lgkmcnt(1)
	v_max_i32_e32 v20, v20, v64
	s_waitcnt lgkmcnt(0)
	v_max_i32_e32 v23, v23, v65
	v_max_i32_e32 v22, v22, v60
	v_max_i32_e32 v19, v19, v59
	v_max_i32_e32 v18, v18, v58
	v_max_i32_e32 v32, v32, v57
	v_max_i32_e32 v27, v27, v56
	v_max_i32_e32 v26, v26, v55
	v_max_i32_e32 v21, v21, v54
	v_max_i32_e32 v29, v29, v53
	v_max_i32_e32 v25, v25, v52
	v_max_i32_e32 v28, v28, v51
	v_max_i32_e32 v33, v33, v50
	v_max_i32_e32 v50, v30, v32
	v_min_i32_e32 v30, v30, v32
	v_max_i32_e32 v32, v31, v27
	v_min_i32_e32 v27, v31, v27
	v_max_i32_e32 v31, v24, v26
	v_min_i32_e32 v24, v24, v26
	v_max_i32_e32 v26, v20, v21
	v_min_i32_e32 v20, v20, v21
	v_max_i32_e32 v21, v23, v29
	v_min_i32_e32 v23, v23, v29
	v_max_i32_e32 v29, v22, v25
	v_min_i32_e32 v22, v22, v25
	v_max_i32_e32 v25, v19, v28
	v_min_i32_e32 v19, v19, v28
	v_max_i32_e32 v28, v18, v33
	v_min_i32_e32 v18, v18, v33
	v_max_i32_e32 v33, v50, v21
	v_min_i32_e32 v21, v50, v21
	v_max_i32_e32 v50, v32, v29
	v_min_i32_e32 v29, v32, v29
	v_max_i32_e32 v32, v31, v25
	v_min_i32_e32 v25, v31, v25
	v_max_i32_e32 v31, v26, v28
	v_max_i32_e32 v64, v50, v31
	v_min_i32_e32 v67, v50, v31
	ds_read_b128 v[50:53], v94 offset:18432
	ds_read_b128 v[54:57], v94 offset:18464
	v_min_i32_e32 v26, v26, v28
	v_max_i32_e32 v28, v30, v23
	v_min_i32_e32 v58, v30, v23
	v_max_i32_e32 v23, v27, v22
	v_min_i32_e32 v59, v27, v22
	v_max_i32_e32 v22, v24, v19
	v_min_i32_e32 v60, v24, v19
	v_max_i32_e32 v19, v20, v18
	v_min_i32_e32 v61, v20, v18
	v_max_i32_e32 v62, v33, v32
	v_min_i32_e32 v66, v33, v32
	v_max_i32_e32 v68, v21, v25
	v_min_i32_e32 v69, v21, v25
	v_max_i32_e32 v70, v29, v26
	v_min_i32_e32 v71, v29, v26
	v_max_i32_e32 v72, v28, v22
	v_min_i32_e32 v73, v28, v22
	v_max_i32_e32 v74, v23, v19
	v_min_i32_e32 v75, v23, v19
	s_waitcnt vmcnt(3) lgkmcnt(1)
	v_mfma_f32_32x32x16_bf16 v[18:33], v[50:53], v[46:49], v[2:17]
	ds_read_b128 v[50:53], v94 offset:18496
	v_max_i32_e32 v76, v58, v60
	v_min_i32_e32 v77, v58, v60
	v_max_i32_e32 v78, v59, v61
	v_min_i32_e32 v79, v59, v61
	v_max_i32_e32 v63, v62, v64
	v_min_i32_e32 v65, v62, v64
	s_waitcnt vmcnt(2) lgkmcnt(1)
	v_mfma_f32_32x32x16_bf16 v[18:33], v[54:57], v[42:45], v[18:33]
	v_max_i32_e32 v64, v66, v67
	v_min_i32_e32 v62, v66, v67
	v_max_i32_e32 v61, v68, v70
	v_min_i32_e32 v60, v68, v70
	v_max_i32_e32 v59, v69, v71
	v_min_i32_e32 v57, v69, v71
	ds_read_b128 v[66:69], v94 offset:18528
	s_waitcnt vmcnt(1) lgkmcnt(1)
	v_mfma_f32_32x32x16_bf16 v[18:33], v[50:53], v[38:41], v[18:33]
	v_max_i32_e32 v55, v72, v74
	v_min_i32_e32 v58, v72, v74
	v_max_i32_e32 v56, v73, v75
	v_min_i32_e32 v54, v73, v75
	v_max_i32_e32 v53, v76, v78
	v_min_i32_e32 v52, v76, v78
	v_max_i32_e32 v51, v77, v79
	s_waitcnt vmcnt(0) lgkmcnt(0)
; #define LAS __attribute__((address_space(3)))
; #define MFMA32(a, b, c) __builtin_amdgcn_mfma_f32_32x32x16_bf16((a), (b), (c), 0, 0, 0)
; __device__ __forceinline__ void route_task(int task, int tl0, const bf16* QP  , const LAS bf16* KHL, LAS unsigned short* EL, LAS float* GL, int lane) {
;     ...
;     { unsigned qo = (unsigned)t * (unsigned)D + (unsigned)(head * 128 + 8 * hi); asm volatile("" : "+v"(qo)); const bf16* qp = QP + qo;
; #pragma unroll
;       for (int hf = 0; hf < 2; ++hf)
; #pragma unroll
;         for (int ks = 0; ks < 4; ++ks) qa[hf][ks] = ldg8(qp + 64 * hf + 16 * ks); }
;     ...
;         for (int kt = 0; kt < 4; ++kt) {
;             f32x16 X;
; #pragma unroll
;             for (int i = 0; i < 16; ++i) X[i] = 8.f;
;             const LAS bf16* khp = KHL + (half * 128 + 32 * kt + r) * 72 + 8 * hi;
; #pragma unroll
;             for (int ks = 0; ks < 4; ++ks) {
;                 const bf16x8 kh = lds8(khp + 16 * ks);
;                 X = MFMA32(kh, qa[half][ks], X);
;             }
;             int grp[16];
; #pragma unroll
;             for (int i = 0; i < 16; ++i) grp[i] = (int)((__float_as_uint(X[i]) | 127u) - (unsigned)(32 * kt + (i & 3) + 8 * (i >> 2)));
;             sort16_desc(grp);
;             if (kt == 0) {
; #pragma unroll
;                 for (int i = 0; i < 16; ++i) cur[i] = grp[i];
;             } else merge16_desc(cur, grp);
	v_or_b32_e32 v146, s10, v88
	v_mov_b32_e32 v147, v83
	v_lshl_add_u64 v[148:149], v[146:147], 1, s[80:81]
	global_load_dwordx4 v[150:153], v[148:149], off
	global_load_dwordx4 v[154:157], v[148:149], off offset:32
	global_load_dwordx4 v[158:161], v[148:149], off offset:64
	global_load_dwordx4 v[162:165], v[148:149], off offset:96
	global_load_dwordx4 v[166:169], v[148:149], off offset:128
	global_load_dwordx4 v[170:173], v[148:149], off offset:160
	global_load_dwordx4 v[174:177], v[148:149], off offset:192
	global_load_dwordx4 v[178:181], v[148:149], off offset:224
	v_mfma_f32_32x32x16_bf16 v[18:33], v[66:69], v[34:37], v[18:33]
	v_min_i32_e32 v50, v77, v79
	s_nop 10
	v_bitop3_b32 v21, v21, s42, 3 bitop3:0x56
	v_bitop3_b32 v32, v32, s42, 26 bitop3:0x56
	v_bitop3_b32 v22, v22, s42, 8 bitop3:0x56
	v_bitop3_b32 v26, v26, s42, 16 bitop3:0x56
	v_bitop3_b32 v31, v31, s42, 25 bitop3:0x56
	v_bitop3_b32 v23, v23, s42, 9 bitop3:0x56
	v_bitop3_b32 v24, v24, s42, 10 bitop3:0x56
	v_bitop3_b32 v27, v27, s42, 17 bitop3:0x56
	v_bitop3_b32 v28, v28, s42, 18 bitop3:0x56
	v_bitop3_b32 v20, v20, s42, 2 bitop3:0x56
	v_bitop3_b32 v33, v33, s42, 27 bitop3:0x56
	v_bitop3_b32 v25, v25, s42, 11 bitop3:0x56
	v_bitop3_b32 v29, v29, s42, 19 bitop3:0x56
	v_bitop3_b32 v19, v19, s42, 1 bitop3:0x56
	v_bitop3_b32 v30, v30, s42, 24 bitop3:0x56
	v_or_b32_e32 v18, 0x7f, v18
	v_max_i32_e32 v66, v21, v32
	v_max_i32_e32 v67, v22, v26
	v_max_i32_e32 v69, v18, v31
	v_max_i32_e32 v70, v23, v24
	v_min_i32_e32 v73, v27, v28
	v_min_i32_e32 v74, v20, v33
	v_min_i32_e32 v76, v25, v29
	v_min_i32_e32 v77, v19, v30
	v_min_i32_e32 v23, v23, v24
	v_min_i32_e32 v18, v18, v31
	v_min_i32_e32 v22, v22, v26
	v_min_i32_e32 v21, v21, v32
	v_max_i32_e32 v19, v19, v30
	v_max_i32_e32 v25, v25, v29
	v_max_i32_e32 v20, v20, v33
	v_max_i32_e32 v27, v27, v28
	v_max_i32_e32 v24, v23, v18
	v_max_i32_e32 v26, v22, v21
	v_min_i32_e32 v29, v19, v25
	v_min_i32_e32 v28, v20, v27
	v_max_i32_e32 v31, v24, v26
	v_min_i32_e32 v24, v24, v26
	v_min_i32_e32 v26, v29, v28
	v_min_i32_e32 v68, v66, v67
	v_min_i32_e32 v71, v69, v70
	v_max_i32_e32 v75, v73, v74
	v_max_i32_e32 v78, v76, v77
	v_max_i32_e32 v30, v29, v28
	v_max_i32_e32 v28, v24, v26
	v_min_i32_e32 v81, v24, v26
	v_min_i32_e32 v24, v76, v77
	v_min_i32_e32 v18, v23, v18
	v_min_i32_e32 v21, v22, v21
	v_min_i32_e32 v22, v73, v74
	v_min_i32_e32 v72, v68, v71
	v_min_i32_e32 v79, v75, v78
	v_min_i32_e32 v76, v24, v18
	v_min_i32_e32 v74, v21, v22
	v_max_i32_e32 v18, v24, v18
	v_max_i32_e32 v21, v21, v22
	v_max_i32_e32 v23, v69, v70
	v_max_i32_e32 v19, v19, v25
	v_max_i32_e32 v20, v20, v27
	v_max_i32_e32 v25, v66, v67
	v_max_i32_e32 v80, v72, v79
	v_max_i32_e32 v29, v68, v71
	v_max_i32_e32 v68, v75, v78
	v_min_i32_e32 v79, v72, v79
	v_max_i32_e32 v77, v76, v74
	v_min_i32_e32 v124, v18, v21
	v_min_i32_e32 v24, v23, v19
	v_min_i32_e32 v26, v20, v25
	v_min_i32_e32 v32, v31, v30
	v_min_i32_e32 v71, v29, v68
	v_max_i32_e32 v82, v81, v79
	v_max_i32_e32 v125, v77, v124
	v_min_i32_e32 v27, v24, v26
	v_max_i32_e32 v18, v18, v21
	v_min_i32_e32 v33, v80, v32
	v_min_i32_e32 v75, v28, v71
	v_max_i32_e32 v22, v82, v125
	v_min_i32_e32 v21, v27, v18
	v_max_i32_e32 v78, v33, v75
	v_max_i32_e32 v66, v22, v21
	v_max_i32_e32 v70, v78, v66
	v_max_i32_e32 v131, v29, v68
	v_min_i32_e32 v78, v78, v66
	ds_read_b128 v[66:69], v97
	v_max_i32_e32 v127, v23, v19
	v_max_i32_e32 v128, v20, v25
	v_max_i32_e32 v126, v24, v26
	v_min_i32_e32 v129, v127, v128
	v_max_i32_e32 v132, v31, v30
	v_min_i32_e32 v130, v126, v129
	v_min_i32_e32 v133, v131, v132
	v_max_i32_e32 v18, v27, v18
	v_min_i32_e32 v19, v130, v133
	v_max_i32_e32 v23, v80, v32
	v_max_i32_e32 v24, v28, v71
	v_min_i32_e32 v20, v18, v19
	v_min_i32_e32 v25, v23, v24
	v_min_i32_e32 v26, v20, v25
	v_min_i32_e32 v80, v70, v26
	v_max_i32_e32 v143, v70, v26
	ds_read_b128 v[70:73], v97 offset:32
	v_min_i32_e32 v75, v33, v75
	v_min_i32_e32 v134, v22, v21
	v_max_i32_e32 v138, v18, v19
	v_max_i32_e32 v139, v23, v24
	v_max_i32_e32 v141, v20, v25
	s_waitcnt lgkmcnt(1)
	v_mfma_f32_32x32x16_bf16 v[18:33], v[66:69], v[46:49], v[2:17]
	ds_read_b128 v[66:69], v97 offset:64
	v_max_i32_e32 v135, v75, v134
	v_max_i32_e32 v136, v78, v135
	v_min_i32_e32 v79, v81, v79
	v_min_i32_e32 v77, v77, v124
	v_min_i32_e32 v78, v78, v135
	v_max_i32_e32 v130, v130, v133
	s_waitcnt lgkmcnt(1)
	v_mfma_f32_32x32x16_bf16 v[18:33], v[70:73], v[42:45], v[18:33]
	ds_read_b128 v[70:73], v97 offset:96
	v_max_i32_e32 v126, v126, v129
	v_min_i32_e32 v74, v76, v74
	v_min_i32_e32 v140, v138, v139
	v_max_i32_e32 v81, v79, v77
	v_min_i32_e32 v82, v82, v125
	v_min_i32_e32 v75, v75, v134
	s_waitcnt lgkmcnt(1)
	v_mfma_f32_32x32x16_bf16 v[18:33], v[66:69], v[38:41], v[18:33]
	v_max_i32_e32 v66, v131, v132
	v_max_i32_e32 v134, v138, v139
	v_min_i32_e32 v77, v79, v77
	v_max_i32_e32 v124, v81, v82
	v_min_i32_e32 v81, v81, v82
	v_min_i32_e32 v67, v126, v66
	v_min_i32_e32 v142, v140, v141
	s_waitcnt lgkmcnt(0)
; #define LAS __attribute__((address_space(3)))
; #define MFMA32(a, b, c) __builtin_amdgcn_mfma_f32_32x32x16_bf16((a), (b), (c), 0, 0, 0)
; #define CE_(a, b) ce_desc(v[a], v[b])
; __device__ __forceinline__ void sort16_desc(int (&v)[16]) {
;     ...
;     CE_(0,13); CE_(1,12); CE_(2,15); CE_(3,14); CE_(4,8); CE_(5,6); CE_(7,11); CE_(9,10);
;     CE_(0,5); CE_(1,7); CE_(2,9); CE_(3,4); CE_(6,13); CE_(8,14); CE_(10,15); CE_(11,12);
;     CE_(0,1); CE_(2,3); CE_(4,5); CE_(6,8); CE_(7,9); CE_(10,11); CE_(12,13); CE_(14,15);
;     CE_(0,2); CE_(1,3); CE_(4,10); CE_(5,11); CE_(6,7); CE_(8,9); CE_(12,14); CE_(13,15);
;     CE_(1,2); CE_(3,12); CE_(4,6); CE_(5,7); CE_(8,10); CE_(9,11); CE_(13,14);
;     CE_(1,4); CE_(2,6); CE_(5,8); CE_(7,10); CE_(9,13); CE_(11,14);
;     CE_(2,4); CE_(3,6); CE_(9,12); CE_(11,13);
;     CE_(3,5); CE_(6,8); CE_(7,9); CE_(10,12);
;     CE_(3,4); CE_(5,6); CE_(7,8); CE_(9,10); CE_(11,12);
;     CE_(6,7); CE_(8,9);
;     ...
; }
; __device__ __forceinline__ void merge16_desc(int (&a)[16], const int (&b)[16]) {
; #pragma unroll
;     for (int i = 0; i < 16; ++i) a[i] = a[i] > b[15 - i] ? a[i] : b[15 - i];
; #pragma unroll
;     for (int j = 8; j > 0; j >>= 1)
; #pragma unroll
;         for (int i = 0; i < 16; ++i) { const int l = i ^ j; if (l > i) ce_desc(a[i], a[l]); }
; }
; __device__ __forceinline__ void route_task(int task, int tl0, const bf16* QP  , const LAS bf16* KHL, LAS unsigned short* EL, LAS float* GL, int lane) {
;     ...
;         for (int kt = 0; kt < 4; ++kt) {
;             f32x16 X;
; #pragma unroll
;             for (int i = 0; i < 16; ++i) X[i] = 8.f;
;             const LAS bf16* khp = KHL + (half * 128 + 32 * kt + r) * 72 + 8 * hi;
; #pragma unroll
;             for (int ks = 0; ks < 4; ++ks) {
;                 const bf16x8 kh = lds8(khp + 16 * ks);
;                 X = MFMA32(kh, qa[half][ks], X);
;             }
;             int grp[16];
; #pragma unroll
;             for (int i = 0; i < 16; ++i) grp[i] = (int)((__float_as_uint(X[i]) | 127u) - (unsigned)(32 * kt + (i & 3) + 8 * (i >> 2)));
;             sort16_desc(grp);
;             if (kt == 0) {
; #pragma unroll
;                 for (int i = 0; i < 16; ++i) cur[i] = grp[i];
;             } else merge16_desc(cur, grp);
	v_mfma_f32_32x32x16_bf16 v[18:33], v[70:73], v[34:37], v[18:33]
	v_min_i32_e32 v68, v130, v67
	v_min_i32_e32 v137, v80, v136
	v_min_i32_e32 v144, v142, v143
	v_min_i32_e32 v125, v124, v75
	v_min_i32_e32 v69, v134, v68
	s_nop 6
	v_bitop3_b32 v21, v21, s42, 35 bitop3:0x56
	v_bitop3_b32 v32, v32, s42, 58 bitop3:0x56
	v_bitop3_b32 v22, v22, s42, 40 bitop3:0x56
	v_bitop3_b32 v26, v26, s42, 48 bitop3:0x56
	v_bitop3_b32 v18, v18, s42, 32 bitop3:0x56
	v_bitop3_b32 v31, v31, s42, 57 bitop3:0x56
	v_bitop3_b32 v23, v23, s42, 41 bitop3:0x56
	v_bitop3_b32 v24, v24, s42, 42 bitop3:0x56
	v_bitop3_b32 v27, v27, s42, 49 bitop3:0x56
	v_bitop3_b32 v28, v28, s42, 50 bitop3:0x56
	v_bitop3_b32 v20, v20, s42, 34 bitop3:0x56
	v_bitop3_b32 v33, v33, s42, 59 bitop3:0x56
	v_bitop3_b32 v25, v25, s42, 43 bitop3:0x56
	v_bitop3_b32 v29, v29, s42, 51 bitop3:0x56
	v_bitop3_b32 v19, v19, s42, 33 bitop3:0x56
	v_bitop3_b32 v30, v30, s42, 56 bitop3:0x56
	v_max_i32_e32 v70, v21, v32
	v_max_i32_e32 v71, v22, v26
	v_max_i32_e32 v73, v18, v31
	v_max_i32_e32 v76, v23, v24
	v_min_i32_e32 v129, v27, v28
	v_min_i32_e32 v131, v20, v33
	v_min_i32_e32 v133, v25, v29
	v_min_i32_e32 v135, v19, v30
	v_min_i32_e32 v23, v23, v24
	v_min_i32_e32 v18, v18, v31
	v_min_i32_e32 v22, v22, v26
	v_min_i32_e32 v21, v21, v32
	v_max_i32_e32 v19, v19, v30
	v_max_i32_e32 v25, v25, v29
	v_max_i32_e32 v20, v20, v33
	v_max_i32_e32 v27, v27, v28
	v_min_i32_e32 v72, v70, v71
	v_min_i32_e32 v79, v73, v76
	v_max_i32_e32 v132, v129, v131
	v_max_i32_e32 v138, v133, v135
	v_max_i32_e32 v24, v23, v18
	v_max_i32_e32 v26, v22, v21
	v_min_i32_e32 v29, v19, v25
	v_min_i32_e32 v28, v20, v27
	v_min_i32_e32 v133, v133, v135
	v_min_i32_e32 v18, v23, v18
	v_min_i32_e32 v21, v22, v21
	v_min_i32_e32 v22, v129, v131
	v_max_i32_e32 v73, v73, v76
	v_max_i32_e32 v19, v19, v25
	v_max_i32_e32 v20, v20, v27
	v_max_i32_e32 v27, v70, v71
	v_min_i32_e32 v82, v72, v79
	v_min_i32_e32 v139, v132, v138
	v_max_i32_e32 v31, v24, v26
	v_max_i32_e32 v30, v29, v28
	v_min_i32_e32 v24, v24, v26
	v_min_i32_e32 v26, v29, v28
	v_max_i32_e32 v29, v72, v79
	v_max_i32_e32 v72, v132, v138
	v_min_i32_e32 v23, v133, v18
	v_min_i32_e32 v129, v21, v22
	v_max_i32_e32 v18, v133, v18
	v_max_i32_e32 v21, v21, v22
	v_min_i32_e32 v25, v73, v19
	v_min_i32_e32 v70, v20, v27
	v_max_i32_e32 v19, v73, v19
	v_max_i32_e32 v20, v20, v27
	v_min_i32_e32 v32, v31, v30
	v_max_i32_e32 v28, v24, v26
	v_min_i32_e32 v79, v29, v72
	v_min_i32_e32 v24, v24, v26
	v_min_i32_e32 v26, v82, v139
	v_max_i32_e32 v131, v23, v129
	v_min_i32_e32 v22, v18, v21
	v_min_i32_e32 v71, v25, v70
	v_max_i32_e32 v25, v25, v70
	v_min_i32_e32 v27, v19, v20
	v_max_i32_e32 v29, v29, v72
	v_max_i32_e32 v30, v31, v30
	v_max_i32_e32 v145, v82, v139
	v_max_i32_e32 v82, v24, v26
	v_max_i32_e32 v133, v131, v22
	v_max_i32_e32 v18, v18, v21
	v_min_i32_e32 v70, v25, v27
	v_min_i32_e32 v31, v29, v30
	v_min_i32_e32 v33, v145, v32
	v_min_i32_e32 v132, v28, v79
	v_max_i32_e32 v135, v82, v133
	v_min_i32_e32 v21, v71, v18
	v_max_i32_e32 v18, v71, v18
	v_min_i32_e32 v71, v70, v31
	v_max_i32_e32 v32, v145, v32
	v_max_i32_e32 v28, v28, v79
	v_max_i32_e32 v138, v33, v132
	v_max_i32_e32 v76, v135, v21
	v_min_i32_e32 v72, v18, v71
	v_min_i32_e32 v73, v32, v28
	v_min_i32_e32 v33, v33, v132
	v_min_i32_e32 v21, v135, v21
	v_max_i32_e32 v18, v18, v71
	v_max_i32_e32 v28, v32, v28
	v_min_i32_e32 v24, v24, v26
	v_min_i32_e32 v22, v131, v22
	v_max_i32_e32 v25, v25, v27
	v_max_i32_e32 v27, v29, v30
	v_max_i32_e32 v139, v138, v76
	v_min_i32_e32 v79, v72, v73
	v_min_i32_e32 v76, v138, v76
	v_max_i32_e32 v132, v33, v21
	v_min_i32_e32 v32, v18, v28
	v_max_i32_e32 v71, v72, v73
	v_max_i32_e32 v26, v24, v22
	v_min_i32_e32 v82, v82, v133
	v_max_i32_e32 v18, v18, v28
	v_max_i32_e32 v28, v70, v31
	v_min_i32_e32 v29, v25, v27
	v_min_i32_e32 v145, v139, v79
	v_max_i32_e32 v135, v76, v132
	v_min_i32_e32 v72, v32, v71
	v_max_i32_e32 v73, v139, v79
	v_max_i32_e32 v131, v26, v82
	v_min_i32_e32 v21, v33, v21
	v_min_i32_e32 v30, v28, v29
	v_min_i32_e32 v138, v145, v135
	v_min_i32_e32 v79, v72, v73
	v_min_i32_e32 v33, v131, v21
	v_min_i32_e32 v76, v76, v132
	v_min_i32_e32 v31, v18, v30
	v_min_i32_e32 v26, v26, v82
	v_min_i32_e32 v22, v24, v22
	v_min_i32_e32 v23, v23, v129
	v_max3_i32 v23, v127, v128, v23
	v_max3_i32 v22, v126, v66, v22
	v_max3_i32 v24, v130, v67, v26
	v_max3_i32 v26, v134, v68, v33
	v_max3_i32 v21, v69, v131, v21
	v_max3_i32 v33, v140, v141, v76
	v_max3_i32 v66, v142, v143, v138
	v_max3_i32 v67, v144, v145, v135
	v_max3_i32 v68, v80, v136, v79
	v_max3_i32 v69, v137, v72, v73
	v_max3_i32 v32, v78, v32, v71
	v_max3_i32 v31, v124, v75, v31
	v_max3_i32 v18, v125, v18, v30
	v_max3_i32 v28, v81, v28, v29
	v_max3_i32 v25, v77, v25, v27
	v_max3_i32 v19, v74, v19, v20
	v_max_i32_e32 v20, v23, v68
	v_min_i32_e32 v23, v23, v68
	v_max_i32_e32 v27, v22, v69
	v_min_i32_e32 v22, v22, v69
	v_max_i32_e32 v29, v24, v32
	v_min_i32_e32 v24, v24, v32
	v_max_i32_e32 v30, v26, v31
	v_min_i32_e32 v26, v26, v31
	v_max_i32_e32 v31, v21, v18
	v_min_i32_e32 v18, v21, v18
	v_max_i32_e32 v21, v33, v28
	v_min_i32_e32 v28, v33, v28
	v_max_i32_e32 v32, v66, v25
	v_min_i32_e32 v25, v66, v25
	v_max_i32_e32 v33, v67, v19
	v_min_i32_e32 v19, v67, v19
	ds_read_b128 v[66:69], v94 offset:27648
	v_max_i32_e32 v70, v20, v31
	v_min_i32_e32 v74, v20, v31
	v_max_i32_e32 v20, v27, v21
	v_min_i32_e32 v75, v27, v21
	v_max_i32_e32 v21, v29, v32
	v_max_i32_e32 v27, v30, v33
	v_max_i32_e32 v127, v70, v21
	v_min_i32_e32 v128, v70, v21
	ds_read_b128 v[70:73], v94 offset:27680
	v_min_i32_e32 v76, v29, v32
	v_min_i32_e32 v77, v30, v33
	v_max_i32_e32 v78, v23, v18
	v_min_i32_e32 v79, v23, v18
	v_max_i32_e32 v80, v22, v28
	v_min_i32_e32 v81, v22, v28
	v_max_i32_e32 v82, v24, v25
	v_min_i32_e32 v124, v24, v25
	v_max_i32_e32 v125, v26, v19
	v_min_i32_e32 v126, v26, v19
	v_max_i32_e32 v129, v20, v27
	v_min_i32_e32 v130, v20, v27
	s_waitcnt lgkmcnt(1)
; #define LAS __attribute__((address_space(3)))
; #define MFMA32(a, b, c) __builtin_amdgcn_mfma_f32_32x32x16_bf16((a), (b), (c), 0, 0, 0)
; #define CE_(a, b) ce_desc(v[a], v[b])
; __device__ __forceinline__ void sort16_desc(int (&v)[16]) {
;     ...
;     CE_(0,13); CE_(1,12); CE_(2,15); CE_(3,14); CE_(4,8); CE_(5,6); CE_(7,11); CE_(9,10);
;     CE_(0,5); CE_(1,7); CE_(2,9); CE_(3,4); CE_(6,13); CE_(8,14); CE_(10,15); CE_(11,12);
;     CE_(0,1); CE_(2,3); CE_(4,5); CE_(6,8); CE_(7,9); CE_(10,11); CE_(12,13); CE_(14,15);
;     CE_(0,2); CE_(1,3); CE_(4,10); CE_(5,11); CE_(6,7); CE_(8,9); CE_(12,14); CE_(13,15);
;     CE_(1,2); CE_(3,12); CE_(4,6); CE_(5,7); CE_(8,10); CE_(9,11); CE_(13,14);
;     CE_(1,4); CE_(2,6); CE_(5,8); CE_(7,10); CE_(9,13); CE_(11,14);
;     CE_(2,4); CE_(3,6); CE_(9,12); CE_(11,13);
;     CE_(3,5); CE_(6,8); CE_(7,9); CE_(10,12);
;     CE_(3,4); CE_(5,6); CE_(7,8); CE_(9,10); CE_(11,12);
;     CE_(6,7); CE_(8,9);
;     ...
; }
; __device__ __forceinline__ void merge16_desc(int (&a)[16], const int (&b)[16]) {
; #pragma unroll
;     for (int i = 0; i < 16; ++i) a[i] = a[i] > b[15 - i] ? a[i] : b[15 - i];
; #pragma unroll
;     for (int j = 8; j > 0; j >>= 1)
; #pragma unroll
;         for (int i = 0; i < 16; ++i) { const int l = i ^ j; if (l > i) ce_desc(a[i], a[l]); }
; }
; __device__ __forceinline__ void route_task(int task, int tl0, const bf16* QP  , const LAS bf16* KHL, LAS unsigned short* EL, LAS float* GL, int lane) {
;     ...
;         for (int kt = 0; kt < 4; ++kt) {
;             f32x16 X;
; #pragma unroll
;             for (int i = 0; i < 16; ++i) X[i] = 8.f;
;             const LAS bf16* khp = KHL + (half * 128 + 32 * kt + r) * 72 + 8 * hi;
; #pragma unroll
;             for (int ks = 0; ks < 4; ++ks) {
;                 const bf16x8 kh = lds8(khp + 16 * ks);
;                 X = MFMA32(kh, qa[half][ks], X);
;             }
;             int grp[16];
; #pragma unroll
;             for (int i = 0; i < 16; ++i) grp[i] = (int)((__float_as_uint(X[i]) | 127u) - (unsigned)(32 * kt + (i & 3) + 8 * (i >> 2)));
;             sort16_desc(grp);
;             if (kt == 0) {
; #pragma unroll
;                 for (int i = 0; i < 16; ++i) cur[i] = grp[i];
;             } else merge16_desc(cur, grp);
	v_mfma_f32_32x32x16_bf16 v[18:33], v[66:69], v[46:49], v[2:17]
	ds_read_b128 v[66:69], v94 offset:27712
	v_max_i32_e32 v131, v74, v76
	v_min_i32_e32 v74, v74, v76
	v_max_i32_e32 v76, v75, v77
	v_min_i32_e32 v75, v75, v77
	v_max_i32_e32 v77, v78, v82
	v_min_i32_e32 v78, v78, v82
	s_waitcnt lgkmcnt(1)
	v_mfma_f32_32x32x16_bf16 v[18:33], v[70:73], v[42:45], v[18:33]
	ds_read_b128 v[70:73], v94 offset:27744
	v_max_i32_e32 v82, v80, v125
	v_min_i32_e32 v80, v80, v125
	v_max_i32_e32 v125, v79, v124
	v_min_i32_e32 v79, v79, v124
	v_max_i32_e32 v124, v81, v126
	v_min_i32_e32 v81, v81, v126
	s_waitcnt lgkmcnt(1)
	v_mfma_f32_32x32x16_bf16 v[18:33], v[66:69], v[38:41], v[18:33]
	v_min_i32_e32 v126, v127, v129
	v_min_i32_e32 v66, v128, v130
	v_min_i32_e32 v67, v131, v76
	v_min_i32_e32 v69, v77, v82
	v_min_i32_e32 v132, v78, v80
	v_min_i32_e32 v133, v125, v124
	v_min_i32_e32 v68, v74, v75
	s_waitcnt lgkmcnt(0)
	v_mfma_f32_32x32x16_bf16 v[18:33], v[70:73], v[34:37], v[18:33]
	v_min_i32_e32 v134, v79, v81
	s_nop 10
	v_and_or_b32 v21, v21, s43, 60
	v_and_or_b32 v32, v32, s43, 37
	v_and_or_b32 v22, v22, s43, 55
	v_and_or_b32 v26, v26, s43, 47
	v_bitop3_b32 v18, v18, s42, 64 bitop3:0x56
	v_and_or_b32 v31, v31, s43, 38
	v_and_or_b32 v23, v23, s43, 54
	v_and_or_b32 v24, v24, s43, 53
	v_and_or_b32 v27, v27, s43, 46
	v_and_or_b32 v28, v28, s43, 45
	v_and_or_b32 v20, v20, s43, 61
	v_and_or_b32 v33, v33, s43, 36
	v_and_or_b32 v25, v25, s43, 52
	v_and_or_b32 v29, v29, s43, 44
	v_and_or_b32 v19, v19, s43, 62
	v_and_or_b32 v30, v30, s43, 39
	v_max_i32_e32 v70, v21, v32
	v_max_i32_e32 v71, v22, v26
	v_max_i32_e32 v73, v18, v31
	v_max_i32_e32 v135, v23, v24
	v_min_i32_e32 v138, v27, v28
	v_min_i32_e32 v139, v20, v33
	v_min_i32_e32 v141, v25, v29
	v_min_i32_e32 v142, v19, v30
	v_min_i32_e32 v23, v23, v24
	v_min_i32_e32 v18, v18, v31
	v_min_i32_e32 v22, v22, v26
	v_min_i32_e32 v21, v21, v32
	v_max_i32_e32 v19, v19, v30
	v_max_i32_e32 v25, v25, v29
	v_max_i32_e32 v20, v20, v33
	v_max_i32_e32 v27, v27, v28
	v_min_i32_e32 v72, v70, v71
	v_min_i32_e32 v136, v73, v135
	v_max_i32_e32 v140, v138, v139
	v_max_i32_e32 v143, v141, v142
	v_max_i32_e32 v24, v23, v18
	v_max_i32_e32 v26, v22, v21
	v_min_i32_e32 v29, v19, v25
	v_min_i32_e32 v28, v20, v27
	v_min_i32_e32 v141, v141, v142
	v_min_i32_e32 v18, v23, v18
	v_min_i32_e32 v21, v22, v21
	v_min_i32_e32 v22, v138, v139
	v_max_i32_e32 v73, v73, v135
	v_max_i32_e32 v19, v19, v25
	v_max_i32_e32 v20, v20, v27
	v_max_i32_e32 v27, v70, v71
	v_min_i32_e32 v137, v72, v136
	v_min_i32_e32 v144, v140, v143
	v_max_i32_e32 v31, v24, v26
	v_max_i32_e32 v30, v29, v28
	v_min_i32_e32 v24, v24, v26
	v_min_i32_e32 v26, v29, v28
	v_max_i32_e32 v29, v72, v136
	v_max_i32_e32 v72, v140, v143
	v_min_i32_e32 v23, v141, v18
	v_min_i32_e32 v138, v21, v22
	v_max_i32_e32 v18, v141, v18
	v_max_i32_e32 v21, v21, v22
	v_min_i32_e32 v25, v73, v19
	v_min_i32_e32 v70, v20, v27
	v_max_i32_e32 v19, v73, v19
	v_max_i32_e32 v20, v20, v27
	v_min_i32_e32 v32, v31, v30
	v_max_i32_e32 v28, v24, v26
	v_min_i32_e32 v136, v29, v72
	v_min_i32_e32 v24, v24, v26
	v_min_i32_e32 v26, v137, v144
	v_max_i32_e32 v139, v23, v138
	v_min_i32_e32 v22, v18, v21
	v_min_i32_e32 v71, v25, v70
	v_max_i32_e32 v25, v25, v70
	v_min_i32_e32 v27, v19, v20
	v_max_i32_e32 v29, v29, v72
	v_max_i32_e32 v30, v31, v30
	v_max_i32_e32 v145, v137, v144
	v_max_i32_e32 v137, v24, v26
	v_max_i32_e32 v141, v139, v22
	v_max_i32_e32 v18, v18, v21
	v_min_i32_e32 v70, v25, v27
	v_min_i32_e32 v31, v29, v30
	v_min_i32_e32 v33, v145, v32
	v_min_i32_e32 v140, v28, v136
	v_max_i32_e32 v142, v137, v141
	v_min_i32_e32 v21, v71, v18
	v_max_i32_e32 v18, v71, v18
	v_min_i32_e32 v71, v70, v31
	v_max_i32_e32 v32, v145, v32
	v_max_i32_e32 v28, v28, v136
	v_max_i32_e32 v143, v33, v140
	v_max_i32_e32 v135, v142, v21
	v_min_i32_e32 v72, v18, v71
	v_min_i32_e32 v73, v32, v28
	v_min_i32_e32 v33, v33, v140
	v_min_i32_e32 v21, v142, v21
	v_max_i32_e32 v18, v18, v71
	v_max_i32_e32 v28, v32, v28
	v_min_i32_e32 v24, v24, v26
	v_min_i32_e32 v22, v139, v22
	v_max_i32_e32 v25, v25, v27
	v_max_i32_e32 v27, v29, v30
	v_max_i32_e32 v144, v143, v135
	v_min_i32_e32 v136, v72, v73
	v_min_i32_e32 v135, v143, v135
	v_max_i32_e32 v140, v33, v21
	v_min_i32_e32 v32, v18, v28
	v_max_i32_e32 v71, v72, v73
	v_max_i32_e32 v26, v24, v22
	v_min_i32_e32 v137, v137, v141
	v_max_i32_e32 v18, v18, v28
	v_max_i32_e32 v28, v70, v31
	v_min_i32_e32 v29, v25, v27
	v_min_i32_e32 v145, v144, v136
	v_max_i32_e32 v142, v135, v140
	v_min_i32_e32 v72, v32, v71
	v_max_i32_e32 v73, v144, v136
	v_max_i32_e32 v139, v26, v137
	v_min_i32_e32 v21, v33, v21
	v_min_i32_e32 v30, v28, v29
	v_min_i32_e32 v143, v145, v142
	v_min_i32_e32 v136, v72, v73
	v_min_i32_e32 v33, v139, v21
	v_max_i32_e32 v21, v139, v21
	v_min_i32_e32 v135, v135, v140
	v_max_i32_e32 v32, v32, v71
	v_min_i32_e32 v31, v18, v30
	v_max_i32_e32 v18, v18, v30
	v_min_i32_e32 v26, v26, v137
	v_min_i32_e32 v22, v24, v22
	v_max_i32_e32 v24, v25, v27
	v_min_i32_e32 v23, v23, v138
	v_max3_i32 v23, v127, v129, v23
	v_max_i32_e32 v22, v126, v22
	v_max3_i32 v25, v128, v130, v26
	v_max_i32_e32 v26, v66, v33
	v_max3_i32 v21, v131, v76, v21
	v_max_i32_e32 v27, v67, v135
	v_max3_i32 v30, v74, v75, v143
	v_max3_i32 v66, v77, v82, v136
	v_max3_i32 v67, v69, v72, v73
	v_max3_i32 v32, v78, v80, v32
	v_max_i32_e32 v31, v132, v31
	v_max3_i32 v18, v125, v124, v18
	v_max3_i32 v28, v133, v28, v29
	v_max3_i32 v24, v79, v81, v24
	v_max3_i32 v33, v68, v145, v142
	v_max3_i32 v19, v134, v19, v20
	v_max_i32_e32 v20, v23, v66
	v_min_i32_e32 v23, v23, v66
	v_max_i32_e32 v29, v22, v67
	v_max_i32_e32 v66, v25, v32
	v_min_i32_e32 v25, v25, v32
	v_max_i32_e32 v32, v26, v31
	v_min_i32_e32 v26, v26, v31
	v_max_i32_e32 v31, v21, v18
	v_min_i32_e32 v18, v21, v18
	v_max_i32_e32 v21, v27, v28
	v_min_i32_e32 v27, v27, v28
	v_max_i32_e32 v28, v30, v24
	v_min_i32_e32 v22, v22, v67
	v_min_i32_e32 v24, v30, v24
	v_max_i32_e32 v30, v33, v19
	v_min_i32_e32 v19, v33, v19
	v_max_i32_e32 v33, v20, v31
	v_min_i32_e32 v74, v20, v31
	v_max_i32_e32 v20, v29, v21
	v_min_i32_e32 v75, v29, v21
	v_max_i32_e32 v21, v66, v28
	v_min_i32_e32 v76, v66, v28
	ds_read_b128 v[66:69], v98
	ds_read_b128 v[70:73], v98 offset:32
	v_max_i32_e32 v28, v32, v30
	v_min_i32_e32 v77, v32, v30
	v_max_i32_e32 v78, v23, v18
	v_min_i32_e32 v79, v23, v18
	v_max_i32_e32 v80, v22, v27
	v_min_i32_e32 v81, v22, v27
	v_max_i32_e32 v82, v25, v24
	v_min_i32_e32 v124, v25, v24
	v_max_i32_e32 v125, v26, v19
	v_min_i32_e32 v126, v26, v19
	v_max_i32_e32 v127, v33, v21
	v_min_i32_e32 v128, v33, v21
	v_max_i32_e32 v129, v20, v28
	v_min_i32_e32 v130, v20, v28
	s_waitcnt lgkmcnt(1)
; #define LAS __attribute__((address_space(3)))
; #define MFMA32(a, b, c) __builtin_amdgcn_mfma_f32_32x32x16_bf16((a), (b), (c), 0, 0, 0)
; #define CE_(a, b) ce_desc(v[a], v[b])
; __device__ __forceinline__ void sort16_desc(int (&v)[16]) {
;     ...
;     CE_(0,13); CE_(1,12); CE_(2,15); CE_(3,14); CE_(4,8); CE_(5,6); CE_(7,11); CE_(9,10);
;     CE_(0,5); CE_(1,7); CE_(2,9); CE_(3,4); CE_(6,13); CE_(8,14); CE_(10,15); CE_(11,12);
;     CE_(0,1); CE_(2,3); CE_(4,5); CE_(6,8); CE_(7,9); CE_(10,11); CE_(12,13); CE_(14,15);
;     CE_(0,2); CE_(1,3); CE_(4,10); CE_(5,11); CE_(6,7); CE_(8,9); CE_(12,14); CE_(13,15);
;     CE_(1,2); CE_(3,12); CE_(4,6); CE_(5,7); CE_(8,10); CE_(9,11); CE_(13,14);
;     CE_(1,4); CE_(2,6); CE_(5,8); CE_(7,10); CE_(9,13); CE_(11,14);
;     CE_(2,4); CE_(3,6); CE_(9,12); CE_(11,13);
;     CE_(3,5); CE_(6,8); CE_(7,9); CE_(10,12);
;     CE_(3,4); CE_(5,6); CE_(7,8); CE_(9,10); CE_(11,12);
;     CE_(6,7); CE_(8,9);
;     ...
; }
; __device__ __forceinline__ void merge16_desc(int (&a)[16], const int (&b)[16]) {
; #pragma unroll
;     for (int i = 0; i < 16; ++i) a[i] = a[i] > b[15 - i] ? a[i] : b[15 - i];
; #pragma unroll
;     for (int j = 8; j > 0; j >>= 1)
; #pragma unroll
;         for (int i = 0; i < 16; ++i) { const int l = i ^ j; if (l > i) ce_desc(a[i], a[l]); }
; }
; __device__ __forceinline__ void route_task(int task, int tl0, const bf16* QP  , const LAS bf16* KHL, LAS unsigned short* EL, LAS float* GL, int lane) {
;     ...
;         for (int kt = 0; kt < 4; ++kt) {
;             f32x16 X;
; #pragma unroll
;             for (int i = 0; i < 16; ++i) X[i] = 8.f;
;             const LAS bf16* khp = KHL + (half * 128 + 32 * kt + r) * 72 + 8 * hi;
; #pragma unroll
;             for (int ks = 0; ks < 4; ++ks) {
;                 const bf16x8 kh = lds8(khp + 16 * ks);
;                 X = MFMA32(kh, qa[half][ks], X);
;             }
;             int grp[16];
; #pragma unroll
;             for (int i = 0; i < 16; ++i) grp[i] = (int)((__float_as_uint(X[i]) | 127u) - (unsigned)(32 * kt + (i & 3) + 8 * (i >> 2)));
;             sort16_desc(grp);
;             if (kt == 0) {
; #pragma unroll
;                 for (int i = 0; i < 16; ++i) cur[i] = grp[i];
;             } else merge16_desc(cur, grp);
	v_mfma_f32_32x32x16_bf16 v[18:33], v[66:69], v[46:49], v[2:17]
	ds_read_b128 v[46:49], v98 offset:64
	v_max_i32_e32 v67, v75, v77
	v_min_i32_e32 v68, v75, v77
	v_max_i32_e32 v75, v80, v125
	v_max_i32_e32 v131, v74, v76
	v_min_i32_e32 v66, v74, v76
	v_max_i32_e32 v69, v78, v82
	s_waitcnt lgkmcnt(1)
	v_mfma_f32_32x32x16_bf16 v[18:33], v[70:73], v[42:45], v[18:33]
	ds_read_b128 v[42:45], v98 offset:96
	v_min_i32_e32 v70, v80, v125
	v_max_i32_e32 v71, v79, v124
	v_min_i32_e32 v72, v79, v124
	v_min_i32_e32 v74, v78, v82
	v_max_i32_e32 v73, v81, v126
	v_min_i32_e32 v76, v81, v126
	s_waitcnt lgkmcnt(1)
	v_mfma_f32_32x32x16_bf16 v[18:33], v[46:49], v[38:41], v[18:33]
	v_min_i32_e32 v77, v127, v129
	v_min_i32_e32 v38, v128, v130
	v_min_i32_e32 v39, v131, v67
	v_min_i32_e32 v40, v66, v68
	v_min_i32_e32 v41, v69, v75
	v_min_i32_e32 v46, v74, v70
	v_min_i32_e32 v47, v71, v73
	s_waitcnt lgkmcnt(0)
	v_mfma_f32_32x32x16_bf16 v[18:33], v[42:45], v[34:37], v[18:33]
	v_min_i32_e32 v48, v72, v76
	s_nop 10
	v_and_or_b32 v25, v25, s43, 20
	v_and_or_b32 v29, v29, s43, 12
	v_and_or_b32 v19, v19, s43, 30
	v_and_or_b32 v30, v30, s43, 7
	v_and_or_b32 v23, v23, s43, 22
	v_and_or_b32 v24, v24, s43, 21
	v_and_or_b32 v18, v18, s43, 31
	v_and_or_b32 v31, v31, s43, 6
	v_and_or_b32 v22, v22, s43, 23
	v_and_or_b32 v26, v26, s43, 15
	v_and_or_b32 v21, v21, s43, 28
	v_and_or_b32 v32, v32, s43, 5
	v_and_or_b32 v27, v27, s43, 14
	v_and_or_b32 v28, v28, s43, 13
	v_and_or_b32 v20, v20, s43, 29
	v_and_or_b32 v33, v33, s43, 4
	v_min_i32_e32 v34, v25, v29
	v_min_i32_e32 v35, v19, v30
	v_min_i32_e32 v37, v23, v24
	v_min_i32_e32 v42, v18, v31
	v_min_i32_e32 v45, v22, v26
	v_min_i32_e32 v49, v21, v32
	v_min_i32_e32 v79, v27, v28
	v_min_i32_e32 v80, v20, v33
	v_max_i32_e32 v18, v18, v31
	v_max_i32_e32 v23, v23, v24
	v_max_i32_e32 v19, v19, v30
	v_max_i32_e32 v25, v25, v29
	v_max_i32_e32 v20, v20, v33
	v_max_i32_e32 v27, v27, v28
	v_max_i32_e32 v21, v21, v32
	v_max_i32_e32 v22, v22, v26
	v_max_i32_e32 v24, v18, v23
	v_max_i32_e32 v29, v19, v25
	v_max_i32_e32 v28, v20, v27
	v_max_i32_e32 v26, v21, v22
	v_min_i32_e32 v30, v24, v29
	v_min_i32_e32 v31, v28, v26
	v_min_i32_e32 v43, v37, v42
	v_min_i32_e32 v32, v30, v31
	v_max_i32_e32 v30, v30, v31
	v_min_i32_e32 v21, v21, v22
	v_min_i32_e32 v18, v18, v23
	v_max_i32_e32 v23, v79, v80
	v_max_i32_e32 v31, v34, v35
	v_max_i32_e32 v37, v37, v42
	v_max_i32_e32 v42, v45, v49
	v_min_i32_e32 v19, v19, v25
	v_min_i32_e32 v20, v20, v27
	v_min_i32_e32 v36, v34, v35
	v_min_i32_e32 v78, v45, v49
	v_min_i32_e32 v81, v79, v80
	v_max_i32_e32 v22, v21, v18
	v_max_i32_e32 v45, v37, v42
	v_max_i32_e32 v25, v19, v20
	v_min_i32_e32 v18, v21, v18
	v_min_i32_e32 v21, v23, v31
	v_min_i32_e32 v44, v36, v43
	v_min_i32_e32 v82, v78, v81
	v_max_i32_e32 v33, v36, v43
	v_max_i32_e32 v36, v78, v81
	v_max_i32_e32 v24, v24, v29
	v_max_i32_e32 v26, v28, v26
	v_max_i32_e32 v34, v23, v31
	v_max_i32_e32 v27, v45, v25
	v_max_i32_e32 v23, v18, v21
	v_min_i32_e32 v25, v45, v25
	v_min_i32_e32 v37, v37, v42
	v_min_i32_e32 v19, v19, v20
	v_max_i32_e32 v43, v33, v36
	v_min_i32_e32 v28, v24, v26
	v_max_i32_e32 v35, v22, v34
	v_max_i32_e32 v31, v23, v25
	v_max_i32_e32 v20, v37, v19
	v_min_i32_e32 v23, v23, v25
	v_min_i32_e32 v19, v37, v19
	v_min_i32_e32 v18, v18, v21
	v_max_i32_e32 v25, v44, v82
	v_min_i32_e32 v33, v33, v36
	v_min_i32_e32 v29, v30, v28
	v_min_i32_e32 v49, v35, v27
	v_min_i32_e32 v22, v22, v34
	v_max_i32_e32 v21, v19, v18
	v_max_i32_e32 v36, v25, v33
	v_max_i32_e32 v78, v32, v43
	v_min_i32_e32 v79, v29, v49
	v_max_i32_e32 v34, v20, v22
	v_min_i32_e32 v20, v20, v22
	v_max_i32_e32 v37, v21, v36
	v_min_i32_e32 v32, v32, v43
	v_max_i32_e32 v80, v78, v79
	v_max_i32_e32 v42, v31, v34
	v_min_i32_e32 v78, v78, v79
	v_min_i32_e32 v31, v31, v34
	v_max_i32_e32 v22, v23, v20
	v_max_i32_e32 v43, v37, v32
	v_min_i32_e32 v18, v19, v18
	v_min_i32_e32 v19, v25, v33
	v_min_i32_e32 v20, v23, v20
	v_min_i32_e32 v23, v37, v32
	v_max_i32_e32 v28, v30, v28
	v_max_i32_e32 v27, v35, v27
	v_min_i32_e32 v124, v44, v82
	v_min_i32_e32 v45, v80, v42
	v_max_i32_e32 v34, v78, v31
	v_max_i32_e32 v44, v22, v43
	v_min_i32_e32 v31, v78, v31
	v_max_i32_e32 v25, v18, v19
	v_min_i32_e32 v21, v21, v36
	v_min_i32_e32 v32, v20, v23
	v_max_i32_e32 v29, v29, v49
	v_min_i32_e32 v30, v28, v27
	v_min_i32_e32 v22, v22, v43
	v_max_i32_e32 v20, v20, v23
	v_min_i32_e32 v79, v45, v34
	v_max_i32_e32 v78, v44, v31
	v_max_i32_e32 v33, v25, v21
	v_max_i32_e32 v37, v80, v42
	v_min_i32_e32 v35, v29, v30
	v_min_i32_e32 v31, v44, v31
	v_max_i32_e32 v23, v22, v20
	v_min_i32_e32 v81, v79, v78
	v_max_i32_e32 v36, v33, v32
	v_max_i32_e32 v42, v37, v35
	v_min_i32_e32 v21, v25, v21
	v_max_i32_e32 v25, v45, v34
	v_min_i32_e32 v43, v31, v23
	v_max_i32_e32 v27, v28, v27
	v_min_i32_e32 v18, v18, v19
	v_min_i32_e32 v20, v22, v20
	v_min_i32_e32 v32, v33, v32
	v_min_i32_e32 v33, v37, v35
	v_max3_i32 v124, v127, v129, v124
	v_max3_i32 v69, v69, v75, v81
	v_max3_i32 v36, v131, v67, v36
	v_max3_i32 v42, v71, v73, v42
	v_max3_i32 v21, v128, v130, v21
	v_max3_i32 v25, v74, v70, v25
	v_max3_i32 v43, v66, v68, v43
	v_max3_i32 v27, v72, v76, v27
	v_max_i32_e32 v18, v77, v18
	v_max3_i32 v19, v41, v79, v78
	v_max_i32_e32 v20, v39, v20
	v_max3_i32 v22, v47, v29, v30
	v_max_i32_e32 v32, v38, v32
	v_max_i32_e32 v33, v46, v33
	v_max3_i32 v23, v40, v31, v23
	v_max3_i32 v24, v48, v24, v26
	v_min_i32_e32 v49, v36, v42
	v_min_i32_e32 v34, v21, v25
	v_min_i32_e32 v41, v18, v19
	v_min_i32_e32 v29, v20, v22
	v_min_i32_e32 v26, v23, v24
	v_max_i32_e32 v39, v124, v69
	v_max_i32_e32 v36, v36, v42
	v_max_i32_e32 v21, v21, v25
	v_max_i32_e32 v25, v43, v27
; __device__ __forceinline__ void route_task(int task, int tl0, const bf16* QP  , const LAS bf16* KHL, LAS unsigned short* EL, LAS float* GL, int lane) {
;     ...
;         { const unsigned h4 = 4u * (unsigned)hi;
; #pragma unroll
;           for (int i = 0; i < 16; ++i) cur[i] -= (int)h4; }
;         int oth[16];
; #pragma unroll
;         for (int i = 0; i < 16; ++i) oth[i] = __shfl_xor(cur[i], 32);
;         merge16_desc(cur, oth);
; #pragma unroll
;         for (int i = 0; i < 16; ++i) top[half][i] = cur[i];
;     }
;     unsigned P1[4], P2[4];
; #pragma unroll
;     for (int q = 0; q < 4; ++q) { P1[q] = 0u; P2[q] = 0u;
; #pragma unroll
;         for (int s = 0; s < 4; ++s) { P1[q] |= (127u - ((unsigned)top[0][4 * q + s] & 127u)) << (8 * s); P2[q] |= (127u - ((unsigned)top[1][4 * q + s] & 127u)) << (8 * s); } }
	v_max_i32_e32 v18, v18, v19
	v_max_i32_e32 v19, v20, v22
	v_max_i32_e32 v22, v32, v33
	v_max_i32_e32 v23, v23, v24
	v_min_i32_e32 v28, v43, v27
	v_max_i32_e32 v40, v39, v36
	v_max_i32_e32 v27, v21, v25
	v_max_i32_e32 v20, v18, v19
	v_max_i32_e32 v24, v22, v23
	v_min_i32_e32 v35, v32, v33
	v_max_i32_e32 v42, v40, v27
	v_max_i32_e32 v32, v20, v24
	v_min_i32_e32 v27, v40, v27
	v_min_i32_e32 v20, v20, v24
	v_max_i32_e32 v24, v27, v20
	v_min_i32_e32 v20, v27, v20
	v_min_i32_e32 v27, v39, v36
	v_min_i32_e32 v21, v21, v25
	v_min_i32_e32 v18, v18, v19
	v_min_i32_e32 v19, v22, v23
	v_min_i32_e32 v75, v124, v69
	v_max_i32_e32 v25, v27, v21
	v_max_i32_e32 v22, v18, v19
	v_min_i32_e32 v21, v27, v21
	v_min_i32_e32 v18, v18, v19
	v_min_i32_e32 v44, v34, v28
	v_min_i32_e32 v31, v35, v26
	v_max_i32_e32 v23, v25, v22
	v_min_i32_e32 v22, v25, v22
	v_max_i32_e32 v19, v21, v18
	v_min_i32_e32 v18, v21, v18
	v_max_i32_e32 v21, v75, v49
	v_max_i32_e32 v25, v34, v28
	v_max_i32_e32 v28, v41, v29
	v_max_i32_e32 v26, v35, v26
	v_min_i32_e32 v67, v75, v49
	v_min_i32_e32 v30, v41, v29
	v_max_i32_e32 v27, v21, v25
	v_min_i32_e32 v21, v21, v25
	v_min_i32_e32 v25, v28, v26
	v_min_i32_e32 v45, v67, v44
	v_min_i32_e32 v37, v30, v31
	v_max_i32_e32 v29, v28, v26
	v_max_i32_e32 v26, v21, v25
	v_min_i32_e32 v21, v21, v25
	v_max_i32_e32 v25, v67, v44
	v_max_i32_e32 v28, v30, v31
	v_min_i32_e32 v38, v45, v37
	v_max_i32_e32 v33, v42, v32
	v_min_i32_e32 v32, v42, v32
	v_max_i32_e32 v34, v27, v29
	v_min_i32_e32 v27, v27, v29
	v_max_i32_e32 v29, v25, v28
	v_min_i32_e32 v25, v25, v28
	v_max_i32_e32 v28, v45, v37
	v_sub_u32_e32 v30, v33, v87
	v_sub_u32_e32 v31, v32, v87
	v_sub_u32_e32 v24, v24, v87
	v_sub_u32_e32 v20, v20, v87
	v_sub_u32_e32 v23, v23, v87
	v_sub_u32_e32 v22, v22, v87
	v_sub_u32_e32 v19, v19, v87
	v_sub_u32_e32 v18, v18, v87
	v_sub_u32_e32 v32, v34, v87
	v_sub_u32_e32 v27, v27, v87
	v_sub_u32_e32 v26, v26, v87
	v_sub_u32_e32 v21, v21, v87
	v_sub_u32_e32 v29, v29, v87
	v_sub_u32_e32 v25, v25, v87
	v_sub_u32_e32 v28, v28, v87
	v_sub_u32_e32 v33, v38, v87
	ds_bpermute_b32 v34, v123, v30
	ds_bpermute_b32 v35, v123, v31
	ds_bpermute_b32 v36, v123, v24
	ds_bpermute_b32 v37, v123, v20
	ds_bpermute_b32 v38, v123, v23
	ds_bpermute_b32 v39, v123, v22
	ds_bpermute_b32 v40, v123, v19
	ds_bpermute_b32 v41, v123, v18
	ds_bpermute_b32 v42, v123, v32
	ds_bpermute_b32 v43, v123, v27
	ds_bpermute_b32 v44, v123, v26
	ds_bpermute_b32 v45, v123, v33
	ds_bpermute_b32 v46, v123, v28
	ds_bpermute_b32 v47, v123, v25
	ds_bpermute_b32 v48, v123, v29
	ds_bpermute_b32 v49, v123, v21
	s_waitcnt lgkmcnt(4)
	v_max_i32_e32 v30, v30, v45
	s_waitcnt lgkmcnt(3)
	v_max_i32_e32 v31, v31, v46
	s_waitcnt lgkmcnt(2)
	v_max_i32_e32 v24, v24, v47
	s_waitcnt lgkmcnt(1)
	v_max_i32_e32 v20, v20, v48
	s_waitcnt lgkmcnt(0)
	v_max_i32_e32 v23, v23, v49
	v_max_i32_e32 v22, v22, v44
	v_max_i32_e32 v19, v19, v43
	v_max_i32_e32 v18, v18, v42
	v_max_i32_e32 v32, v32, v41
	v_max_i32_e32 v27, v27, v40
	v_max_i32_e32 v26, v26, v39
	v_max_i32_e32 v21, v21, v38
	v_max_i32_e32 v29, v29, v37
	v_max_i32_e32 v25, v25, v36
	v_max_i32_e32 v28, v28, v35
	v_max_i32_e32 v33, v33, v34
	v_max_i32_e32 v34, v30, v32
	v_min_i32_e32 v30, v30, v32
	v_max_i32_e32 v32, v31, v27
	v_min_i32_e32 v27, v31, v27
	v_max_i32_e32 v31, v24, v26
	v_min_i32_e32 v24, v24, v26
	v_max_i32_e32 v26, v20, v21
	v_min_i32_e32 v20, v20, v21
	v_max_i32_e32 v21, v23, v29
	v_min_i32_e32 v23, v23, v29
	v_max_i32_e32 v29, v22, v25
	v_min_i32_e32 v22, v22, v25
	v_max_i32_e32 v25, v19, v28
	v_min_i32_e32 v19, v19, v28
	v_max_i32_e32 v28, v18, v33
	v_min_i32_e32 v18, v18, v33
	v_max_i32_e32 v33, v34, v21
	v_min_i32_e32 v21, v34, v21
	v_max_i32_e32 v34, v32, v29
	v_min_i32_e32 v29, v32, v29
	v_max_i32_e32 v32, v31, v25
	v_min_i32_e32 v25, v31, v25
	v_max_i32_e32 v31, v26, v28
	v_min_i32_e32 v26, v26, v28
	v_max_i32_e32 v28, v30, v23
	v_min_i32_e32 v23, v30, v23
	v_max_i32_e32 v30, v27, v22
	v_min_i32_e32 v22, v27, v22
	v_max_i32_e32 v27, v24, v19
	v_min_i32_e32 v19, v24, v19
	v_max_i32_e32 v24, v20, v18
	v_min_i32_e32 v18, v20, v18
	v_max_i32_e32 v20, v33, v32
	v_min_i32_e32 v32, v33, v32
	v_max_i32_e32 v33, v34, v31
	v_min_i32_e32 v31, v34, v31
	v_max_i32_e32 v34, v21, v25
	v_min_i32_e32 v21, v21, v25
	v_max_i32_e32 v25, v29, v26
	v_min_i32_e32 v29, v29, v26
	v_max_i32_e32 v35, v28, v27
	v_min_i32_e32 v27, v28, v27
	v_max_i32_e32 v28, v30, v24
	v_min_i32_e32 v24, v30, v24
	v_max_i32_e32 v30, v23, v19
	v_min_i32_e32 v19, v23, v19
	v_max_i32_e32 v23, v22, v18
	v_min_i32_e32 v18, v22, v18
	v_max_i32_e32 v26, v20, v33
	v_min_i32_e32 v33, v20, v33
	v_lshlrev_b32_e32 v20, 8, v65
	v_lshlrev_b32_e32 v22, 16, v64
	v_max_i32_e32 v36, v32, v31
	v_max_i32_e32 v40, v19, v18
	v_min_i32_e32 v41, v19, v18
	v_and_b32_e32 v18, 0x7f, v63
	v_and_b32_e32 v20, 0x7f00, v20
	v_and_b32_e32 v22, 0x7f0000, v22
	v_max_i32_e32 v37, v21, v29
	v_min_i32_e32 v29, v21, v29
	v_lshlrev_b32_e32 v21, 8, v33
	v_or3_b32 v18, v20, v18, v22
	v_lshlrev_b32_e32 v20, 16, v36
	v_and_b32_e32 v19, 0x7f, v26
	v_and_b32_e32 v21, 0x7f00, v21
	v_and_b32_e32 v20, 0x7f0000, v20
	v_or3_b32 v20, v21, v19, v20
	v_lshlrev_b32_e32 v19, 24, v62
	v_min_i32_e32 v31, v32, v31
	v_and_b32_e32 v19, 0x7f000000, v19
	v_bitop3_b32 v19, v18, s68, v19 bitop3:0x36
	v_lshlrev_b32_e32 v18, 24, v31
	v_max_i32_e32 v38, v35, v28
	v_min_i32_e32 v28, v35, v28
	v_max_i32_e32 v35, v27, v24
	v_min_i32_e32 v27, v27, v24
	v_and_b32_e32 v18, 0x7f000000, v18
	v_lshlrev_b32_e32 v22, 8, v60
	v_lshlrev_b32_e32 v24, 16, v59
	v_max_i32_e32 v32, v34, v25
	v_min_i32_e32 v34, v34, v25
	v_bitop3_b32 v18, v20, s68, v18 bitop3:0x36
	v_and_b32_e32 v20, 0x7f, v61
; __device__ __forceinline__ void route_task(int task, int tl0, const bf16* QP  , const LAS bf16* KHL, LAS unsigned short* EL, LAS float* GL, int lane) {
;     ...
;     unsigned P1[4], P2[4];
; #pragma unroll
;     for (int q = 0; q < 4; ++q) { P1[q] = 0u; P2[q] = 0u;
; #pragma unroll
;         for (int s = 0; s < 4; ++s) { P1[q] |= (127u - ((unsigned)top[0][4 * q + s] & 127u)) << (8 * s); P2[q] |= (127u - ((unsigned)top[1][4 * q + s] & 127u)) << (8 * s); } }
;     int bk[16];
;     {
;         int hi2 = hi; asm volatile("" : "+v"(hi2));
;         const bool h1 = hi2 != 0;
;         constexpr int A1[16] = {1, 1, 1, 1, 1, 1, 1, 1, 2, 2, 2, 2, 2, 3, 3, 3}, B1[16] = {0, 1, 2, 3, 4, 5, 6, 7, 0, 1, 2, 3, 4, 0, 1, 2};
; #pragma unroll
;         for (int i = 0; i < 16; ++i) { const float ta = __int_as_float(h1 ? top[0][A1[i]] : top[0][0]), tb = __int_as_float(h1 ? top[1][B1[i]] : top[1][i]); const unsigned code = h1 ? (unsigned)(A1[i] * 16 + B1[i]) : (unsigned)i;
;             bk[i] = (int)((__float_as_uint(ta + tb) | 255u) - code); }
;         sort16_desc(bk);
	v_and_b32_e32 v22, 0x7f00, v22
	v_and_b32_e32 v24, 0x7f0000, v24
	v_max_i32_e32 v39, v30, v23
	v_min_i32_e32 v30, v30, v23
	v_lshlrev_b32_e32 v23, 8, v34
	v_or3_b32 v20, v22, v20, v24
	v_lshlrev_b32_e32 v22, 16, v37
	v_and_b32_e32 v21, 0x7f, v32
	v_and_b32_e32 v23, 0x7f00, v23
	v_and_b32_e32 v22, 0x7f0000, v22
	v_or3_b32 v22, v23, v21, v22
	v_lshlrev_b32_e32 v21, 24, v57
	v_and_b32_e32 v21, 0x7f000000, v21
	v_bitop3_b32 v21, v20, s68, v21 bitop3:0x36
	v_lshlrev_b32_e32 v20, 24, v29
	v_and_b32_e32 v20, 0x7f000000, v20
	v_lshlrev_b32_e32 v24, 8, v58
	v_lshlrev_b32_e32 v42, 16, v56
	v_bitop3_b32 v20, v22, s68, v20 bitop3:0x36
	v_and_b32_e32 v22, 0x7f, v55
	v_and_b32_e32 v24, 0x7f00, v24
	v_and_b32_e32 v42, 0x7f0000, v42
	v_lshlrev_b32_e32 v25, 8, v28
	v_or3_b32 v22, v24, v22, v42
	v_lshlrev_b32_e32 v24, 16, v35
	v_and_b32_e32 v23, 0x7f, v38
	v_and_b32_e32 v25, 0x7f00, v25
	v_and_b32_e32 v24, 0x7f0000, v24
	v_or3_b32 v24, v25, v23, v24
	v_lshlrev_b32_e32 v23, 24, v54
	v_and_b32_e32 v23, 0x7f000000, v23
	v_bitop3_b32 v23, v22, s68, v23 bitop3:0x36
	v_lshlrev_b32_e32 v22, 24, v27
	v_and_b32_e32 v22, 0x7f000000, v22
	v_lshlrev_b32_e32 v42, 8, v52
	v_lshlrev_b32_e32 v44, 16, v51
	v_bitop3_b32 v22, v24, s68, v22 bitop3:0x36
	v_and_b32_e32 v24, 0x7f, v53
	v_and_b32_e32 v42, 0x7f00, v42
	v_and_b32_e32 v44, 0x7f0000, v44
	v_lshlrev_b32_e32 v43, 8, v30
	v_or3_b32 v24, v42, v24, v44
	v_lshlrev_b32_e32 v42, 16, v40
	v_and_b32_e32 v25, 0x7f, v39
	v_and_b32_e32 v43, 0x7f00, v43
	v_and_b32_e32 v42, 0x7f0000, v42
	v_or3_b32 v42, v43, v25, v42
	v_lshlrev_b32_e32 v25, 24, v50
	v_and_b32_e32 v25, 0x7f000000, v25
	v_bitop3_b32 v25, v24, s68, v25 bitop3:0x36
	v_lshlrev_b32_e32 v24, 24, v41
	v_and_b32_e32 v24, 0x7f000000, v24
	v_bitop3_b32 v24, v42, s68, v24 bitop3:0x36
	v_mov_b32_e32 v42, v86
	v_add_f32_e32 v55, v55, v26
	v_cmp_eq_u32_e32 vcc, 0, v42
	v_add_f32_e32 v56, v56, v26
	v_add_f32_e32 v54, v54, v26
	v_cndmask_b32_e32 v42, v65, v63, vcc
	v_add_f32_e32 v44, v42, v26
	v_cndmask_b32_e64 v43, -16, 0, vcc
	v_or_b32_e32 v44, 0xff, v44
	v_add_f32_e32 v45, v42, v33
	v_add_u32_e32 v43, v44, v43
	v_cndmask_b32_e64 v44, v99, -1, vcc
	v_or_b32_e32 v45, 0xff, v45
	v_add_f32_e32 v46, v42, v36
	v_add_u32_e32 v44, v45, v44
	v_cndmask_b32_e64 v45, v100, -2, vcc
	v_or_b32_e32 v46, 0xff, v46
	v_add_f32_e32 v47, v42, v31
	v_add_u32_e32 v45, v46, v45
	v_cndmask_b32_e64 v46, v101, -3, vcc
	v_or_b32_e32 v47, 0xff, v47
	v_add_f32_e32 v48, v42, v32
	v_add_u32_e32 v46, v47, v46
	v_cndmask_b32_e64 v47, v102, -4, vcc
	v_or_b32_e32 v48, 0xff, v48
	v_add_f32_e32 v34, v42, v34
	v_add_f32_e32 v37, v42, v37
	v_add_f32_e32 v29, v42, v29
	v_cndmask_b32_e32 v42, v64, v63, vcc
	v_cndmask_b32_e32 v32, v32, v39, vcc
	v_add_u32_e32 v47, v48, v47
	v_cndmask_b32_e64 v48, v103, -5, vcc
	v_or_b32_e32 v34, 0xff, v34
	v_add_f32_e32 v32, v42, v32
	v_add_u32_e32 v34, v34, v48
	v_cndmask_b32_e64 v48, v104, -6, vcc
	v_or_b32_e32 v37, 0xff, v37
	v_cndmask_b32_e32 v38, v26, v38, vcc
	v_cndmask_b32_e64 v39, v116, -12, vcc
	v_or_b32_e32 v32, 0xff, v32
	v_add_u32_e32 v37, v37, v48
	v_cndmask_b32_e64 v48, v105, -7, vcc
	v_or_b32_e32 v29, 0xff, v29
	v_add_f32_e32 v38, v42, v38
	v_cndmask_b32_e32 v28, v33, v28, vcc
	v_add_u32_e32 v32, v32, v39
	v_cndmask_b32_e32 v39, v62, v63, vcc
	v_cndmask_b32_e32 v30, v26, v30, vcc
	v_add_u32_e32 v29, v29, v48
	v_cndmask_b32_e64 v48, v106, -8, vcc
	v_or_b32_e32 v38, 0xff, v38
	v_add_f32_e32 v28, v42, v28
	v_cndmask_b32_e32 v35, v36, v35, vcc
	v_cndmask_b32_e32 v27, v31, v27, vcc
	v_add_f32_e32 v30, v39, v30
	v_cndmask_b32_e32 v40, v33, v40, vcc
	v_add_u32_e32 v38, v38, v48
	v_cndmask_b32_e64 v48, v107, -9, vcc
	v_or_b32_e32 v28, 0xff, v28
	v_add_f32_e32 v35, v42, v35
	v_add_f32_e32 v27, v42, v27
	v_cndmask_b32_e64 v42, v117, -13, vcc
	v_or_b32_e32 v30, 0xff, v30
	v_add_f32_e32 v40, v39, v40
	v_cndmask_b32_e32 v41, v36, v41, vcc
	v_add_u32_e32 v28, v28, v48
	v_cndmask_b32_e64 v48, v114, -10, vcc
	v_or_b32_e32 v35, 0xff, v35
	v_add_u32_e32 v30, v30, v42
	v_cndmask_b32_e64 v42, v118, -14, vcc
	v_or_b32_e32 v40, 0xff, v40
	v_add_f32_e32 v39, v39, v41
	v_add_u32_e32 v35, v35, v48
	v_cndmask_b32_e64 v48, v115, -11, vcc
	v_or_b32_e32 v27, 0xff, v27
	v_add_u32_e32 v40, v40, v42
	v_cndmask_b32_e64 v42, v119, -15, vcc
	v_or_b32_e32 v39, 0xff, v39
	v_add_u32_e32 v27, v27, v48
	v_add_u32_e32 v39, v39, v42
	v_max_i32_e32 v41, v43, v30
	v_min_i32_e32 v30, v43, v30
	v_max_i32_e32 v42, v44, v32
	v_min_i32_e32 v32, v44, v32
	v_max_i32_e32 v43, v45, v39
	v_min_i32_e32 v39, v45, v39
	v_max_i32_e32 v44, v46, v40
	v_min_i32_e32 v40, v46, v40
	v_max_i32_e32 v45, v47, v38
	v_min_i32_e32 v38, v47, v38
	v_max_i32_e32 v46, v34, v37
	v_min_i32_e32 v34, v34, v37
	v_max_i32_e32 v37, v29, v27
	v_min_i32_e32 v27, v29, v27
	v_max_i32_e32 v29, v28, v35
	v_min_i32_e32 v28, v28, v35
	v_max_i32_e32 v35, v41, v46
	v_min_i32_e32 v41, v41, v46
	v_max_i32_e32 v46, v42, v37
	v_min_i32_e32 v37, v42, v37
	v_max_i32_e32 v42, v43, v29
	v_min_i32_e32 v29, v43, v29
	v_max_i32_e32 v43, v44, v45
	v_min_i32_e32 v44, v44, v45
	v_max_i32_e32 v45, v34, v30
	v_min_i32_e32 v30, v34, v30
	v_max_i32_e32 v34, v38, v40
	v_min_i32_e32 v38, v38, v40
	v_max_i32_e32 v40, v28, v39
	v_min_i32_e32 v28, v28, v39
	v_max_i32_e32 v39, v27, v32
	v_min_i32_e32 v27, v27, v32
	v_max_i32_e32 v32, v35, v46
	v_min_i32_e32 v35, v35, v46
	v_max_i32_e32 v46, v42, v43
	v_min_i32_e32 v42, v42, v43
	v_max_i32_e32 v43, v44, v41
	v_min_i32_e32 v41, v44, v41
	v_max_i32_e32 v44, v45, v34
	v_min_i32_e32 v34, v45, v34
	v_max_i32_e32 v45, v37, v29
	v_min_i32_e32 v29, v37, v29
	v_max_i32_e32 v37, v40, v39
	v_min_i32_e32 v39, v40, v39
	v_max_i32_e32 v40, v27, v30
; #define CAND(a, b) (int)((__float_as_uint(__int_as_float(top[0][a]) + __int_as_float(top[1][b])) | 255u) - (unsigned)((a) * 16 + (b)))
; __device__ __forceinline__ void route_task(int task, int tl0, const bf16* QP  , const LAS bf16* KHL, LAS unsigned short* EL, LAS float* GL, int lane) {
;     ...
;         sort16_desc(bk);
;         int oth[16];
; #pragma unroll
;         for (int i = 0; i < 16; ++i) oth[i] = __shfl_xor(bk[i], 32);
;         merge16_desc(bk, oth);
;     }
;     ...
;     {
;         int gk[16];
;         gk[0] = CAND(3, 3); gk[1] = CAND(4, 0); gk[2] = CAND(4, 1); gk[3] = CAND(4, 2); gk[4] = CAND(5, 0); gk[5] = CAND(5, 1); gk[6] = CAND(6, 0); gk[7] = CAND(6, 1);
;         gk[8] = CAND(7, 0); gk[9] = CAND(7, 1); gk[10] = CAND(8, 0); gk[11] = CAND(9, 0); gk[12] = CAND(10, 0); gk[13] = CAND(11, 0); gk[14] = CAND(12, 0); gk[15] = CAND(13, 0);
	v_min_i32_e32 v27, v27, v30
	v_max_i32_e32 v30, v38, v28
	v_min_i32_e32 v28, v38, v28
	v_max_i32_e32 v38, v32, v46
	v_min_i32_e32 v32, v32, v46
	v_max_i32_e32 v46, v35, v42
	v_min_i32_e32 v35, v35, v42
	v_max_i32_e32 v42, v43, v37
	v_min_i32_e32 v37, v43, v37
	v_max_i32_e32 v43, v41, v39
	v_min_i32_e32 v39, v41, v39
	v_max_i32_e32 v41, v44, v45
	v_min_i32_e32 v44, v44, v45
	v_max_i32_e32 v45, v34, v29
	v_min_i32_e32 v29, v34, v29
	v_max_i32_e32 v34, v40, v30
	v_min_i32_e32 v30, v40, v30
	v_max_i32_e32 v40, v27, v28
	v_min_i32_e32 v27, v27, v28
	v_max_i32_e32 v28, v46, v32
	v_min_i32_e32 v32, v46, v32
	v_max_i32_e32 v46, v35, v34
	v_min_i32_e32 v34, v35, v34
	v_max_i32_e32 v35, v42, v41
	v_min_i32_e32 v41, v42, v41
	v_max_i32_e32 v42, v43, v44
	v_min_i32_e32 v43, v43, v44
	v_max_i32_e32 v44, v45, v37
	v_min_i32_e32 v37, v45, v37
	v_max_i32_e32 v45, v29, v39
	v_min_i32_e32 v29, v29, v39
	v_max_i32_e32 v39, v40, v30
	v_min_i32_e32 v30, v40, v30
	v_max_i32_e32 v40, v28, v35
	v_min_i32_e32 v28, v28, v35
	v_max_i32_e32 v35, v32, v41
	v_min_i32_e32 v32, v32, v41
	v_max_i32_e32 v41, v42, v44
	v_min_i32_e32 v42, v42, v44
	v_max_i32_e32 v44, v43, v37
	v_min_i32_e32 v37, v43, v37
	v_max_i32_e32 v43, v45, v39
	v_min_i32_e32 v39, v45, v39
	v_max_i32_e32 v45, v29, v30
	v_min_i32_e32 v29, v29, v30
	v_max_i32_e32 v30, v35, v28
	v_min_i32_e32 v28, v35, v28
	v_max_i32_e32 v35, v46, v32
	v_min_i32_e32 v32, v46, v32
	v_max_i32_e32 v46, v43, v34
	v_min_i32_e32 v34, v43, v34
	v_max_i32_e32 v43, v45, v39
	v_min_i32_e32 v39, v45, v39
	v_max_i32_e32 v45, v35, v41
	v_min_i32_e32 v35, v35, v41
	v_max_i32_e32 v41, v32, v42
	v_min_i32_e32 v32, v32, v42
	v_max_i32_e32 v42, v44, v46
	v_min_i32_e32 v44, v44, v46
	v_max_i32_e32 v46, v37, v34
	v_min_i32_e32 v34, v37, v34
	v_max_i32_e32 v37, v45, v28
	v_min_i32_e32 v28, v45, v28
	v_max_i32_e32 v45, v35, v41
	v_min_i32_e32 v35, v35, v41
	v_max_i32_e32 v41, v42, v32
	v_min_i32_e32 v32, v42, v32
	v_max_i32_e32 v42, v44, v46
	v_min_i32_e32 v44, v44, v46
	v_max_i32_e32 v46, v43, v34
	v_min_i32_e32 v34, v43, v34
	v_max_i32_e32 v43, v35, v41
	v_min_i32_e32 v35, v35, v41
	v_max_i32_e32 v41, v32, v42
	v_min_i32_e32 v32, v32, v42
	ds_bpermute_b32 v67, v123, v41
	ds_bpermute_b32 v68, v123, v32
	ds_bpermute_b32 v69, v123, v44
	ds_bpermute_b32 v64, v123, v45
	ds_bpermute_b32 v65, v123, v43
	ds_bpermute_b32 v66, v123, v35
	s_waitcnt lgkmcnt(4)
	v_max_i32_e32 v43, v43, v68
	s_waitcnt lgkmcnt(3)
	v_max_i32_e32 v45, v45, v69
	v_max_i32_e32 v35, v35, v67
	v_add_f32_e32 v31, v62, v31
	v_add_f32_e32 v62, v61, v26
	v_add_f32_e32 v67, v61, v33
	v_add_f32_e32 v36, v61, v36
	v_add_f32_e32 v61, v60, v26
	v_add_f32_e32 v60, v60, v33
	v_add_f32_e32 v68, v59, v26
	v_add_f32_e32 v59, v59, v33
	v_add_f32_e32 v69, v57, v26
	v_add_f32_e32 v33, v57, v33
	v_add_f32_e32 v57, v58, v26
	v_add_f32_e32 v53, v53, v26
	v_add_f32_e32 v52, v52, v26
	ds_bpermute_b32 v70, v123, v27
	v_or_b32_e32 v31, 0xff, v31
	v_or_b32_e32 v62, 0xff, v62
	v_or_b32_e32 v67, 0xff, v67
	v_or_b32_e32 v36, 0xff, v36
	v_or_b32_e32 v61, 0xff, v61
	v_or_b32_e32 v60, 0xff, v60
	v_or_b32_e32 v68, 0xff, v68
	v_or_b32_e32 v59, 0xff, v59
	v_or_b32_e32 v69, 0xff, v69
	v_or_b32_e32 v33, 0xff, v33
	v_or_b32_e32 v55, 0xff, v55
	v_or_b32_e32 v57, 0xff, v57
	v_or_b32_e32 v56, 0xff, v56
	v_or_b32_e32 v54, 0xff, v54
	v_or_b32_e32 v53, 0xff, v53
	v_or_b32_e32 v52, 0xff, v52
	v_subrev_u32_e32 v31, 51, v31
	v_subrev_u32_e32 v62, 64, v62
	v_add_u32_e32 v67, 0xffffffbf, v67
	v_add_u32_e32 v36, 0xffffffbe, v36
	v_add_u32_e32 v61, 0xffffffb0, v61
	v_add_u32_e32 v60, 0xffffffaf, v60
	v_add_u32_e32 v68, 0xffffffa0, v68
	v_add_u32_e32 v59, 0xffffff9f, v59
	v_add_u32_e32 v69, 0xffffff90, v69
	v_add_u32_e32 v33, 0xffffff8f, v33
	v_add_u32_e32 v55, 0xffffff80, v55
	v_add_u32_e32 v57, 0xffffff70, v57
	v_add_u32_e32 v56, 0xffffff60, v56
	v_add_u32_e32 v54, 0xffffff50, v54
	v_add_u32_e32 v53, 0xffffff40, v53
	v_add_u32_e32 v52, 0xffffff30, v52
	ds_bpermute_b32 v42, v123, v38
	ds_bpermute_b32 v47, v123, v40
	ds_bpermute_b32 v48, v123, v30
	ds_bpermute_b32 v49, v123, v37
	ds_bpermute_b32 v63, v123, v28
	ds_bpermute_b32 v71, v123, v29
	ds_bpermute_b32 v72, v123, v39
	ds_bpermute_b32 v73, v123, v34
	ds_bpermute_b32 v74, v123, v46
	v_max_i32_e32 v58, v31, v54
	v_min_i32_e32 v31, v31, v54
	v_max_i32_e32 v54, v62, v56
	v_min_i32_e32 v56, v62, v56
	v_max_i32_e32 v62, v67, v52
	v_min_i32_e32 v52, v67, v52
	v_max_i32_e32 v67, v36, v53
	v_min_i32_e32 v36, v36, v53
	v_max_i32_e32 v53, v61, v69
	v_min_i32_e32 v61, v61, v69
	v_max_i32_e32 v69, v60, v68
	v_min_i32_e32 v60, v60, v68
	v_max_i32_e32 v68, v59, v57
	v_min_i32_e32 v57, v59, v57
	v_max_i32_e32 v59, v33, v55
	v_min_i32_e32 v33, v33, v55
	v_max_i32_e32 v55, v58, v69
	v_min_i32_e32 v58, v58, v69
	v_max_i32_e32 v69, v54, v68
	v_min_i32_e32 v54, v54, v68
	v_max_i32_e32 v68, v62, v59
	v_min_i32_e32 v59, v62, v59
	v_max_i32_e32 v62, v67, v53
	v_min_i32_e32 v53, v67, v53
	v_max_i32_e32 v67, v60, v31
	v_min_i32_e32 v31, v60, v31
	v_max_i32_e32 v60, v61, v36
	v_min_i32_e32 v36, v61, v36
	v_max_i32_e32 v61, v33, v52
	v_min_i32_e32 v33, v33, v52
	v_max_i32_e32 v52, v57, v56
	v_min_i32_e32 v56, v57, v56
	v_max_i32_e32 v57, v55, v69
	v_min_i32_e32 v55, v55, v69
	v_max_i32_e32 v69, v68, v62
	v_min_i32_e32 v62, v68, v62
	v_max_i32_e32 v68, v53, v58
	v_min_i32_e32 v53, v53, v58
	v_max_i32_e32 v58, v67, v60
	v_min_i32_e32 v60, v67, v60
	v_max_i32_e32 v67, v54, v59
	v_min_i32_e32 v54, v54, v59
	v_max_i32_e32 v59, v61, v52
	v_min_i32_e32 v52, v61, v52
	v_max_i32_e32 v61, v56, v31
	v_min_i32_e32 v31, v56, v31
	v_max_i32_e32 v56, v36, v33
	v_min_i32_e32 v33, v36, v33
	s_waitcnt lgkmcnt(9)
; #define CAND(a, b) (int)((__float_as_uint(__int_as_float(top[0][a]) + __int_as_float(top[1][b])) | 255u) - (unsigned)((a) * 16 + (b)))
; __device__ __forceinline__ void merge16_desc(int (&a)[16], const int (&b)[16]) {
; #pragma unroll
;     for (int i = 0; i < 16; ++i) a[i] = a[i] > b[15 - i] ? a[i] : b[15 - i];
; #pragma unroll
;     for (int j = 8; j > 0; j >>= 1)
; #pragma unroll
;         for (int i = 0; i < 16; ++i) { const int l = i ^ j; if (l > i) ce_desc(a[i], a[l]); }
; }
; __device__ __forceinline__ void route_task(int task, int tl0, const bf16* QP  , const LAS bf16* KHL, LAS unsigned short* EL, LAS float* GL, int lane) {
;     ...
;         int gk[16];
;         gk[0] = CAND(3, 3); gk[1] = CAND(4, 0); gk[2] = CAND(4, 1); gk[3] = CAND(4, 2); gk[4] = CAND(5, 0); gk[5] = CAND(5, 1); gk[6] = CAND(6, 0); gk[7] = CAND(6, 1);
;         gk[8] = CAND(7, 0); gk[9] = CAND(7, 1); gk[10] = CAND(8, 0); gk[11] = CAND(9, 0); gk[12] = CAND(10, 0); gk[13] = CAND(11, 0); gk[14] = CAND(12, 0); gk[15] = CAND(13, 0);
;         sort16_desc(gk);
;         merge16_desc(bk, gk);
	v_max_i32_e32 v38, v38, v70
	v_min_i32_e32 v36, v57, v69
	v_max_i32_e32 v70, v55, v62
	v_min_i32_e32 v55, v55, v62
	v_max_i32_e32 v62, v68, v59
	v_min_i32_e32 v59, v68, v59
	v_max_i32_e32 v68, v53, v52
	v_min_i32_e32 v52, v53, v52
	v_max_i32_e32 v53, v58, v67
	v_min_i32_e32 v58, v58, v67
	v_max_i32_e32 v67, v60, v54
	v_min_i32_e32 v54, v60, v54
	v_max_i32_e32 v60, v61, v56
	v_min_i32_e32 v56, v61, v56
	v_max_i32_e32 v61, v31, v33
	v_min_i32_e32 v31, v31, v33
	v_max_i32_e32 v33, v70, v36
	v_min_i32_e32 v36, v70, v36
	v_max_i32_e32 v70, v55, v60
	v_min_i32_e32 v55, v55, v60
	v_max_i32_e32 v60, v62, v53
	v_min_i32_e32 v53, v62, v53
	v_max_i32_e32 v62, v68, v58
	v_min_i32_e32 v58, v68, v58
	v_max_i32_e32 v68, v67, v59
	v_min_i32_e32 v59, v67, v59
	v_max_i32_e32 v67, v54, v52
	v_min_i32_e32 v52, v54, v52
	v_max_i32_e32 v54, v61, v56
	s_waitcnt lgkmcnt(3)
	v_max_i32_e32 v40, v40, v71
	s_waitcnt lgkmcnt(2)
	v_max_i32_e32 v30, v30, v72
	s_waitcnt lgkmcnt(1)
	v_max_i32_e32 v37, v37, v73
	s_waitcnt lgkmcnt(0)
	v_max_i32_e32 v28, v28, v74
	v_max_i32_e32 v41, v41, v66
	v_max_i32_e32 v32, v32, v65
	v_max_i32_e32 v44, v44, v64
	v_max_i32_e32 v46, v46, v63
	v_max_i32_e32 v34, v34, v49
	v_max_i32_e32 v39, v39, v48
	v_max_i32_e32 v29, v29, v47
	v_max_i32_e32 v27, v27, v42
	v_min_i32_e32 v56, v61, v56
	v_max_i32_e32 v61, v33, v60
	v_min_i32_e32 v33, v33, v60
	v_max_i32_e32 v60, v36, v53
	v_min_i32_e32 v36, v36, v53
	v_max_i32_e32 v53, v62, v68
	v_min_i32_e32 v62, v62, v68
	v_max_i32_e32 v68, v58, v59
	v_min_i32_e32 v58, v58, v59
	v_max_i32_e32 v59, v67, v54
	v_max_i32_e32 v42, v38, v41
	v_min_i32_e32 v38, v38, v41
	v_max_i32_e32 v41, v40, v32
	v_min_i32_e32 v32, v40, v32
	v_max_i32_e32 v40, v30, v44
	v_min_i32_e32 v30, v30, v44
	v_max_i32_e32 v44, v37, v46
	v_min_i32_e32 v37, v37, v46
	v_max_i32_e32 v46, v28, v34
	v_min_i32_e32 v28, v28, v34
	v_max_i32_e32 v34, v45, v39
	v_min_i32_e32 v39, v45, v39
	v_max_i32_e32 v45, v43, v29
	v_min_i32_e32 v29, v43, v29
	v_max_i32_e32 v43, v35, v27
	v_min_i32_e32 v27, v35, v27
	v_min_i32_e32 v54, v67, v54
	v_max_i32_e32 v67, v52, v56
	v_max_i32_e32 v71, v70, v36
	v_min_i32_e32 v36, v70, v36
	v_max_i32_e32 v70, v59, v55
	v_min_i32_e32 v55, v59, v55
	v_max_i32_e32 v35, v42, v46
	v_min_i32_e32 v42, v42, v46
	v_max_i32_e32 v46, v41, v34
	v_min_i32_e32 v34, v41, v34
	v_max_i32_e32 v41, v40, v45
	v_min_i32_e32 v40, v40, v45
	v_max_i32_e32 v45, v44, v43
	v_min_i32_e32 v43, v44, v43
	v_max_i32_e32 v44, v38, v28
	v_min_i32_e32 v28, v38, v28
	v_max_i32_e32 v38, v32, v39
	v_min_i32_e32 v32, v32, v39
	v_max_i32_e32 v39, v30, v29
	v_min_i32_e32 v29, v30, v29
	v_max_i32_e32 v30, v37, v27
	v_min_i32_e32 v27, v37, v27
	v_min_i32_e32 v52, v52, v56
	v_min_i32_e32 v56, v60, v33
	v_max_i32_e32 v59, v67, v54
	v_min_i32_e32 v54, v67, v54
	v_max_i32_e32 v67, v71, v53
	v_min_i32_e32 v53, v71, v53
	v_max_i32_e32 v71, v36, v62
	v_min_i32_e32 v36, v36, v62
	v_max_i32_e32 v62, v68, v70
	v_min_i32_e32 v68, v68, v70
	v_max_i32_e32 v70, v58, v55
	v_max_i32_e32 v37, v35, v41
	v_min_i32_e32 v35, v35, v41
	v_max_i32_e32 v41, v46, v45
	v_min_i32_e32 v45, v46, v45
	v_max_i32_e32 v46, v42, v40
	v_min_i32_e32 v40, v42, v40
	v_max_i32_e32 v42, v34, v43
	v_min_i32_e32 v34, v34, v43
	v_max_i32_e32 v43, v44, v39
	v_min_i32_e32 v39, v44, v39
	v_max_i32_e32 v44, v38, v30
	v_min_i32_e32 v30, v38, v30
	v_max_i32_e32 v38, v28, v29
	v_min_i32_e32 v28, v28, v29
	v_max_i32_e32 v29, v32, v27
	v_min_i32_e32 v27, v32, v27
	v_min_i32_e32 v55, v58, v55
	v_max_i32_e32 v58, v67, v56
	v_min_i32_e32 v56, v67, v56
	v_max_i32_e32 v67, v53, v71
	v_min_i32_e32 v53, v53, v71
	v_max_i32_e32 v71, v62, v36
	v_min_i32_e32 v36, v62, v36
	v_max_i32_e32 v62, v68, v70
	v_min_i32_e32 v32, v37, v41
	v_min_i32_e32 v47, v35, v45
	v_min_i32_e32 v48, v46, v42
	v_min_i32_e32 v49, v40, v34
	v_min_i32_e32 v63, v43, v44
	v_min_i32_e32 v64, v39, v30
	v_min_i32_e32 v65, v38, v29
	v_min_i32_e32 v66, v28, v27
	v_min_i32_e32 v68, v68, v70
	v_max_i32_e32 v70, v59, v55
	v_min_i32_e32 v55, v59, v55
	v_min_i32_e32 v59, v53, v71
	v_min_i32_e32 v72, v36, v62
	v_max3_i32 v31, v37, v41, v31
	v_max_i32_e32 v32, v32, v52
	v_max3_i32 v35, v35, v45, v54
	v_max_i32_e32 v37, v47, v55
	v_max3_i32 v41, v46, v42, v70
	v_max_i32_e32 v42, v48, v68
	v_max3_i32 v34, v40, v34, v72
	v_max3_i32 v36, v49, v36, v62
	v_max3_i32 v40, v43, v44, v59
	v_max3_i32 v43, v63, v53, v71
	v_max3_i32 v30, v39, v30, v67
	v_max_i32_e32 v39, v64, v56
	v_max3_i32 v29, v38, v29, v58
	v_max3_i32 v33, v65, v60, v33
	v_max3_i32 v27, v28, v27, v61
	v_max3_i32 v28, v66, v57, v69
	v_max_i32_e32 v38, v31, v40
	v_min_i32_e32 v31, v31, v40
	v_max_i32_e32 v40, v32, v43
	v_min_i32_e32 v32, v32, v43
	v_max_i32_e32 v43, v35, v30
	v_min_i32_e32 v30, v35, v30
	v_max_i32_e32 v35, v37, v39
	v_min_i32_e32 v37, v37, v39
	v_max_i32_e32 v39, v41, v29
	v_min_i32_e32 v29, v41, v29
	v_max_i32_e32 v41, v42, v33
	v_min_i32_e32 v33, v42, v33
	v_max_i32_e32 v42, v34, v27
	v_min_i32_e32 v27, v34, v27
	v_max_i32_e32 v34, v36, v28
	v_min_i32_e32 v28, v36, v28
	v_max_i32_e32 v36, v38, v39
	v_min_i32_e32 v38, v38, v39
	v_max_i32_e32 v39, v40, v41
	v_min_i32_e32 v40, v40, v41
	v_max_i32_e32 v41, v43, v42
	v_min_i32_e32 v42, v43, v42
	v_max_i32_e32 v43, v35, v34
	v_min_i32_e32 v34, v35, v34
	v_max_i32_e32 v35, v31, v29
	v_min_i32_e32 v29, v31, v29
	v_max_i32_e32 v31, v32, v33
	v_min_i32_e32 v32, v32, v33
	v_max_i32_e32 v33, v30, v27
	v_min_i32_e32 v27, v30, v27
	v_max_i32_e32 v30, v37, v28
	v_min_i32_e32 v28, v37, v28
	v_max_i32_e32 v37, v36, v41
	v_min_i32_e32 v36, v36, v41
	v_max_i32_e32 v41, v39, v43
	v_min_i32_e32 v39, v39, v43
	v_max_i32_e32 v43, v38, v42
	v_min_i32_e32 v38, v38, v42
; #define CAND(a, b) (int)((__float_as_uint(__int_as_float(top[0][a]) + __int_as_float(top[1][b])) | 255u) - (unsigned)((a) * 16 + (b)))
; __device__ __forceinline__ void route_task(int task, int tl0, const bf16* QP  , const LAS bf16* KHL, LAS unsigned short* EL, LAS float* GL, int lane) {
;     ...
;     {
;         const int c14 = CAND(14, 0), c15 = CAND(15, 0);
;         const int n14 = max(bk[14], c14), n15 = max(min(bk[14], c14), max(bk[15], c15));
;         bk[14] = n14; bk[15] = n15;
;     }
;     ...
;     int my[8];
; #pragma unroll
;     for (int i = 0; i < 8; ++i) { int lo_ = bk[i], hi_ = bk[8 + i]; asm volatile("" : "+v"(lo_), "+v"(hi_)); my[i] = hi ? hi_ : lo_; }
;     int bv[8];
; #pragma unroll
;     for (int i = 0; i < 8; ++i) {
;         const unsigned cd = 255u - ((unsigned)my[i] & 255u), ca = cd >> 4, cb = cd & 15u;
;         const unsigned wa = (ca >> 2) == 0u ? P1[0] : (ca >> 2) == 1u ? P1[1] : (ca >> 2) == 2u ? P1[2] : P1[3];
;         const unsigned wb = (cb >> 2) == 0u ? P2[0] : (cb >> 2) == 1u ? P2[1] : (cb >> 2) == 2u ? P2[2] : P2[3];
;         bv[i] = (int)((((wa >> (8u * (ca & 3u))) & 255u) << 7) | ((wb >> (8u * (cb & 3u))) & 255u));
	v_max_i32_e32 v42, v40, v34
	v_min_i32_e32 v34, v40, v34
	v_max_i32_e32 v40, v35, v33
	v_min_i32_e32 v33, v35, v33
	v_max_i32_e32 v35, v31, v30
	v_min_i32_e32 v30, v31, v30
	v_max_i32_e32 v31, v29, v27
	v_min_i32_e32 v27, v29, v27
	v_max_i32_e32 v29, v32, v28
	v_min_i32_e32 v28, v32, v28
	v_max_i32_e32 v32, v37, v41
	v_min_i32_e32 v37, v37, v41
	v_max_i32_e32 v41, v36, v39
	v_min_i32_e32 v36, v36, v39
	v_max_i32_e32 v39, v43, v42
	v_min_i32_e32 v42, v43, v42
	v_max_i32_e32 v43, v38, v34
	v_min_i32_e32 v34, v38, v34
	v_max_i32_e32 v38, v40, v35
	v_min_i32_e32 v35, v40, v35
	v_max_i32_e32 v40, v33, v30
	v_min_i32_e32 v30, v33, v30
	v_max_i32_e32 v33, v31, v29
	v_min_i32_e32 v29, v31, v29
	v_max_i32_e32 v31, v27, v28
	v_min_i32_e32 v27, v27, v28
	v_add_f32_e32 v28, v51, v26
	v_or_b32_e32 v28, 0xff, v28
	v_add_f32_e32 v26, v50, v26
	v_add_u32_e32 v28, 0xffffff20, v28
	v_or_b32_e32 v26, 0xff, v26
	v_add_u32_e32 v26, 0xffffff10, v26
	v_max_i32_e32 v44, v31, v28
	v_min_i32_e32 v28, v31, v28
	v_max3_i32 v26, v28, v27, v26
	v_mov_b32_e32 v27, v32
	s_nop 0
	v_cndmask_b32_e64 v27, v38, v27, s[6:7]
	v_not_b32_e32 v28, v27
	v_bfe_u32 v45, v28, 6, 2
	v_cmp_eq_u32_e32 vcc, 2, v45
	v_cndmask_b32_e64 v34, v26, v34, s[6:7]
	v_bitop3_b32 v26, v27, s3, v27 bitop3:0xc
	v_cndmask_b32_e32 v46, v25, v23, vcc
	v_cmp_eq_u32_e32 vcc, 1, v45
	v_cndmask_b32_e64 v31, v35, v37, s[6:7]
	v_not_b32_e32 v35, v31
	v_cndmask_b32_e32 v45, v46, v21, vcc
	v_cmp_gt_u32_e32 vcc, 64, v26
	v_cndmask_b32_e64 v37, v40, v41, s[6:7]
	v_cndmask_b32_e64 v41, v44, v43, s[6:7]
	v_cndmask_b32_e32 v26, v45, v19, vcc
	v_bfe_u32 v45, v28, 2, 2
	v_cmp_eq_u32_e32 vcc, 2, v45
	v_bitop3_b32 v44, v27, 15, v27 bitop3:0xc
	v_bfe_u32 v47, v35, 6, 2
	v_cndmask_b32_e32 v46, v24, v22, vcc
	v_cmp_eq_u32_e32 vcc, 1, v45
	v_not_b32_e32 v38, v37
	v_bfe_u32 v49, v38, 6, 2
	v_cndmask_b32_e32 v45, v46, v20, vcc
	v_cmp_gt_u32_e32 vcc, 4, v44
	v_bitop3_b32 v46, v31, 15, v31 bitop3:0xc
	v_cndmask_b32_e64 v30, v30, v36, s[6:7]
	v_cndmask_b32_e32 v44, v45, v18, vcc
	v_cmp_eq_u32_e32 vcc, 2, v47
	v_bitop3_b32 v45, v31, s3, v31 bitop3:0xc
	v_not_b32_e32 v36, v30
	v_cndmask_b32_e32 v48, v25, v23, vcc
	v_cmp_eq_u32_e32 vcc, 1, v47
	v_bfe_u32 v51, v36, 6, 2
	v_cndmask_b32_e64 v33, v33, v39, s[6:7]
	v_cndmask_b32_e32 v47, v48, v21, vcc
	v_cmp_gt_u32_e32 vcc, 64, v45
	v_not_b32_e32 v39, v33
	v_bfe_u32 v53, v39, 6, 2
	v_cndmask_b32_e32 v45, v47, v19, vcc
	v_bfe_u32 v47, v35, 2, 2
	v_cmp_eq_u32_e32 vcc, 2, v47
	v_cndmask_b32_e64 v29, v29, v42, s[6:7]
	v_not_b32_e32 v40, v29
	v_cndmask_b32_e32 v48, v24, v22, vcc
	v_cmp_eq_u32_e32 vcc, 1, v47
	v_bfe_u32 v55, v40, 6, 2
	v_not_b32_e32 v42, v41
	v_cndmask_b32_e32 v47, v48, v20, vcc
	v_cmp_gt_u32_e32 vcc, 4, v46
	v_bitop3_b32 v48, v37, 15, v37 bitop3:0xc
	v_bfe_u32 v57, v42, 6, 2
	v_cndmask_b32_e32 v46, v47, v18, vcc
	v_cmp_eq_u32_e32 vcc, 2, v49
	v_bitop3_b32 v47, v37, s3, v37 bitop3:0xc
	v_not_b32_e32 v43, v34
	v_cndmask_b32_e32 v50, v25, v23, vcc
	v_cmp_eq_u32_e32 vcc, 1, v49
	v_bfe_u32 v59, v43, 6, 2
	v_or_b32_e32 v82, s10, v88
	v_cndmask_b32_e32 v49, v50, v21, vcc
	v_cmp_gt_u32_e32 vcc, 64, v47
	s_nop 1
	v_cndmask_b32_e32 v47, v49, v19, vcc
	v_bfe_u32 v49, v38, 2, 2
	v_cmp_eq_u32_e32 vcc, 2, v49
	s_nop 1
	v_cndmask_b32_e32 v50, v24, v22, vcc
	v_cmp_eq_u32_e32 vcc, 1, v49
	s_nop 1
	v_cndmask_b32_e32 v49, v50, v20, vcc
	v_cmp_gt_u32_e32 vcc, 4, v48
	v_bitop3_b32 v50, v30, 15, v30 bitop3:0xc
	s_nop 0
	v_cndmask_b32_e32 v48, v49, v18, vcc
	v_cmp_eq_u32_e32 vcc, 2, v51
	v_bitop3_b32 v49, v30, s3, v30 bitop3:0xc
	s_nop 0
	v_cndmask_b32_e32 v52, v25, v23, vcc
	v_cmp_eq_u32_e32 vcc, 1, v51
	s_nop 1
	v_cndmask_b32_e32 v51, v52, v21, vcc
	v_cmp_gt_u32_e32 vcc, 64, v49
	s_nop 1
	v_cndmask_b32_e32 v49, v51, v19, vcc
	v_bfe_u32 v51, v36, 2, 2
	v_cmp_eq_u32_e32 vcc, 2, v51
	s_nop 1
	v_cndmask_b32_e32 v52, v24, v22, vcc
	v_cmp_eq_u32_e32 vcc, 1, v51
	s_nop 1
	v_cndmask_b32_e32 v51, v52, v20, vcc
	v_cmp_gt_u32_e32 vcc, 4, v50
	v_bitop3_b32 v52, v33, 15, v33 bitop3:0xc
	s_nop 0
	v_cndmask_b32_e32 v50, v51, v18, vcc
	v_cmp_eq_u32_e32 vcc, 2, v53
	v_bitop3_b32 v51, v33, s3, v33 bitop3:0xc
	s_nop 0
	v_cndmask_b32_e32 v54, v25, v23, vcc
	v_cmp_eq_u32_e32 vcc, 1, v53
	s_nop 1
	v_cndmask_b32_e32 v53, v54, v21, vcc
	v_cmp_gt_u32_e32 vcc, 64, v51
	s_nop 1
	v_cndmask_b32_e32 v51, v53, v19, vcc
	v_bfe_u32 v53, v39, 2, 2
	v_cmp_eq_u32_e32 vcc, 2, v53
	s_nop 1
	v_cndmask_b32_e32 v54, v24, v22, vcc
	v_cmp_eq_u32_e32 vcc, 1, v53
	s_nop 1
	v_cndmask_b32_e32 v53, v54, v20, vcc
	v_cmp_gt_u32_e32 vcc, 4, v52
	v_bitop3_b32 v54, v29, 15, v29 bitop3:0xc
	s_nop 0
	v_cndmask_b32_e32 v52, v53, v18, vcc
	v_cmp_eq_u32_e32 vcc, 2, v55
	v_bitop3_b32 v53, v29, s3, v29 bitop3:0xc
	s_nop 0
	v_cndmask_b32_e32 v56, v25, v23, vcc
	v_cmp_eq_u32_e32 vcc, 1, v55
	s_nop 1
	v_cndmask_b32_e32 v55, v56, v21, vcc
	v_cmp_gt_u32_e32 vcc, 64, v53
	s_nop 1
	v_cndmask_b32_e32 v53, v55, v19, vcc
	v_bfe_u32 v55, v40, 2, 2
	v_cmp_eq_u32_e32 vcc, 2, v55
	s_nop 1
	v_cndmask_b32_e32 v56, v24, v22, vcc
	v_cmp_eq_u32_e32 vcc, 1, v55
	s_nop 1
	v_cndmask_b32_e32 v55, v56, v20, vcc
	v_cmp_gt_u32_e32 vcc, 4, v54
	v_bitop3_b32 v56, v41, 15, v41 bitop3:0xc
	s_nop 0
	v_cndmask_b32_e32 v54, v55, v18, vcc
	v_cmp_eq_u32_e32 vcc, 2, v57
	v_bitop3_b32 v55, v41, s3, v41 bitop3:0xc
	s_nop 0
	v_cndmask_b32_e32 v58, v25, v23, vcc
	v_cmp_eq_u32_e32 vcc, 1, v57
	s_nop 1
	v_cndmask_b32_e32 v57, v58, v21, vcc
	v_cmp_gt_u32_e32 vcc, 64, v55
	s_nop 1
	v_cndmask_b32_e32 v55, v57, v19, vcc
	v_bfe_u32 v57, v42, 2, 2
	v_cmp_eq_u32_e32 vcc, 2, v57
	s_nop 1
	v_cndmask_b32_e32 v58, v24, v22, vcc
	v_cmp_eq_u32_e32 vcc, 1, v57
	s_nop 1
	v_cndmask_b32_e32 v57, v58, v20, vcc
; #define LAS __attribute__((address_space(3)))
; #define MFMA32(a, b, c) __builtin_amdgcn_mfma_f32_32x32x16_bf16((a), (b), (c), 0, 0, 0)
; __device__ __forceinline__ void route_task(int task, int tl0, const bf16* QP  , const LAS bf16* KHL, LAS unsigned short* EL, LAS float* GL, int lane) {
;     ...
;     { unsigned qo = (unsigned)t * (unsigned)D + (unsigned)(head * 128 + 8 * hi); asm volatile("" : "+v"(qo)); const bf16* qp = QP + qo;
; #pragma unroll
;       for (int hf = 0; hf < 2; ++hf)
; #pragma unroll
;         for (int ks = 0; ks < 4; ++ks) qa[hf][ks] = ldg8(qp + 64 * hf + 16 * ks); }
; #pragma unroll
;     for (int half = 0; half < 2; ++half) {
;         int cur[16];
; #pragma unroll
;         for (int kt = 0; kt < 4; ++kt) {
;             f32x16 X;
; #pragma unroll
;             for (int i = 0; i < 16; ++i) X[i] = 8.f;
;             const LAS bf16* khp = KHL + (half * 128 + 32 * kt + r) * 72 + 8 * hi;
; #pragma unroll
;             for (int ks = 0; ks < 4; ++ks) {
;                 const bf16x8 kh = lds8(khp + 16 * ks);
;                 X = MFMA32(kh, qa[half][ks], X);
;     ...
;         const unsigned cd = 255u - ((unsigned)my[i] & 255u), ca = cd >> 4, cb = cd & 15u;
;         const unsigned wa = (ca >> 2) == 0u ? P1[0] : (ca >> 2) == 1u ? P1[1] : (ca >> 2) == 2u ? P1[2] : P1[3];
;         const unsigned wb = (cb >> 2) == 0u ? P2[0] : (cb >> 2) == 1u ? P2[1] : (cb >> 2) == 2u ? P2[2] : P2[3];
;         bv[i] = (int)((((wa >> (8u * (ca & 3u))) & 255u) << 7) | ((wb >> (8u * (cb & 3u))) & 255u));
;     }
;     float e[8], se = 0.f;
; #pragma unroll
;     for (int i = 0; i < 8; ++i) { e[i] = __expf(__int_as_float(my[i]) - __int_as_float(bk[0])); se += e[i]; }
;     se += __shfl_xor(se, 32);
;     const float inv = 1.f / se;
;     {
;         int l2 = lane; asm volatile("" : "+v"(l2));
;         const int o2 = (tl0 + ((l2 & 31) >> 3)) * 128 + (l2 & 7) * 16 + 8 * (l2 >> 5);
;         LAS v4u* ip = (LAS v4u*)(EL + o2); typedef float f4v __attribute__((ext_vector_type(4))); LAS f4v* gp = (LAS f4v*)(GL + o2);
;         ip[0] = (v4u){(unsigned)bv[0] | ((unsigned)bv[1] << 16), (unsigned)bv[2] | ((unsigned)bv[3] << 16), (unsigned)bv[4] | ((unsigned)bv[5] << 16), (unsigned)bv[6] | ((unsigned)bv[7] << 16)};
;         gp[0] = (f4v){e[0] * inv, e[1] * inv, e[2] * inv, e[3] * inv}; gp[1] = (f4v){e[4] * inv, e[5] * inv, e[6] * inv, e[7] * inv};
;     }
	v_cmp_gt_u32_e32 vcc, 4, v56
	v_bitop3_b32 v58, v34, 15, v34 bitop3:0xc
	s_nop 0
	v_cndmask_b32_e32 v56, v57, v18, vcc
	v_cmp_eq_u32_e32 vcc, 2, v59
	v_bitop3_b32 v57, v34, s3, v34 bitop3:0xc
	s_nop 0
	v_cndmask_b32_e32 v23, v25, v23, vcc
	v_cmp_eq_u32_e32 vcc, 1, v59
	v_sub_f32_e32 v25, v30, v32
	v_mul_f32_e32 v25, 0x3fb8aa3b, v25
	v_cndmask_b32_e32 v21, v23, v21, vcc
	v_cmp_gt_u32_e32 vcc, 64, v57
	v_lshrrev_b32_e32 v23, 1, v39
	v_and_b32_e32 v23, 24, v23
	v_cndmask_b32_e32 v19, v21, v19, vcc
	v_bfe_u32 v21, v43, 2, 2
	v_cmp_eq_u32_e32 vcc, 2, v21
	v_lshrrev_b32_e32 v23, v23, v51
	v_lshlrev_b32_e32 v23, 7, v23
	v_cndmask_b32_e32 v22, v24, v22, vcc
	v_cmp_eq_u32_e32 vcc, 1, v21
	v_lshrrev_b32_e32 v21, 1, v42
	v_and_b32_e32 v21, 24, v21
	v_cndmask_b32_e32 v20, v22, v20, vcc
	v_cmp_gt_u32_e32 vcc, 4, v58
	v_lshrrev_b32_e32 v21, v21, v55
	v_lshrrev_b32_e32 v22, 1, v40
	v_cndmask_b32_e32 v18, v20, v18, vcc
	v_lshlrev_b32_e32 v20, 3, v42
	v_lshlrev_b32_e32 v21, 7, v21
	v_and_b32_e32 v22, 24, v22
	v_lshrrev_b32_e32 v20, v20, v56
	v_and_b32_e32 v21, 0x7f80, v21
	v_lshrrev_b32_e32 v22, v22, v53
	v_and_or_b32 v21, v20, s3, v21
	v_lshlrev_b32_e32 v20, 3, v40
	v_lshlrev_b32_e32 v22, 7, v22
	v_lshrrev_b32_e32 v20, v20, v54
	v_and_b32_e32 v22, 0x7f80, v22
	v_and_or_b32 v20, v20, s3, v22
	v_lshlrev_b32_e32 v22, 3, v39
	v_lshrrev_b32_e32 v22, v22, v52
	v_and_b32_e32 v23, 0x7f80, v23
	v_and_or_b32 v39, v22, s3, v23
	v_lshrrev_b32_e32 v23, 1, v36
	v_and_b32_e32 v23, 24, v23
	v_lshrrev_b32_e32 v23, v23, v49
	v_lshlrev_b32_e32 v22, 3, v36
	v_lshlrev_b32_e32 v23, 7, v23
	v_lshrrev_b32_e32 v22, v22, v50
	v_and_b32_e32 v23, 0x7f80, v23
	v_and_or_b32 v36, v22, s3, v23
	v_lshrrev_b32_e32 v23, 1, v38
	v_and_b32_e32 v23, 24, v23
	v_lshrrev_b32_e32 v23, v23, v47
	v_lshlrev_b32_e32 v22, 3, v38
	v_lshlrev_b32_e32 v23, 7, v23
	v_lshrrev_b32_e32 v22, v22, v48
	v_and_b32_e32 v23, 0x7f80, v23
	v_and_or_b32 v38, v22, s3, v23
	v_lshrrev_b32_e32 v23, 1, v35
	v_and_b32_e32 v23, 24, v23
	v_lshrrev_b32_e32 v23, v23, v45
	v_lshlrev_b32_e32 v22, 3, v35
	v_lshlrev_b32_e32 v23, 7, v23
	v_lshrrev_b32_e32 v22, v22, v46
	v_and_b32_e32 v23, 0x7f80, v23
	v_and_or_b32 v35, v22, s3, v23
	v_lshrrev_b32_e32 v23, 1, v28
	v_and_b32_e32 v23, 24, v23
	v_lshrrev_b32_e32 v23, v23, v26
	v_lshlrev_b32_e32 v22, 3, v28
	v_lshlrev_b32_e32 v23, 7, v23
	v_lshrrev_b32_e32 v22, v22, v44
	v_and_b32_e32 v23, 0x7f80, v23
	v_and_or_b32 v40, v22, s3, v23
	v_sub_f32_e32 v22, v27, v32
	v_mul_f32_e32 v22, 0x3fb8aa3b, v22
	v_sub_f32_e32 v23, v31, v32
	v_exp_f32_e32 v22, v22
	v_mul_f32_e32 v23, 0x3fb8aa3b, v23
	v_sub_f32_e32 v24, v37, v32
	v_exp_f32_e32 v23, v23
	v_mul_f32_e32 v24, 0x3fb8aa3b, v24
	v_exp_f32_e32 v24, v24
	v_exp_f32_e32 v25, v25
	v_add_f32_e32 v26, 0, v22
	v_add_f32_e32 v26, v23, v26
	v_add_f32_e32 v26, v24, v26
	v_add_f32_e32 v30, v25, v26
	v_sub_f32_e32 v26, v33, v32
	v_mul_f32_e32 v26, 0x3fb8aa3b, v26
	v_sub_f32_e32 v27, v29, v32
	v_exp_f32_e32 v26, v26
	v_mul_f32_e32 v27, 0x3fb8aa3b, v27
	v_sub_f32_e32 v28, v41, v32
	v_exp_f32_e32 v27, v27
	v_mul_f32_e32 v28, 0x3fb8aa3b, v28
	v_sub_f32_e32 v29, v34, v32
	v_exp_f32_e32 v28, v28
	v_mul_f32_e32 v29, 0x3fb8aa3b, v29
	v_exp_f32_e32 v29, v29
	v_add_f32_e32 v30, v26, v30
	v_add_f32_e32 v30, v27, v30
	v_add_f32_e32 v30, v28, v30
	v_add_f32_e32 v30, v29, v30
	ds_bpermute_b32 v31, v123, v30
	v_lshrrev_b32_e32 v42, 1, v43
	v_and_b32_e32 v32, 24, v42
	v_lshrrev_b32_e32 v19, v32, v19
	v_lshlrev_b32_e32 v19, 7, v19
	s_waitcnt lgkmcnt(0)
	v_add_f32_e32 v30, v30, v31
	v_div_scale_f32 v31, s[12:13], v30, v30, 1.0
	v_rcp_f32_e32 v32, v31
	v_lshlrev_b32_e32 v33, 3, v43
	v_and_b32_e32 v19, 0x7f80, v19
	v_lshrrev_b32_e32 v18, v33, v18
	v_and_or_b32 v33, v18, s3, v19
	v_fma_f32 v18, -v31, v32, 1.0
	v_fmac_f32_e32 v32, v18, v32
	v_div_scale_f32 v18, vcc, 1.0, v30, 1.0
	v_mul_f32_e32 v19, v18, v32
	v_fma_f32 v34, -v31, v19, v18
	v_fmac_f32_e32 v19, v34, v32
	v_fma_f32 v18, -v31, v19, v18
	v_div_fmas_f32 v18, v18, v32, v19
	v_div_fixup_f32 v30, v18, v30, 1.0
	v_mov_b32_e32 v18, v1
	v_lshl_or_b32 v20, v20, 16, v39
	v_lshrrev_b32_e32 v19, 3, v18
	v_and_or_b32 v19, v19, 3, s55
	v_lshlrev_b32_e32 v31, 4, v18
	v_ashrrev_i32_e32 v18, 2, v18
	v_lshlrev_b32_e32 v19, 7, v19
	v_and_b32_e32 v31, 0x70, v31
	v_and_b32_e32 v18, -8, v18
	v_add3_u32 v18, v18, v31, v19
	v_lshl_add_u32 v31, v18, 1, s11
	v_lshl_add_u32 v32, v18, 2, s69
	v_lshl_or_b32 v18, v35, 16, v40
	v_lshl_or_b32 v19, v36, 16, v38
	v_lshl_or_b32 v21, v33, 16, v21
	ds_write_b128 v31, v[18:21]
	v_pk_mul_f32 v[20:21], v[24:25], v[30:31] op_sel_hi:[1,0]
	v_pk_mul_f32 v[18:19], v[22:23], v[30:31] op_sel_hi:[1,0]
	ds_write_b128 v32, v[18:21]
	v_pk_mul_f32 v[20:21], v[28:29], v[30:31] op_sel_hi:[1,0]
	v_pk_mul_f32 v[18:19], v[26:27], v[30:31] op_sel_hi:[1,0]
	ds_write_b128 v32, v[18:21] offset:16
	v_mov_b64_e32 v[32:33], s[30:31]
	v_lshl_add_u64 v[128:129], v[82:83], 1, s[80:81]
	s_waitcnt vmcnt(4)
	v_mov_b32_e32 v78, v150
	v_mov_b32_e32 v79, v151
	v_mov_b32_e32 v80, v152
	v_mov_b32_e32 v81, v153
	v_mov_b32_e32 v74, v154
	v_mov_b32_e32 v75, v155
	v_mov_b32_e32 v76, v156
	v_mov_b32_e32 v77, v157
	v_mov_b32_e32 v70, v158
	v_mov_b32_e32 v71, v159
	v_mov_b32_e32 v72, v160
	v_mov_b32_e32 v73, v161
	v_mov_b32_e32 v66, v162
	v_mov_b32_e32 v67, v163
	v_mov_b32_e32 v68, v164
	v_mov_b32_e32 v69, v165
	ds_read_b128 v[50:53], v94
	ds_read_b128 v[54:57], v94 offset:32
	v_mov_b64_e32 v[30:31], s[28:29]
	v_mov_b64_e32 v[28:29], s[26:27]
	v_mov_b64_e32 v[26:27], s[24:25]
	v_mov_b64_e32 v[24:25], s[22:23]
	v_mov_b64_e32 v[22:23], s[20:21]
	v_mov_b64_e32 v[20:21], s[18:19]
	v_mov_b64_e32 v[18:19], s[16:17]
	s_waitcnt vmcnt(3) lgkmcnt(1)
; #define LAS __attribute__((address_space(3)))
; #define MFMA32(a, b, c) __builtin_amdgcn_mfma_f32_32x32x16_bf16((a), (b), (c), 0, 0, 0)
; #define CE_(a, b) ce_desc(v[a], v[b])
; __device__ __forceinline__ void sort16_desc(int (&v)[16]) {
;     ...
;     CE_(0,13); CE_(1,12); CE_(2,15); CE_(3,14); CE_(4,8); CE_(5,6); CE_(7,11); CE_(9,10);
;     CE_(0,5); CE_(1,7); CE_(2,9); CE_(3,4); CE_(6,13); CE_(8,14); CE_(10,15); CE_(11,12);
;     CE_(0,1); CE_(2,3); CE_(4,5); CE_(6,8); CE_(7,9); CE_(10,11); CE_(12,13); CE_(14,15);
;     CE_(0,2); CE_(1,3); CE_(4,10); CE_(5,11); CE_(6,7); CE_(8,9); CE_(12,14); CE_(13,15);
;     CE_(1,2); CE_(3,12); CE_(4,6); CE_(5,7); CE_(8,10); CE_(9,11); CE_(13,14);
;     CE_(1,4); CE_(2,6); CE_(5,8); CE_(7,10); CE_(9,13); CE_(11,14);
;     CE_(2,4); CE_(3,6); CE_(9,12); CE_(11,13);
;     CE_(3,5); CE_(6,8); CE_(7,9); CE_(10,12);
;     CE_(3,4); CE_(5,6); CE_(7,8); CE_(9,10); CE_(11,12);
;     CE_(6,7); CE_(8,9);
;     ...
; }
; __device__ __forceinline__ void route_task(int task, int tl0, const bf16* QP  , const LAS bf16* KHL, LAS unsigned short* EL, LAS float* GL, int lane) {
;     ...
;         for (int kt = 0; kt < 4; ++kt) {
;             f32x16 X;
; #pragma unroll
;             for (int i = 0; i < 16; ++i) X[i] = 8.f;
;             const LAS bf16* khp = KHL + (half * 128 + 32 * kt + r) * 72 + 8 * hi;
; #pragma unroll
;             for (int ks = 0; ks < 4; ++ks) {
;                 const bf16x8 kh = lds8(khp + 16 * ks);
;                 X = MFMA32(kh, qa[half][ks], X);
;             }
;             int grp[16];
; #pragma unroll
;             for (int i = 0; i < 16; ++i) grp[i] = (int)((__float_as_uint(X[i]) | 127u) - (unsigned)(32 * kt + (i & 3) + 8 * (i >> 2)));
;             sort16_desc(grp);
;             if (kt == 0) {
; #pragma unroll
;                 for (int i = 0; i < 16; ++i) cur[i] = grp[i];
;             } else merge16_desc(cur, grp);
	s_nop 0
	v_mfma_f32_32x32x16_bf16 v[34:49], v[50:53], v[78:81], v[18:33]
	ds_read_b128 v[50:53], v94 offset:64
	ds_read_b128 v[124:127], v94 offset:96
	s_waitcnt vmcnt(2) lgkmcnt(2)
	v_mfma_f32_32x32x16_bf16 v[34:49], v[54:57], v[74:77], v[34:49]
	s_waitcnt vmcnt(1) lgkmcnt(1)
	v_mfma_f32_32x32x16_bf16 v[34:49], v[50:53], v[70:73], v[34:49]
	s_waitcnt vmcnt(0)
	v_mov_b32_e32 v62, v166
	v_mov_b32_e32 v63, v167
	v_mov_b32_e32 v64, v168
	v_mov_b32_e32 v65, v169
	v_mov_b32_e32 v58, v170
	v_mov_b32_e32 v59, v171
	v_mov_b32_e32 v60, v172
	v_mov_b32_e32 v61, v173
	v_mov_b32_e32 v54, v174
	v_mov_b32_e32 v55, v175
	v_mov_b32_e32 v56, v176
	v_mov_b32_e32 v57, v177
	v_mov_b32_e32 v50, v178
	v_mov_b32_e32 v51, v179
	v_mov_b32_e32 v52, v180
	v_mov_b32_e32 v53, v181
	s_waitcnt vmcnt(4) lgkmcnt(0)
	v_mfma_f32_32x32x16_bf16 v[34:49], v[124:127], v[66:69], v[34:49]
	s_nop 11
	v_bitop3_b32 v37, v37, s42, 3 bitop3:0x56
	v_bitop3_b32 v48, v48, s42, 26 bitop3:0x56
	v_bitop3_b32 v38, v38, s42, 8 bitop3:0x56
	v_bitop3_b32 v42, v42, s42, 16 bitop3:0x56
	v_bitop3_b32 v47, v47, s42, 25 bitop3:0x56
	v_bitop3_b32 v39, v39, s42, 9 bitop3:0x56
	v_bitop3_b32 v40, v40, s42, 10 bitop3:0x56
	v_bitop3_b32 v43, v43, s42, 17 bitop3:0x56
	v_bitop3_b32 v44, v44, s42, 18 bitop3:0x56
	v_bitop3_b32 v36, v36, s42, 2 bitop3:0x56
	v_bitop3_b32 v49, v49, s42, 27 bitop3:0x56
	v_bitop3_b32 v41, v41, s42, 11 bitop3:0x56
	v_bitop3_b32 v45, v45, s42, 19 bitop3:0x56
	v_bitop3_b32 v35, v35, s42, 1 bitop3:0x56
	v_bitop3_b32 v46, v46, s42, 24 bitop3:0x56
	v_or_b32_e32 v34, 0x7f, v34
	v_max_i32_e32 v82, v37, v48
	v_max_i32_e32 v124, v38, v42
	v_max_i32_e32 v126, v34, v47
	v_max_i32_e32 v127, v39, v40
	v_min_i32_e32 v130, v43, v44
	v_min_i32_e32 v131, v36, v49
	v_min_i32_e32 v133, v41, v45
	v_min_i32_e32 v134, v35, v46
	v_min_i32_e32 v39, v39, v40
	v_min_i32_e32 v34, v34, v47
	v_min_i32_e32 v38, v38, v42
	v_min_i32_e32 v37, v37, v48
	v_max_i32_e32 v35, v35, v46
	v_max_i32_e32 v41, v41, v45
	v_max_i32_e32 v36, v36, v49
	v_max_i32_e32 v43, v43, v44
	v_min_i32_e32 v125, v82, v124
	v_min_i32_e32 v128, v126, v127
	v_max_i32_e32 v132, v130, v131
	v_max_i32_e32 v135, v133, v134
	v_max_i32_e32 v40, v39, v34
	v_max_i32_e32 v42, v38, v37
	v_min_i32_e32 v45, v35, v41
	v_min_i32_e32 v44, v36, v43
	v_min_i32_e32 v129, v125, v128
	v_max_i32_e32 v47, v40, v42
	v_max_i32_e32 v46, v45, v44
	v_min_i32_e32 v40, v40, v42
	v_min_i32_e32 v42, v45, v44
	v_max_i32_e32 v45, v125, v128
	v_max_i32_e32 v125, v132, v135
	v_min_i32_e32 v128, v45, v125
	v_min_i32_e32 v34, v39, v34
	v_max_i32_e32 v39, v126, v127
	v_max_i32_e32 v35, v35, v41
	v_max_i32_e32 v41, v82, v124
	v_max_i32_e32 v148, v45, v125
	ds_read_b128 v[124:127], v95
	v_max_i32_e32 v44, v40, v42
	v_min_i32_e32 v138, v40, v42
	v_min_i32_e32 v40, v133, v134
	v_min_i32_e32 v37, v38, v37
	v_min_i32_e32 v38, v130, v131
	v_max_i32_e32 v36, v36, v43
	v_min_i32_e32 v136, v132, v135
	v_min_i32_e32 v133, v40, v34
	v_min_i32_e32 v134, v37, v38
	v_max_i32_e32 v34, v40, v34
	v_max_i32_e32 v37, v37, v38
	v_min_i32_e32 v40, v39, v35
	v_min_i32_e32 v42, v36, v41
	v_max_i32_e32 v144, v39, v35
	v_max_i32_e32 v145, v36, v41
	v_max_i32_e32 v137, v129, v136
	v_min_i32_e32 v136, v129, v136
	v_max_i32_e32 v140, v133, v134
	v_min_i32_e32 v141, v34, v37
	v_max_i32_e32 v143, v40, v42
	v_min_i32_e32 v146, v144, v145
	v_max_i32_e32 v149, v47, v46
	v_min_i32_e32 v48, v47, v46
	v_max_i32_e32 v139, v138, v136
	v_max_i32_e32 v142, v140, v141
	v_min_i32_e32 v43, v40, v42
	v_max_i32_e32 v34, v34, v37
	v_min_i32_e32 v147, v143, v146
	v_min_i32_e32 v150, v148, v149
	v_min_i32_e32 v49, v137, v48
	v_min_i32_e32 v132, v44, v128
	v_max_i32_e32 v38, v139, v142
	v_min_i32_e32 v37, v43, v34
	v_max_i32_e32 v34, v43, v34
	v_min_i32_e32 v35, v147, v150
	v_max_i32_e32 v39, v137, v48
	v_max_i32_e32 v40, v44, v128
	v_max_i32_e32 v135, v49, v132
	v_max_i32_e32 v82, v38, v37
	v_min_i32_e32 v36, v34, v35
	v_min_i32_e32 v41, v39, v40
	v_max_i32_e32 v129, v135, v82
	v_min_i32_e32 v42, v36, v41
	v_min_i32_e32 v137, v129, v42
	v_max_i32_e32 v159, v129, v42
	ds_read_b128 v[128:131], v95 offset:32
	v_min_i32_e32 v82, v135, v82
	v_min_i32_e32 v132, v49, v132
	v_min_i32_e32 v135, v38, v37
	v_max_i32_e32 v154, v34, v35
	v_max_i32_e32 v155, v39, v40
	v_max_i32_e32 v157, v36, v41
	s_waitcnt lgkmcnt(1)
	v_mfma_f32_32x32x16_bf16 v[34:49], v[124:127], v[78:81], v[18:33]
	ds_read_b128 v[124:127], v95 offset:64
	v_max_i32_e32 v151, v132, v135
	v_max_i32_e32 v152, v82, v151
	v_min_i32_e32 v136, v138, v136
	v_min_i32_e32 v138, v140, v141
	v_min_i32_e32 v82, v82, v151
	v_max_i32_e32 v147, v147, v150
	s_waitcnt lgkmcnt(1)
	v_mfma_f32_32x32x16_bf16 v[34:49], v[128:131], v[74:77], v[34:49]
	ds_read_b128 v[128:131], v95 offset:96
	v_max_i32_e32 v143, v143, v146
	v_min_i32_e32 v133, v133, v134
	v_min_i32_e32 v156, v154, v155
	v_max_i32_e32 v140, v136, v138
	v_min_i32_e32 v139, v139, v142
	v_max_i32_e32 v142, v154, v155
	s_waitcnt lgkmcnt(1)
	v_mfma_f32_32x32x16_bf16 v[34:49], v[124:127], v[70:73], v[34:49]
	v_max_i32_e32 v124, v148, v149
	v_min_i32_e32 v136, v136, v138
	v_max_i32_e32 v141, v140, v139
	v_min_i32_e32 v139, v140, v139
	v_min_i32_e32 v125, v143, v124
	v_min_i32_e32 v158, v156, v157
	v_min_i32_e32 v132, v132, v135
	s_waitcnt lgkmcnt(0)
; #define LAS __attribute__((address_space(3)))
; #define MFMA32(a, b, c) __builtin_amdgcn_mfma_f32_32x32x16_bf16((a), (b), (c), 0, 0, 0)
; #define CE_(a, b) ce_desc(v[a], v[b])
; __device__ __forceinline__ void sort16_desc(int (&v)[16]) {
;     ...
;     CE_(0,13); CE_(1,12); CE_(2,15); CE_(3,14); CE_(4,8); CE_(5,6); CE_(7,11); CE_(9,10);
;     CE_(0,5); CE_(1,7); CE_(2,9); CE_(3,4); CE_(6,13); CE_(8,14); CE_(10,15); CE_(11,12);
;     CE_(0,1); CE_(2,3); CE_(4,5); CE_(6,8); CE_(7,9); CE_(10,11); CE_(12,13); CE_(14,15);
;     CE_(0,2); CE_(1,3); CE_(4,10); CE_(5,11); CE_(6,7); CE_(8,9); CE_(12,14); CE_(13,15);
;     CE_(1,2); CE_(3,12); CE_(4,6); CE_(5,7); CE_(8,10); CE_(9,11); CE_(13,14);
;     CE_(1,4); CE_(2,6); CE_(5,8); CE_(7,10); CE_(9,13); CE_(11,14);
;     CE_(2,4); CE_(3,6); CE_(9,12); CE_(11,13);
;     CE_(3,5); CE_(6,8); CE_(7,9); CE_(10,12);
;     CE_(3,4); CE_(5,6); CE_(7,8); CE_(9,10); CE_(11,12);
;     CE_(6,7); CE_(8,9);
;     ...
; }
; __device__ __forceinline__ void merge16_desc(int (&a)[16], const int (&b)[16]) {
; #pragma unroll
;     for (int i = 0; i < 16; ++i) a[i] = a[i] > b[15 - i] ? a[i] : b[15 - i];
; #pragma unroll
;     for (int j = 8; j > 0; j >>= 1)
; #pragma unroll
;         for (int i = 0; i < 16; ++i) { const int l = i ^ j; if (l > i) ce_desc(a[i], a[l]); }
; }
; __device__ __forceinline__ void route_task(int task, int tl0, const bf16* QP  , const LAS bf16* KHL, LAS unsigned short* EL, LAS float* GL, int lane) {
;     ...
;         for (int kt = 0; kt < 4; ++kt) {
;             f32x16 X;
; #pragma unroll
;             for (int i = 0; i < 16; ++i) X[i] = 8.f;
;             const LAS bf16* khp = KHL + (half * 128 + 32 * kt + r) * 72 + 8 * hi;
; #pragma unroll
;             for (int ks = 0; ks < 4; ++ks) {
;                 const bf16x8 kh = lds8(khp + 16 * ks);
;                 X = MFMA32(kh, qa[half][ks], X);
;             }
;             int grp[16];
; #pragma unroll
;             for (int i = 0; i < 16; ++i) grp[i] = (int)((__float_as_uint(X[i]) | 127u) - (unsigned)(32 * kt + (i & 3) + 8 * (i >> 2)));
;             sort16_desc(grp);
;             if (kt == 0) {
; #pragma unroll
;                 for (int i = 0; i < 16; ++i) cur[i] = grp[i];
;             } else merge16_desc(cur, grp);
	v_mfma_f32_32x32x16_bf16 v[34:49], v[128:131], v[66:69], v[34:49]
	v_min_i32_e32 v126, v147, v125
	v_min_i32_e32 v153, v137, v152
	v_min_i32_e32 v160, v158, v159
	v_min_i32_e32 v135, v141, v132
	v_min_i32_e32 v127, v142, v126
	s_nop 6
	v_bitop3_b32 v37, v37, s42, 35 bitop3:0x56
	v_bitop3_b32 v48, v48, s42, 58 bitop3:0x56
	v_bitop3_b32 v38, v38, s42, 40 bitop3:0x56
	v_bitop3_b32 v42, v42, s42, 48 bitop3:0x56
	v_bitop3_b32 v34, v34, s42, 32 bitop3:0x56
	v_bitop3_b32 v47, v47, s42, 57 bitop3:0x56
	v_bitop3_b32 v39, v39, s42, 41 bitop3:0x56
	v_bitop3_b32 v40, v40, s42, 42 bitop3:0x56
	v_bitop3_b32 v43, v43, s42, 49 bitop3:0x56
	v_bitop3_b32 v44, v44, s42, 50 bitop3:0x56
	v_bitop3_b32 v36, v36, s42, 34 bitop3:0x56
	v_bitop3_b32 v49, v49, s42, 59 bitop3:0x56
	v_bitop3_b32 v41, v41, s42, 43 bitop3:0x56
	v_bitop3_b32 v45, v45, s42, 51 bitop3:0x56
	v_bitop3_b32 v35, v35, s42, 33 bitop3:0x56
	v_bitop3_b32 v46, v46, s42, 56 bitop3:0x56
	v_max_i32_e32 v128, v37, v48
	v_max_i32_e32 v129, v38, v42
	v_max_i32_e32 v131, v34, v47
	v_max_i32_e32 v134, v39, v40
	v_min_i32_e32 v146, v43, v44
	v_min_i32_e32 v148, v36, v49
	v_min_i32_e32 v150, v41, v45
	v_min_i32_e32 v151, v35, v46
	v_min_i32_e32 v39, v39, v40
	v_min_i32_e32 v34, v34, v47
	v_min_i32_e32 v38, v38, v42
	v_min_i32_e32 v37, v37, v48
	v_max_i32_e32 v35, v35, v46
	v_max_i32_e32 v41, v41, v45
	v_max_i32_e32 v36, v36, v49
	v_max_i32_e32 v43, v43, v44
	v_min_i32_e32 v130, v128, v129
	v_min_i32_e32 v138, v131, v134
	v_max_i32_e32 v149, v146, v148
	v_max_i32_e32 v154, v150, v151
	v_max_i32_e32 v40, v39, v34
	v_max_i32_e32 v42, v38, v37
	v_min_i32_e32 v45, v35, v41
	v_min_i32_e32 v44, v36, v43
	v_min_i32_e32 v150, v150, v151
	v_min_i32_e32 v34, v39, v34
	v_min_i32_e32 v37, v38, v37
	v_min_i32_e32 v38, v146, v148
	v_max_i32_e32 v131, v131, v134
	v_max_i32_e32 v35, v35, v41
	v_max_i32_e32 v36, v36, v43
	v_max_i32_e32 v43, v128, v129
	v_min_i32_e32 v140, v130, v138
	v_min_i32_e32 v155, v149, v154
	v_max_i32_e32 v47, v40, v42
	v_max_i32_e32 v46, v45, v44
	v_min_i32_e32 v40, v40, v42
	v_min_i32_e32 v42, v45, v44
	v_max_i32_e32 v45, v130, v138
	v_max_i32_e32 v130, v149, v154
	v_min_i32_e32 v39, v150, v34
	v_min_i32_e32 v146, v37, v38
	v_max_i32_e32 v34, v150, v34
	v_max_i32_e32 v37, v37, v38
	v_min_i32_e32 v41, v131, v35
	v_min_i32_e32 v128, v36, v43
	v_max_i32_e32 v35, v131, v35
	v_max_i32_e32 v36, v36, v43
	v_min_i32_e32 v48, v47, v46
	v_max_i32_e32 v44, v40, v42
	v_min_i32_e32 v138, v45, v130
	v_min_i32_e32 v40, v40, v42
	v_min_i32_e32 v42, v140, v155
	v_max_i32_e32 v148, v39, v146
	v_min_i32_e32 v38, v34, v37
	v_min_i32_e32 v129, v41, v128
	v_max_i32_e32 v41, v41, v128
	v_min_i32_e32 v43, v35, v36
	v_max_i32_e32 v45, v45, v130
	v_max_i32_e32 v46, v47, v46
	v_max_i32_e32 v161, v140, v155
	v_max_i32_e32 v140, v40, v42
	v_max_i32_e32 v150, v148, v38
	v_max_i32_e32 v34, v34, v37
	v_min_i32_e32 v128, v41, v43
	v_min_i32_e32 v47, v45, v46
	v_min_i32_e32 v49, v161, v48
	v_min_i32_e32 v149, v44, v138
	v_max_i32_e32 v151, v140, v150
	v_min_i32_e32 v37, v129, v34
	v_max_i32_e32 v34, v129, v34
	v_min_i32_e32 v129, v128, v47
	v_max_i32_e32 v48, v161, v48
	v_max_i32_e32 v44, v44, v138
	v_max_i32_e32 v154, v49, v149
	v_max_i32_e32 v134, v151, v37
	v_min_i32_e32 v130, v34, v129
	v_min_i32_e32 v131, v48, v44
	v_min_i32_e32 v49, v49, v149
	v_min_i32_e32 v37, v151, v37
	v_max_i32_e32 v34, v34, v129
	v_max_i32_e32 v44, v48, v44
	v_min_i32_e32 v40, v40, v42
	v_min_i32_e32 v38, v148, v38
	v_max_i32_e32 v41, v41, v43
	v_max_i32_e32 v43, v45, v46
	v_max_i32_e32 v155, v154, v134
	v_min_i32_e32 v138, v130, v131
	v_min_i32_e32 v134, v154, v134
	v_max_i32_e32 v149, v49, v37
	v_min_i32_e32 v48, v34, v44
	v_max_i32_e32 v129, v130, v131
	v_max_i32_e32 v42, v40, v38
	v_min_i32_e32 v140, v140, v150
	v_max_i32_e32 v34, v34, v44
	v_max_i32_e32 v44, v128, v47
	v_min_i32_e32 v45, v41, v43
	v_min_i32_e32 v161, v155, v138
	v_max_i32_e32 v151, v134, v149
	v_min_i32_e32 v130, v48, v129
	v_max_i32_e32 v131, v155, v138
	v_max_i32_e32 v148, v42, v140
	v_min_i32_e32 v37, v49, v37
	v_min_i32_e32 v46, v44, v45
	v_min_i32_e32 v154, v161, v151
	v_min_i32_e32 v138, v130, v131
	v_min_i32_e32 v49, v148, v37
	v_min_i32_e32 v134, v134, v149
	v_min_i32_e32 v47, v34, v46
	v_min_i32_e32 v42, v42, v140
	v_min_i32_e32 v38, v40, v38
	v_min_i32_e32 v39, v39, v146
	v_max3_i32 v39, v144, v145, v39
	v_max3_i32 v38, v143, v124, v38
	v_max3_i32 v40, v147, v125, v42
	v_max3_i32 v42, v142, v126, v49
	v_max3_i32 v37, v127, v148, v37
	v_max3_i32 v49, v156, v157, v134
	v_max3_i32 v124, v158, v159, v154
	v_max3_i32 v125, v160, v161, v151
	v_max3_i32 v126, v137, v152, v138
	v_max3_i32 v127, v153, v130, v131
	v_max3_i32 v48, v82, v48, v129
	v_max3_i32 v47, v141, v132, v47
	v_max3_i32 v34, v135, v34, v46
	v_max3_i32 v44, v139, v44, v45
	v_max3_i32 v41, v136, v41, v43
	v_max3_i32 v35, v133, v35, v36
	v_max_i32_e32 v36, v39, v126
	v_min_i32_e32 v39, v39, v126
	v_max_i32_e32 v43, v38, v127
	v_min_i32_e32 v38, v38, v127
	v_max_i32_e32 v45, v40, v48
	v_min_i32_e32 v40, v40, v48
	v_max_i32_e32 v46, v42, v47
	v_min_i32_e32 v42, v42, v47
	v_max_i32_e32 v47, v37, v34
	v_min_i32_e32 v34, v37, v34
	v_max_i32_e32 v37, v49, v44
	v_min_i32_e32 v44, v49, v44
	v_max_i32_e32 v48, v124, v41
	v_min_i32_e32 v41, v124, v41
	v_max_i32_e32 v49, v125, v35
	v_min_i32_e32 v35, v125, v35
	ds_read_b128 v[124:127], v94 offset:9216
	ds_read_b128 v[128:131], v94 offset:9248
	v_max_i32_e32 v82, v36, v47
	v_min_i32_e32 v132, v36, v47
	v_max_i32_e32 v36, v43, v37
	v_min_i32_e32 v133, v43, v37
	v_max_i32_e32 v37, v45, v48
	v_max_i32_e32 v43, v46, v49
	v_min_i32_e32 v134, v45, v48
	v_min_i32_e32 v135, v46, v49
	v_max_i32_e32 v136, v39, v34
	v_min_i32_e32 v137, v39, v34
	v_max_i32_e32 v138, v38, v44
	v_min_i32_e32 v139, v38, v44
	v_max_i32_e32 v140, v40, v41
	v_min_i32_e32 v141, v40, v41
	v_max_i32_e32 v142, v42, v35
	v_min_i32_e32 v143, v42, v35
	v_max_i32_e32 v144, v82, v37
	v_min_i32_e32 v82, v82, v37
	v_max_i32_e32 v145, v36, v43
	v_min_i32_e32 v146, v36, v43
	s_waitcnt lgkmcnt(1)
; #define LAS __attribute__((address_space(3)))
; #define MFMA32(a, b, c) __builtin_amdgcn_mfma_f32_32x32x16_bf16((a), (b), (c), 0, 0, 0)
; #define CE_(a, b) ce_desc(v[a], v[b])
; __device__ __forceinline__ void sort16_desc(int (&v)[16]) {
;     ...
;     CE_(0,13); CE_(1,12); CE_(2,15); CE_(3,14); CE_(4,8); CE_(5,6); CE_(7,11); CE_(9,10);
;     CE_(0,5); CE_(1,7); CE_(2,9); CE_(3,4); CE_(6,13); CE_(8,14); CE_(10,15); CE_(11,12);
;     CE_(0,1); CE_(2,3); CE_(4,5); CE_(6,8); CE_(7,9); CE_(10,11); CE_(12,13); CE_(14,15);
;     CE_(0,2); CE_(1,3); CE_(4,10); CE_(5,11); CE_(6,7); CE_(8,9); CE_(12,14); CE_(13,15);
;     CE_(1,2); CE_(3,12); CE_(4,6); CE_(5,7); CE_(8,10); CE_(9,11); CE_(13,14);
;     CE_(1,4); CE_(2,6); CE_(5,8); CE_(7,10); CE_(9,13); CE_(11,14);
;     CE_(2,4); CE_(3,6); CE_(9,12); CE_(11,13);
;     CE_(3,5); CE_(6,8); CE_(7,9); CE_(10,12);
;     CE_(3,4); CE_(5,6); CE_(7,8); CE_(9,10); CE_(11,12);
;     CE_(6,7); CE_(8,9);
;     ...
; }
; __device__ __forceinline__ void merge16_desc(int (&a)[16], const int (&b)[16]) {
; #pragma unroll
;     for (int i = 0; i < 16; ++i) a[i] = a[i] > b[15 - i] ? a[i] : b[15 - i];
; #pragma unroll
;     for (int j = 8; j > 0; j >>= 1)
; #pragma unroll
;         for (int i = 0; i < 16; ++i) { const int l = i ^ j; if (l > i) ce_desc(a[i], a[l]); }
; }
; __device__ __forceinline__ void route_task(int task, int tl0, const bf16* QP  , const LAS bf16* KHL, LAS unsigned short* EL, LAS float* GL, int lane) {
;     ...
;         for (int kt = 0; kt < 4; ++kt) {
;             f32x16 X;
; #pragma unroll
;             for (int i = 0; i < 16; ++i) X[i] = 8.f;
;             const LAS bf16* khp = KHL + (half * 128 + 32 * kt + r) * 72 + 8 * hi;
; #pragma unroll
;             for (int ks = 0; ks < 4; ++ks) {
;                 const bf16x8 kh = lds8(khp + 16 * ks);
;                 X = MFMA32(kh, qa[half][ks], X);
;             }
;             int grp[16];
; #pragma unroll
;             for (int i = 0; i < 16; ++i) grp[i] = (int)((__float_as_uint(X[i]) | 127u) - (unsigned)(32 * kt + (i & 3) + 8 * (i >> 2)));
;             sort16_desc(grp);
;             if (kt == 0) {
; #pragma unroll
;                 for (int i = 0; i < 16; ++i) cur[i] = grp[i];
;             } else merge16_desc(cur, grp);
	v_mfma_f32_32x32x16_bf16 v[34:49], v[124:127], v[78:81], v[18:33]
	ds_read_b128 v[124:127], v94 offset:9280
	v_max_i32_e32 v147, v132, v134
	v_min_i32_e32 v132, v132, v134
	v_max_i32_e32 v134, v133, v135
	v_min_i32_e32 v133, v133, v135
	v_max_i32_e32 v135, v136, v140
	v_min_i32_e32 v136, v136, v140
	s_waitcnt lgkmcnt(1)
	v_mfma_f32_32x32x16_bf16 v[34:49], v[128:131], v[74:77], v[34:49]
	ds_read_b128 v[128:131], v94 offset:9312
	v_max_i32_e32 v140, v138, v142
	v_min_i32_e32 v138, v138, v142
	v_max_i32_e32 v142, v137, v141
	v_min_i32_e32 v137, v137, v141
	v_max_i32_e32 v141, v139, v143
	v_min_i32_e32 v139, v139, v143
	s_waitcnt lgkmcnt(1)
	v_mfma_f32_32x32x16_bf16 v[34:49], v[124:127], v[70:73], v[34:49]
	v_min_i32_e32 v143, v144, v145
	v_min_i32_e32 v124, v82, v146
	v_min_i32_e32 v127, v135, v140
	v_min_i32_e32 v125, v147, v134
	v_min_i32_e32 v126, v132, v133
	v_min_i32_e32 v149, v142, v141
	v_min_i32_e32 v148, v136, v138
	s_waitcnt lgkmcnt(0)
	v_mfma_f32_32x32x16_bf16 v[34:49], v[128:131], v[66:69], v[34:49]
	v_min_i32_e32 v150, v137, v139
	s_nop 10
	v_and_or_b32 v37, v37, s43, 60
	v_and_or_b32 v48, v48, s43, 37
	v_and_or_b32 v38, v38, s43, 55
	v_and_or_b32 v42, v42, s43, 47
	v_bitop3_b32 v34, v34, s42, 64 bitop3:0x56
	v_and_or_b32 v47, v47, s43, 38
	v_and_or_b32 v39, v39, s43, 54
	v_and_or_b32 v40, v40, s43, 53
	v_and_or_b32 v43, v43, s43, 46
	v_and_or_b32 v44, v44, s43, 45
	v_and_or_b32 v36, v36, s43, 61
	v_and_or_b32 v49, v49, s43, 36
	v_and_or_b32 v41, v41, s43, 52
	v_and_or_b32 v45, v45, s43, 44
	v_and_or_b32 v35, v35, s43, 62
	v_and_or_b32 v46, v46, s43, 39
	v_max_i32_e32 v128, v37, v48
	v_max_i32_e32 v129, v38, v42
	v_max_i32_e32 v131, v34, v47
	v_max_i32_e32 v151, v39, v40
	v_min_i32_e32 v154, v43, v44
	v_min_i32_e32 v155, v36, v49
	v_min_i32_e32 v157, v41, v45
	v_min_i32_e32 v158, v35, v46
	v_min_i32_e32 v39, v39, v40
	v_min_i32_e32 v34, v34, v47
	v_min_i32_e32 v38, v38, v42
	v_min_i32_e32 v37, v37, v48
	v_max_i32_e32 v35, v35, v46
	v_max_i32_e32 v41, v41, v45
	v_max_i32_e32 v36, v36, v49
	v_max_i32_e32 v43, v43, v44
	v_min_i32_e32 v130, v128, v129
	v_min_i32_e32 v152, v131, v151
	v_max_i32_e32 v156, v154, v155
	v_max_i32_e32 v159, v157, v158
	v_max_i32_e32 v40, v39, v34
	v_max_i32_e32 v42, v38, v37
	v_min_i32_e32 v45, v35, v41
	v_min_i32_e32 v44, v36, v43
	v_min_i32_e32 v157, v157, v158
	v_min_i32_e32 v34, v39, v34
	v_min_i32_e32 v37, v38, v37
	v_min_i32_e32 v38, v154, v155
	v_max_i32_e32 v131, v131, v151
	v_max_i32_e32 v35, v35, v41
	v_max_i32_e32 v36, v36, v43
	v_max_i32_e32 v43, v128, v129
	v_min_i32_e32 v153, v130, v152
	v_min_i32_e32 v160, v156, v159
	v_max_i32_e32 v47, v40, v42
	v_max_i32_e32 v46, v45, v44
	v_min_i32_e32 v40, v40, v42
	v_min_i32_e32 v42, v45, v44
	v_max_i32_e32 v45, v130, v152
	v_max_i32_e32 v130, v156, v159
	v_min_i32_e32 v39, v157, v34
	v_min_i32_e32 v154, v37, v38
	v_max_i32_e32 v34, v157, v34
	v_max_i32_e32 v37, v37, v38
	v_min_i32_e32 v41, v131, v35
	v_min_i32_e32 v128, v36, v43
	v_max_i32_e32 v35, v131, v35
	v_max_i32_e32 v36, v36, v43
	v_min_i32_e32 v48, v47, v46
	v_max_i32_e32 v44, v40, v42
	v_min_i32_e32 v152, v45, v130
	v_min_i32_e32 v40, v40, v42
	v_min_i32_e32 v42, v153, v160
	v_max_i32_e32 v155, v39, v154
	v_min_i32_e32 v38, v34, v37
	v_min_i32_e32 v129, v41, v128
	v_max_i32_e32 v41, v41, v128
	v_min_i32_e32 v43, v35, v36
	v_max_i32_e32 v45, v45, v130
	v_max_i32_e32 v46, v47, v46
	v_max_i32_e32 v161, v153, v160
	v_max_i32_e32 v153, v40, v42
	v_max_i32_e32 v157, v155, v38
	v_max_i32_e32 v34, v34, v37
	v_min_i32_e32 v128, v41, v43
	v_min_i32_e32 v47, v45, v46
	v_min_i32_e32 v49, v161, v48
	v_min_i32_e32 v156, v44, v152
	v_max_i32_e32 v158, v153, v157
	v_min_i32_e32 v37, v129, v34
	v_max_i32_e32 v34, v129, v34
	v_min_i32_e32 v129, v128, v47
	v_max_i32_e32 v48, v161, v48
	v_max_i32_e32 v44, v44, v152
	v_min_i32_e32 v40, v40, v42
	v_min_i32_e32 v38, v155, v38
	v_max_i32_e32 v159, v49, v156
	v_max_i32_e32 v151, v158, v37
	v_min_i32_e32 v130, v34, v129
	v_min_i32_e32 v131, v48, v44
	v_min_i32_e32 v49, v49, v156
	v_min_i32_e32 v37, v158, v37
	v_max_i32_e32 v34, v34, v129
	v_max_i32_e32 v44, v48, v44
	v_max_i32_e32 v42, v40, v38
	v_min_i32_e32 v153, v153, v157
	v_max_i32_e32 v160, v159, v151
	v_min_i32_e32 v152, v130, v131
	v_max_i32_e32 v156, v49, v37
	v_min_i32_e32 v48, v34, v44
	v_max_i32_e32 v129, v130, v131
	v_max_i32_e32 v155, v42, v153
	v_min_i32_e32 v37, v49, v37
	v_min_i32_e32 v151, v159, v151
	v_min_i32_e32 v130, v48, v129
	v_max_i32_e32 v131, v160, v152
	v_min_i32_e32 v49, v155, v37
	v_max_i32_e32 v41, v41, v43
	v_max_i32_e32 v43, v45, v46
	v_min_i32_e32 v42, v42, v153
	v_min_i32_e32 v38, v40, v38
	v_min_i32_e32 v161, v160, v152
	v_max_i32_e32 v158, v151, v156
	v_min_i32_e32 v151, v151, v156
	v_max_i32_e32 v34, v34, v44
	v_max_i32_e32 v44, v128, v47
	v_min_i32_e32 v45, v41, v43
	v_max_i32_e32 v40, v41, v43
	v_max_i32_e32 v38, v143, v38
	v_max3_i32 v41, v82, v146, v42
	v_max_i32_e32 v42, v124, v49
	v_max3_i32 v124, v127, v130, v131
	v_min_i32_e32 v46, v44, v45
	v_max_i32_e32 v43, v125, v151
	v_max3_i32 v49, v126, v161, v158
	v_max3_i32 v44, v149, v44, v45
	v_max_i32_e32 v45, v38, v124
	v_min_i32_e32 v38, v38, v124
	ds_read_b128 v[124:127], v96
	v_min_i32_e32 v159, v161, v158
	v_min_i32_e32 v152, v130, v131
	v_max_i32_e32 v37, v155, v37
	v_max_i32_e32 v48, v48, v129
	v_min_i32_e32 v47, v34, v46
	v_max_i32_e32 v34, v34, v46
	v_min_i32_e32 v39, v39, v154
	v_max3_i32 v39, v144, v145, v39
	v_max3_i32 v37, v147, v134, v37
	v_max3_i32 v46, v132, v133, v159
	v_max3_i32 v82, v135, v140, v152
	v_max3_i32 v48, v136, v138, v48
	v_max_i32_e32 v47, v148, v47
	v_max3_i32 v34, v142, v141, v34
	v_max3_i32 v40, v137, v139, v40
	v_max3_i32 v35, v150, v35, v36
	v_max_i32_e32 v36, v39, v82
	v_min_i32_e32 v39, v39, v82
	v_max_i32_e32 v82, v41, v48
	v_min_i32_e32 v41, v41, v48
	v_max_i32_e32 v48, v42, v47
	v_min_i32_e32 v42, v42, v47
	v_max_i32_e32 v47, v37, v34
	v_min_i32_e32 v34, v37, v34
	v_max_i32_e32 v37, v43, v44
	v_min_i32_e32 v43, v43, v44
	v_max_i32_e32 v44, v46, v40
	v_min_i32_e32 v40, v46, v40
	v_max_i32_e32 v46, v49, v35
	v_min_i32_e32 v35, v49, v35
	v_max_i32_e32 v49, v36, v47
	v_min_i32_e32 v132, v36, v47
	v_max_i32_e32 v36, v45, v37
	v_min_i32_e32 v133, v45, v37
	v_max_i32_e32 v37, v82, v44
	v_min_i32_e32 v82, v82, v44
	v_max_i32_e32 v44, v48, v46
	ds_read_b128 v[128:131], v96 offset:32
	v_min_i32_e32 v134, v48, v46
	v_max_i32_e32 v135, v39, v34
	v_min_i32_e32 v136, v39, v34
	v_max_i32_e32 v137, v38, v43
	v_min_i32_e32 v138, v38, v43
	v_max_i32_e32 v139, v41, v40
	v_min_i32_e32 v140, v41, v40
	v_max_i32_e32 v141, v42, v35
	v_min_i32_e32 v142, v42, v35
	v_max_i32_e32 v143, v49, v37
	v_min_i32_e32 v144, v49, v37
	v_max_i32_e32 v145, v36, v44
	v_min_i32_e32 v146, v36, v44
	s_waitcnt lgkmcnt(1)
; #define LAS __attribute__((address_space(3)))
; #define MFMA32(a, b, c) __builtin_amdgcn_mfma_f32_32x32x16_bf16((a), (b), (c), 0, 0, 0)
; #define CE_(a, b) ce_desc(v[a], v[b])
; __device__ __forceinline__ void sort16_desc(int (&v)[16]) {
;     ...
;     CE_(0,13); CE_(1,12); CE_(2,15); CE_(3,14); CE_(4,8); CE_(5,6); CE_(7,11); CE_(9,10);
;     CE_(0,5); CE_(1,7); CE_(2,9); CE_(3,4); CE_(6,13); CE_(8,14); CE_(10,15); CE_(11,12);
;     CE_(0,1); CE_(2,3); CE_(4,5); CE_(6,8); CE_(7,9); CE_(10,11); CE_(12,13); CE_(14,15);
;     CE_(0,2); CE_(1,3); CE_(4,10); CE_(5,11); CE_(6,7); CE_(8,9); CE_(12,14); CE_(13,15);
;     CE_(1,2); CE_(3,12); CE_(4,6); CE_(5,7); CE_(8,10); CE_(9,11); CE_(13,14);
;     CE_(1,4); CE_(2,6); CE_(5,8); CE_(7,10); CE_(9,13); CE_(11,14);
;     CE_(2,4); CE_(3,6); CE_(9,12); CE_(11,13);
;     CE_(3,5); CE_(6,8); CE_(7,9); CE_(10,12);
;     CE_(3,4); CE_(5,6); CE_(7,8); CE_(9,10); CE_(11,12);
;     CE_(6,7); CE_(8,9);
;     ...
; }
; __device__ __forceinline__ void merge16_desc(int (&a)[16], const int (&b)[16]) {
; #pragma unroll
;     for (int i = 0; i < 16; ++i) a[i] = a[i] > b[15 - i] ? a[i] : b[15 - i];
; #pragma unroll
;     for (int j = 8; j > 0; j >>= 1)
; #pragma unroll
;         for (int i = 0; i < 16; ++i) { const int l = i ^ j; if (l > i) ce_desc(a[i], a[l]); }
; }
; __device__ __forceinline__ void route_task(int task, int tl0, const bf16* QP  , const LAS bf16* KHL, LAS unsigned short* EL, LAS float* GL, int lane) {
;     ...
;         for (int kt = 0; kt < 4; ++kt) {
;             f32x16 X;
; #pragma unroll
;             for (int i = 0; i < 16; ++i) X[i] = 8.f;
;             const LAS bf16* khp = KHL + (half * 128 + 32 * kt + r) * 72 + 8 * hi;
; #pragma unroll
;             for (int ks = 0; ks < 4; ++ks) {
;                 const bf16x8 kh = lds8(khp + 16 * ks);
;                 X = MFMA32(kh, qa[half][ks], X);
;             }
;             int grp[16];
; #pragma unroll
;             for (int i = 0; i < 16; ++i) grp[i] = (int)((__float_as_uint(X[i]) | 127u) - (unsigned)(32 * kt + (i & 3) + 8 * (i >> 2)));
;             sort16_desc(grp);
;             if (kt == 0) {
; #pragma unroll
;                 for (int i = 0; i < 16; ++i) cur[i] = grp[i];
;             } else merge16_desc(cur, grp);
	v_mfma_f32_32x32x16_bf16 v[34:49], v[124:127], v[78:81], v[18:33]
	ds_read_b128 v[78:81], v96 offset:64
	v_max_i32_e32 v147, v132, v82
	v_min_i32_e32 v82, v132, v82
	v_max_i32_e32 v132, v137, v141
	v_max_i32_e32 v124, v133, v134
	v_min_i32_e32 v125, v133, v134
	v_max_i32_e32 v126, v135, v139
	s_waitcnt lgkmcnt(1)
	v_mfma_f32_32x32x16_bf16 v[34:49], v[128:131], v[74:77], v[34:49]
	ds_read_b128 v[74:77], v96 offset:96
	v_min_i32_e32 v128, v137, v141
	v_max_i32_e32 v129, v136, v140
	v_min_i32_e32 v130, v136, v140
	v_min_i32_e32 v127, v135, v139
	v_max_i32_e32 v131, v138, v142
	v_min_i32_e32 v133, v138, v142
	s_waitcnt lgkmcnt(1)
	v_mfma_f32_32x32x16_bf16 v[34:49], v[78:81], v[70:73], v[34:49]
	v_min_i32_e32 v134, v143, v145
	v_min_i32_e32 v70, v144, v146
	v_min_i32_e32 v71, v147, v124
	v_min_i32_e32 v72, v82, v125
	v_min_i32_e32 v73, v126, v132
	v_min_i32_e32 v78, v127, v128
	v_min_i32_e32 v79, v129, v131
	s_waitcnt lgkmcnt(0)
	v_mfma_f32_32x32x16_bf16 v[34:49], v[74:77], v[66:69], v[34:49]
	v_min_i32_e32 v80, v130, v133
	s_nop 10
	v_and_or_b32 v41, v41, s43, 20
	v_and_or_b32 v45, v45, s43, 12
	v_and_or_b32 v35, v35, s43, 30
	v_and_or_b32 v46, v46, s43, 7
	v_and_or_b32 v39, v39, s43, 22
	v_and_or_b32 v40, v40, s43, 21
	v_and_or_b32 v34, v34, s43, 31
	v_and_or_b32 v47, v47, s43, 6
	v_and_or_b32 v38, v38, s43, 23
	v_and_or_b32 v42, v42, s43, 15
	v_and_or_b32 v37, v37, s43, 28
	v_and_or_b32 v48, v48, s43, 5
	v_and_or_b32 v43, v43, s43, 14
	v_and_or_b32 v44, v44, s43, 13
	v_and_or_b32 v36, v36, s43, 29
	v_and_or_b32 v49, v49, s43, 4
	v_min_i32_e32 v66, v41, v45
	v_min_i32_e32 v67, v35, v46
	v_min_i32_e32 v69, v39, v40
	v_min_i32_e32 v74, v34, v47
	v_min_i32_e32 v77, v38, v42
	v_min_i32_e32 v81, v37, v48
	v_min_i32_e32 v136, v43, v44
	v_min_i32_e32 v137, v36, v49
	v_max_i32_e32 v34, v34, v47
	v_max_i32_e32 v39, v39, v40
	v_max_i32_e32 v35, v35, v46
	v_max_i32_e32 v41, v41, v45
	v_max_i32_e32 v36, v36, v49
	v_max_i32_e32 v43, v43, v44
	v_max_i32_e32 v37, v37, v48
	v_max_i32_e32 v38, v38, v42
	v_max_i32_e32 v40, v34, v39
	v_max_i32_e32 v45, v35, v41
	v_max_i32_e32 v44, v36, v43
	v_max_i32_e32 v42, v37, v38
	v_min_i32_e32 v46, v40, v45
	v_min_i32_e32 v47, v44, v42
	v_min_i32_e32 v75, v69, v74
	v_min_i32_e32 v48, v46, v47
	v_max_i32_e32 v46, v46, v47
	v_min_i32_e32 v37, v37, v38
	v_min_i32_e32 v34, v34, v39
	v_max_i32_e32 v39, v136, v137
	v_max_i32_e32 v47, v66, v67
	v_max_i32_e32 v69, v69, v74
	v_max_i32_e32 v74, v77, v81
	v_min_i32_e32 v35, v35, v41
	v_min_i32_e32 v36, v36, v43
	v_min_i32_e32 v68, v66, v67
	v_min_i32_e32 v135, v77, v81
	v_min_i32_e32 v138, v136, v137
	v_max_i32_e32 v38, v37, v34
	v_max_i32_e32 v77, v69, v74
	v_max_i32_e32 v41, v35, v36
	v_min_i32_e32 v34, v37, v34
	v_min_i32_e32 v37, v39, v47
	v_min_i32_e32 v76, v68, v75
	v_min_i32_e32 v139, v135, v138
	v_max_i32_e32 v49, v68, v75
	v_max_i32_e32 v68, v135, v138
	v_max_i32_e32 v40, v40, v45
	v_max_i32_e32 v42, v44, v42
	v_max_i32_e32 v66, v39, v47
	v_max_i32_e32 v43, v77, v41
	v_max_i32_e32 v39, v34, v37
	v_min_i32_e32 v41, v77, v41
	v_min_i32_e32 v69, v69, v74
	v_min_i32_e32 v35, v35, v36
	v_max_i32_e32 v75, v49, v68
	v_min_i32_e32 v44, v40, v42
	v_max_i32_e32 v67, v38, v66
	v_max_i32_e32 v47, v39, v41
	v_max_i32_e32 v36, v69, v35
	v_min_i32_e32 v39, v39, v41
	v_min_i32_e32 v35, v69, v35
	v_min_i32_e32 v34, v34, v37
	v_max_i32_e32 v41, v76, v139
	v_min_i32_e32 v49, v49, v68
	v_min_i32_e32 v45, v46, v44
	v_min_i32_e32 v81, v67, v43
	v_min_i32_e32 v38, v38, v66
	v_max_i32_e32 v37, v35, v34
	v_max_i32_e32 v68, v41, v49
	v_max_i32_e32 v135, v48, v75
	v_min_i32_e32 v136, v45, v81
	v_max_i32_e32 v66, v36, v38
	v_min_i32_e32 v36, v36, v38
	v_max_i32_e32 v69, v37, v68
	v_min_i32_e32 v48, v48, v75
	v_max_i32_e32 v137, v135, v136
	v_max_i32_e32 v74, v47, v66
	v_min_i32_e32 v135, v135, v136
	v_min_i32_e32 v47, v47, v66
	v_max_i32_e32 v38, v39, v36
	v_max_i32_e32 v75, v69, v48
	v_min_i32_e32 v34, v35, v34
	v_min_i32_e32 v35, v41, v49
	v_min_i32_e32 v36, v39, v36
	v_min_i32_e32 v39, v69, v48
	v_max_i32_e32 v44, v46, v44
	v_max_i32_e32 v43, v67, v43
	v_min_i32_e32 v140, v76, v139
	v_min_i32_e32 v77, v137, v74
	v_max_i32_e32 v66, v135, v47
	v_max_i32_e32 v76, v38, v75
	v_min_i32_e32 v47, v135, v47
	v_max_i32_e32 v41, v34, v35
	v_min_i32_e32 v37, v37, v68
	v_min_i32_e32 v48, v36, v39
	v_max_i32_e32 v45, v45, v81
	v_min_i32_e32 v46, v44, v43
	v_min_i32_e32 v38, v38, v75
	v_max_i32_e32 v36, v36, v39
	v_min_i32_e32 v136, v77, v66
	v_max_i32_e32 v135, v76, v47
	v_max_i32_e32 v49, v41, v37
	v_max_i32_e32 v69, v137, v74
	v_min_i32_e32 v67, v45, v46
	v_min_i32_e32 v47, v76, v47
	v_max_i32_e32 v39, v38, v36
	v_min_i32_e32 v138, v136, v135
	v_max_i32_e32 v68, v49, v48
	v_max_i32_e32 v74, v69, v67
	v_min_i32_e32 v37, v41, v37
	v_max_i32_e32 v41, v77, v66
	v_min_i32_e32 v75, v47, v39
	v_max_i32_e32 v43, v44, v43
	v_min_i32_e32 v34, v34, v35
	v_min_i32_e32 v36, v38, v36
	v_min_i32_e32 v48, v49, v48
	v_min_i32_e32 v49, v69, v67
	v_max3_i32 v140, v143, v145, v140
	v_max3_i32 v126, v126, v132, v138
	v_max3_i32 v68, v147, v124, v68
	v_max3_i32 v74, v129, v131, v74
	v_max3_i32 v37, v144, v146, v37
	v_max3_i32 v41, v127, v128, v41
	v_max3_i32 v75, v82, v125, v75
	v_max3_i32 v43, v130, v133, v43
	v_max_i32_e32 v34, v134, v34
	v_max3_i32 v35, v73, v136, v135
	v_max_i32_e32 v36, v71, v36
	v_max3_i32 v38, v79, v45, v46
	v_max_i32_e32 v48, v70, v48
	v_max_i32_e32 v49, v78, v49
	v_max3_i32 v39, v72, v47, v39
	v_max3_i32 v40, v80, v40, v42
	v_min_i32_e32 v81, v68, v74
	v_min_i32_e32 v66, v37, v41
	v_min_i32_e32 v73, v34, v35
	v_min_i32_e32 v45, v36, v38
	v_min_i32_e32 v42, v39, v40
	v_max_i32_e32 v71, v140, v126
; __device__ __forceinline__ void merge16_desc(int (&a)[16], const int (&b)[16]) {
; #pragma unroll
;     for (int i = 0; i < 16; ++i) a[i] = a[i] > b[15 - i] ? a[i] : b[15 - i];
; #pragma unroll
;     for (int j = 8; j > 0; j >>= 1)
; #pragma unroll
;         for (int i = 0; i < 16; ++i) { const int l = i ^ j; if (l > i) ce_desc(a[i], a[l]); }
; }
; __device__ __forceinline__ void route_task(int task, int tl0, const bf16* QP  , const LAS bf16* KHL, LAS unsigned short* EL, LAS float* GL, int lane) {
;     ...
;         { const unsigned h4 = 4u * (unsigned)hi;
; #pragma unroll
;           for (int i = 0; i < 16; ++i) cur[i] -= (int)h4; }
;         int oth[16];
; #pragma unroll
;         for (int i = 0; i < 16; ++i) oth[i] = __shfl_xor(cur[i], 32);
;         merge16_desc(cur, oth);
; #pragma unroll
;         for (int i = 0; i < 16; ++i) top[half][i] = cur[i];
	v_max_i32_e32 v68, v68, v74
	v_max_i32_e32 v37, v37, v41
	v_max_i32_e32 v41, v75, v43
	v_max_i32_e32 v34, v34, v35
	v_max_i32_e32 v35, v36, v38
	v_max_i32_e32 v38, v48, v49
	v_max_i32_e32 v39, v39, v40
	v_min_i32_e32 v44, v75, v43
	v_max_i32_e32 v72, v71, v68
	v_max_i32_e32 v43, v37, v41
	v_max_i32_e32 v36, v34, v35
	v_max_i32_e32 v40, v38, v39
	v_min_i32_e32 v67, v48, v49
	v_max_i32_e32 v74, v72, v43
	v_max_i32_e32 v48, v36, v40
	v_min_i32_e32 v43, v72, v43
	v_min_i32_e32 v36, v36, v40
	v_max_i32_e32 v40, v43, v36
	v_min_i32_e32 v36, v43, v36
	v_min_i32_e32 v43, v71, v68
	v_min_i32_e32 v37, v37, v41
	v_min_i32_e32 v34, v34, v35
	v_min_i32_e32 v35, v38, v39
	v_min_i32_e32 v132, v140, v126
	v_max_i32_e32 v41, v43, v37
	v_max_i32_e32 v38, v34, v35
	v_min_i32_e32 v37, v43, v37
	v_min_i32_e32 v34, v34, v35
	v_min_i32_e32 v76, v66, v44
	v_min_i32_e32 v47, v67, v42
	v_max_i32_e32 v39, v41, v38
	v_min_i32_e32 v38, v41, v38
	v_max_i32_e32 v35, v37, v34
	v_min_i32_e32 v34, v37, v34
	v_max_i32_e32 v37, v132, v81
	v_max_i32_e32 v41, v66, v44
	v_max_i32_e32 v44, v73, v45
	v_max_i32_e32 v42, v67, v42
	v_min_i32_e32 v124, v132, v81
	v_min_i32_e32 v46, v73, v45
	v_max_i32_e32 v43, v37, v41
	v_min_i32_e32 v37, v37, v41
	v_min_i32_e32 v41, v44, v42
	v_min_i32_e32 v77, v124, v76
	v_min_i32_e32 v69, v46, v47
	v_max_i32_e32 v45, v44, v42
	v_max_i32_e32 v42, v37, v41
	v_min_i32_e32 v37, v37, v41
	v_max_i32_e32 v41, v124, v76
	v_max_i32_e32 v44, v46, v47
	v_min_i32_e32 v70, v77, v69
	v_max_i32_e32 v49, v74, v48
	v_min_i32_e32 v48, v74, v48
	v_max_i32_e32 v66, v43, v45
	v_min_i32_e32 v43, v43, v45
	v_max_i32_e32 v45, v41, v44
	v_min_i32_e32 v41, v41, v44
	v_max_i32_e32 v44, v77, v69
	v_sub_u32_e32 v46, v49, v87
	v_sub_u32_e32 v47, v48, v87
	v_sub_u32_e32 v40, v40, v87
	v_sub_u32_e32 v36, v36, v87
	v_sub_u32_e32 v39, v39, v87
	v_sub_u32_e32 v38, v38, v87
	v_sub_u32_e32 v35, v35, v87
	v_sub_u32_e32 v34, v34, v87
	v_sub_u32_e32 v48, v66, v87
	v_sub_u32_e32 v43, v43, v87
	v_sub_u32_e32 v42, v42, v87
	v_sub_u32_e32 v37, v37, v87
	v_sub_u32_e32 v45, v45, v87
	v_sub_u32_e32 v41, v41, v87
	v_sub_u32_e32 v44, v44, v87
	v_sub_u32_e32 v49, v70, v87
	ds_bpermute_b32 v66, v123, v46
	ds_bpermute_b32 v67, v123, v47
	ds_bpermute_b32 v68, v123, v40
	ds_bpermute_b32 v69, v123, v36
	ds_bpermute_b32 v70, v123, v39
	ds_bpermute_b32 v71, v123, v38
	ds_bpermute_b32 v72, v123, v35
	ds_bpermute_b32 v73, v123, v34
	ds_bpermute_b32 v74, v123, v48
	ds_bpermute_b32 v75, v123, v43
	ds_bpermute_b32 v76, v123, v42
	ds_bpermute_b32 v77, v123, v49
	ds_bpermute_b32 v78, v123, v44
	ds_bpermute_b32 v79, v123, v41
	ds_bpermute_b32 v80, v123, v45
	ds_bpermute_b32 v81, v123, v37
	s_waitcnt lgkmcnt(4)
	v_max_i32_e32 v46, v46, v77
	s_waitcnt lgkmcnt(3)
	v_max_i32_e32 v47, v47, v78
	s_waitcnt lgkmcnt(2)
	v_max_i32_e32 v40, v40, v79
	s_waitcnt lgkmcnt(1)
	v_max_i32_e32 v36, v36, v80
	s_waitcnt lgkmcnt(0)
	v_max_i32_e32 v39, v39, v81
	v_max_i32_e32 v38, v38, v76
	v_max_i32_e32 v35, v35, v75
	v_max_i32_e32 v34, v34, v74
	v_max_i32_e32 v48, v48, v73
	v_max_i32_e32 v43, v43, v72
	v_max_i32_e32 v42, v42, v71
	v_max_i32_e32 v37, v37, v70
	v_max_i32_e32 v45, v45, v69
	v_max_i32_e32 v41, v41, v68
	v_max_i32_e32 v44, v44, v67
	v_max_i32_e32 v49, v49, v66
	v_max_i32_e32 v66, v46, v48
	v_min_i32_e32 v46, v46, v48
	v_max_i32_e32 v48, v47, v43
	v_min_i32_e32 v43, v47, v43
	v_max_i32_e32 v47, v40, v42
	v_min_i32_e32 v40, v40, v42
	v_max_i32_e32 v42, v36, v37
	v_min_i32_e32 v36, v36, v37
	v_max_i32_e32 v37, v39, v45
	v_min_i32_e32 v39, v39, v45
	v_max_i32_e32 v45, v38, v41
	v_min_i32_e32 v38, v38, v41
	v_max_i32_e32 v41, v35, v44
	v_min_i32_e32 v35, v35, v44
	v_max_i32_e32 v44, v34, v49
	v_min_i32_e32 v34, v34, v49
	v_max_i32_e32 v49, v66, v37
	v_min_i32_e32 v37, v66, v37
	v_max_i32_e32 v66, v48, v45
	v_min_i32_e32 v45, v48, v45
	v_max_i32_e32 v48, v47, v41
	v_min_i32_e32 v41, v47, v41
	v_max_i32_e32 v47, v42, v44
	v_max_i32_e32 v80, v66, v47
	v_min_i32_e32 v124, v66, v47
	ds_read_b128 v[66:69], v94 offset:18432
	ds_read_b128 v[70:73], v94 offset:18464
	v_min_i32_e32 v42, v42, v44
	v_max_i32_e32 v44, v46, v39
	v_min_i32_e32 v74, v46, v39
	v_max_i32_e32 v39, v43, v38
	v_min_i32_e32 v75, v43, v38
	v_max_i32_e32 v38, v40, v35
	v_min_i32_e32 v76, v40, v35
	v_max_i32_e32 v35, v36, v34
	v_min_i32_e32 v77, v36, v34
	v_max_i32_e32 v78, v49, v48
	v_min_i32_e32 v82, v49, v48
	v_max_i32_e32 v125, v37, v41
	v_min_i32_e32 v126, v37, v41
	v_max_i32_e32 v127, v45, v42
	v_min_i32_e32 v128, v45, v42
	v_max_i32_e32 v129, v44, v38
	v_min_i32_e32 v130, v44, v38
	v_max_i32_e32 v131, v39, v35
	v_min_i32_e32 v132, v39, v35
	s_waitcnt vmcnt(3) lgkmcnt(1)
	v_mfma_f32_32x32x16_bf16 v[34:49], v[66:69], v[62:65], v[18:33]
	ds_read_b128 v[66:69], v94 offset:18496
	v_max_i32_e32 v133, v74, v76
	v_min_i32_e32 v134, v74, v76
	v_max_i32_e32 v135, v75, v77
	v_min_i32_e32 v136, v75, v77
	v_max_i32_e32 v79, v78, v80
	v_min_i32_e32 v81, v78, v80
	s_waitcnt vmcnt(2) lgkmcnt(1)
	v_mfma_f32_32x32x16_bf16 v[34:49], v[70:73], v[58:61], v[34:49]
	v_max_i32_e32 v80, v82, v124
	v_min_i32_e32 v78, v82, v124
	v_max_i32_e32 v77, v125, v127
	v_min_i32_e32 v76, v125, v127
	v_max_i32_e32 v75, v126, v128
	v_min_i32_e32 v73, v126, v128
	ds_read_b128 v[124:127], v94 offset:18528
	s_waitcnt vmcnt(1) lgkmcnt(1)
	v_mfma_f32_32x32x16_bf16 v[34:49], v[66:69], v[54:57], v[34:49]
	v_max_i32_e32 v71, v129, v131
	v_min_i32_e32 v74, v129, v131
	v_max_i32_e32 v72, v130, v132
	v_min_i32_e32 v70, v130, v132
	v_max_i32_e32 v69, v133, v135
	v_min_i32_e32 v68, v133, v135
	v_max_i32_e32 v67, v134, v136
	s_waitcnt vmcnt(0) lgkmcnt(0)
; #define LAS __attribute__((address_space(3)))
; #define MFMA32(a, b, c) __builtin_amdgcn_mfma_f32_32x32x16_bf16((a), (b), (c), 0, 0, 0)
; #define CE_(a, b) ce_desc(v[a], v[b])
; __device__ __forceinline__ void sort16_desc(int (&v)[16]) {
;     ...
;     CE_(0,13); CE_(1,12); CE_(2,15); CE_(3,14); CE_(4,8); CE_(5,6); CE_(7,11); CE_(9,10);
;     CE_(0,5); CE_(1,7); CE_(2,9); CE_(3,4); CE_(6,13); CE_(8,14); CE_(10,15); CE_(11,12);
;     CE_(0,1); CE_(2,3); CE_(4,5); CE_(6,8); CE_(7,9); CE_(10,11); CE_(12,13); CE_(14,15);
;     CE_(0,2); CE_(1,3); CE_(4,10); CE_(5,11); CE_(6,7); CE_(8,9); CE_(12,14); CE_(13,15);
;     CE_(1,2); CE_(3,12); CE_(4,6); CE_(5,7); CE_(8,10); CE_(9,11); CE_(13,14);
;     CE_(1,4); CE_(2,6); CE_(5,8); CE_(7,10); CE_(9,13); CE_(11,14);
;     CE_(2,4); CE_(3,6); CE_(9,12); CE_(11,13);
;     CE_(3,5); CE_(6,8); CE_(7,9); CE_(10,12);
;     CE_(3,4); CE_(5,6); CE_(7,8); CE_(9,10); CE_(11,12);
;     CE_(6,7); CE_(8,9);
;     ...
; }
; __device__ __forceinline__ void route_task(int task, int tl0, const bf16* QP  , const LAS bf16* KHL, LAS unsigned short* EL, LAS float* GL, int lane) {
;     ...
;         for (int kt = 0; kt < 4; ++kt) {
;             f32x16 X;
; #pragma unroll
;             for (int i = 0; i < 16; ++i) X[i] = 8.f;
;             const LAS bf16* khp = KHL + (half * 128 + 32 * kt + r) * 72 + 8 * hi;
; #pragma unroll
;             for (int ks = 0; ks < 4; ++ks) {
;                 const bf16x8 kh = lds8(khp + 16 * ks);
;                 X = MFMA32(kh, qa[half][ks], X);
;             }
;             int grp[16];
; #pragma unroll
;             for (int i = 0; i < 16; ++i) grp[i] = (int)((__float_as_uint(X[i]) | 127u) - (unsigned)(32 * kt + (i & 3) + 8 * (i >> 2)));
;             sort16_desc(grp);
	v_mfma_f32_32x32x16_bf16 v[34:49], v[124:127], v[50:53], v[34:49]
	v_min_i32_e32 v66, v134, v136
	s_nop 10
	v_bitop3_b32 v37, v37, s42, 3 bitop3:0x56
	v_bitop3_b32 v48, v48, s42, 26 bitop3:0x56
	v_bitop3_b32 v38, v38, s42, 8 bitop3:0x56
	v_bitop3_b32 v42, v42, s42, 16 bitop3:0x56
	v_bitop3_b32 v47, v47, s42, 25 bitop3:0x56
	v_bitop3_b32 v39, v39, s42, 9 bitop3:0x56
	v_bitop3_b32 v40, v40, s42, 10 bitop3:0x56
	v_bitop3_b32 v43, v43, s42, 17 bitop3:0x56
	v_bitop3_b32 v44, v44, s42, 18 bitop3:0x56
	v_bitop3_b32 v36, v36, s42, 2 bitop3:0x56
	v_bitop3_b32 v49, v49, s42, 27 bitop3:0x56
	v_bitop3_b32 v41, v41, s42, 11 bitop3:0x56
	v_bitop3_b32 v45, v45, s42, 19 bitop3:0x56
	v_bitop3_b32 v35, v35, s42, 1 bitop3:0x56
	v_bitop3_b32 v46, v46, s42, 24 bitop3:0x56
	v_or_b32_e32 v34, 0x7f, v34
	v_max_i32_e32 v82, v37, v48
	v_max_i32_e32 v124, v38, v42
	v_max_i32_e32 v126, v34, v47
	v_max_i32_e32 v127, v39, v40
	v_min_i32_e32 v130, v43, v44
	v_min_i32_e32 v131, v36, v49
	v_min_i32_e32 v133, v41, v45
	v_min_i32_e32 v134, v35, v46
	v_min_i32_e32 v39, v39, v40
	v_min_i32_e32 v34, v34, v47
	v_min_i32_e32 v38, v38, v42
	v_min_i32_e32 v37, v37, v48
	v_max_i32_e32 v35, v35, v46
	v_max_i32_e32 v41, v41, v45
	v_max_i32_e32 v36, v36, v49
	v_max_i32_e32 v43, v43, v44
	v_min_i32_e32 v125, v82, v124
	v_min_i32_e32 v128, v126, v127
	v_max_i32_e32 v132, v130, v131
	v_max_i32_e32 v135, v133, v134
	v_max_i32_e32 v40, v39, v34
	v_max_i32_e32 v42, v38, v37
	v_min_i32_e32 v45, v35, v41
	v_min_i32_e32 v44, v36, v43
	v_min_i32_e32 v129, v125, v128
	v_max_i32_e32 v47, v40, v42
	v_max_i32_e32 v46, v45, v44
	v_min_i32_e32 v40, v40, v42
	v_min_i32_e32 v42, v45, v44
	v_max_i32_e32 v45, v125, v128
	v_max_i32_e32 v125, v132, v135
	v_min_i32_e32 v128, v45, v125
	v_min_i32_e32 v34, v39, v34
	v_max_i32_e32 v39, v126, v127
	v_max_i32_e32 v35, v35, v41
	v_max_i32_e32 v41, v82, v124
	v_max_i32_e32 v148, v45, v125
	ds_read_b128 v[124:127], v97
	v_max_i32_e32 v44, v40, v42
	v_min_i32_e32 v138, v40, v42
	v_min_i32_e32 v40, v133, v134
	v_min_i32_e32 v37, v38, v37
	v_min_i32_e32 v38, v130, v131
	v_max_i32_e32 v36, v36, v43
	v_min_i32_e32 v136, v132, v135
	v_min_i32_e32 v133, v40, v34
	v_min_i32_e32 v134, v37, v38
	v_max_i32_e32 v34, v40, v34
	v_max_i32_e32 v37, v37, v38
	v_min_i32_e32 v40, v39, v35
	v_min_i32_e32 v42, v36, v41
	v_max_i32_e32 v144, v39, v35
	v_max_i32_e32 v145, v36, v41
	v_max_i32_e32 v137, v129, v136
	v_min_i32_e32 v136, v129, v136
	v_max_i32_e32 v140, v133, v134
	v_min_i32_e32 v141, v34, v37
	v_max_i32_e32 v143, v40, v42
	v_min_i32_e32 v146, v144, v145
	v_max_i32_e32 v149, v47, v46
	v_min_i32_e32 v48, v47, v46
	v_max_i32_e32 v139, v138, v136
	v_max_i32_e32 v142, v140, v141
	v_min_i32_e32 v43, v40, v42
	v_max_i32_e32 v34, v34, v37
	v_min_i32_e32 v147, v143, v146
	v_min_i32_e32 v150, v148, v149
	v_min_i32_e32 v49, v137, v48
	v_min_i32_e32 v132, v44, v128
	v_max_i32_e32 v38, v139, v142
	v_min_i32_e32 v37, v43, v34
	v_max_i32_e32 v34, v43, v34
	v_min_i32_e32 v35, v147, v150
	v_max_i32_e32 v39, v137, v48
	v_max_i32_e32 v40, v44, v128
	v_max_i32_e32 v135, v49, v132
	v_max_i32_e32 v82, v38, v37
	v_min_i32_e32 v36, v34, v35
	v_min_i32_e32 v41, v39, v40
	v_max_i32_e32 v129, v135, v82
	v_min_i32_e32 v42, v36, v41
	v_min_i32_e32 v137, v129, v42
	v_max_i32_e32 v159, v129, v42
	ds_read_b128 v[128:131], v97 offset:32
	v_min_i32_e32 v82, v135, v82
	v_min_i32_e32 v132, v49, v132
	v_min_i32_e32 v135, v38, v37
	v_max_i32_e32 v154, v34, v35
	v_max_i32_e32 v155, v39, v40
	v_max_i32_e32 v157, v36, v41
	s_waitcnt lgkmcnt(1)
	v_mfma_f32_32x32x16_bf16 v[34:49], v[124:127], v[62:65], v[18:33]
	ds_read_b128 v[124:127], v97 offset:64
	v_max_i32_e32 v151, v132, v135
	v_max_i32_e32 v152, v82, v151
	v_min_i32_e32 v136, v138, v136
	v_min_i32_e32 v138, v140, v141
	v_min_i32_e32 v82, v82, v151
	v_max_i32_e32 v147, v147, v150
	s_waitcnt lgkmcnt(1)
	v_mfma_f32_32x32x16_bf16 v[34:49], v[128:131], v[58:61], v[34:49]
	ds_read_b128 v[128:131], v97 offset:96
	v_max_i32_e32 v143, v143, v146
	v_min_i32_e32 v133, v133, v134
	v_min_i32_e32 v156, v154, v155
	v_max_i32_e32 v140, v136, v138
	v_min_i32_e32 v139, v139, v142
	v_max_i32_e32 v142, v154, v155
	s_waitcnt lgkmcnt(1)
	v_mfma_f32_32x32x16_bf16 v[34:49], v[124:127], v[54:57], v[34:49]
	v_max_i32_e32 v124, v148, v149
	v_min_i32_e32 v136, v136, v138
	v_max_i32_e32 v141, v140, v139
	v_min_i32_e32 v139, v140, v139
	v_min_i32_e32 v125, v143, v124
	v_min_i32_e32 v158, v156, v157
	v_min_i32_e32 v132, v132, v135
	s_waitcnt lgkmcnt(0)
; #define LAS __attribute__((address_space(3)))
; #define MFMA32(a, b, c) __builtin_amdgcn_mfma_f32_32x32x16_bf16((a), (b), (c), 0, 0, 0)
; #define CE_(a, b) ce_desc(v[a], v[b])
; __device__ __forceinline__ void sort16_desc(int (&v)[16]) {
;     ...
;     CE_(0,13); CE_(1,12); CE_(2,15); CE_(3,14); CE_(4,8); CE_(5,6); CE_(7,11); CE_(9,10);
;     CE_(0,5); CE_(1,7); CE_(2,9); CE_(3,4); CE_(6,13); CE_(8,14); CE_(10,15); CE_(11,12);
;     CE_(0,1); CE_(2,3); CE_(4,5); CE_(6,8); CE_(7,9); CE_(10,11); CE_(12,13); CE_(14,15);
;     CE_(0,2); CE_(1,3); CE_(4,10); CE_(5,11); CE_(6,7); CE_(8,9); CE_(12,14); CE_(13,15);
;     CE_(1,2); CE_(3,12); CE_(4,6); CE_(5,7); CE_(8,10); CE_(9,11); CE_(13,14);
;     CE_(1,4); CE_(2,6); CE_(5,8); CE_(7,10); CE_(9,13); CE_(11,14);
;     CE_(2,4); CE_(3,6); CE_(9,12); CE_(11,13);
;     CE_(3,5); CE_(6,8); CE_(7,9); CE_(10,12);
;     CE_(3,4); CE_(5,6); CE_(7,8); CE_(9,10); CE_(11,12);
;     CE_(6,7); CE_(8,9);
;     ...
; }
; __device__ __forceinline__ void merge16_desc(int (&a)[16], const int (&b)[16]) {
; #pragma unroll
;     for (int i = 0; i < 16; ++i) a[i] = a[i] > b[15 - i] ? a[i] : b[15 - i];
; #pragma unroll
;     for (int j = 8; j > 0; j >>= 1)
; #pragma unroll
;         for (int i = 0; i < 16; ++i) { const int l = i ^ j; if (l > i) ce_desc(a[i], a[l]); }
; }
; __device__ __forceinline__ void route_task(int task, int tl0, const bf16* QP  , const LAS bf16* KHL, LAS unsigned short* EL, LAS float* GL, int lane) {
;     ...
;         for (int kt = 0; kt < 4; ++kt) {
;             f32x16 X;
; #pragma unroll
;             for (int i = 0; i < 16; ++i) X[i] = 8.f;
;             const LAS bf16* khp = KHL + (half * 128 + 32 * kt + r) * 72 + 8 * hi;
; #pragma unroll
;             for (int ks = 0; ks < 4; ++ks) {
;                 const bf16x8 kh = lds8(khp + 16 * ks);
;                 X = MFMA32(kh, qa[half][ks], X);
;             }
;             int grp[16];
; #pragma unroll
;             for (int i = 0; i < 16; ++i) grp[i] = (int)((__float_as_uint(X[i]) | 127u) - (unsigned)(32 * kt + (i & 3) + 8 * (i >> 2)));
;             sort16_desc(grp);
;             if (kt == 0) {
; #pragma unroll
;                 for (int i = 0; i < 16; ++i) cur[i] = grp[i];
;             } else merge16_desc(cur, grp);
	v_mfma_f32_32x32x16_bf16 v[34:49], v[128:131], v[50:53], v[34:49]
	v_min_i32_e32 v126, v147, v125
	v_min_i32_e32 v153, v137, v152
	v_min_i32_e32 v160, v158, v159
	v_min_i32_e32 v135, v141, v132
	v_min_i32_e32 v127, v142, v126
	s_nop 6
	v_bitop3_b32 v37, v37, s42, 35 bitop3:0x56
	v_bitop3_b32 v48, v48, s42, 58 bitop3:0x56
	v_bitop3_b32 v38, v38, s42, 40 bitop3:0x56
	v_bitop3_b32 v42, v42, s42, 48 bitop3:0x56
	v_bitop3_b32 v34, v34, s42, 32 bitop3:0x56
	v_bitop3_b32 v47, v47, s42, 57 bitop3:0x56
	v_bitop3_b32 v39, v39, s42, 41 bitop3:0x56
	v_bitop3_b32 v40, v40, s42, 42 bitop3:0x56
	v_bitop3_b32 v43, v43, s42, 49 bitop3:0x56
	v_bitop3_b32 v44, v44, s42, 50 bitop3:0x56
	v_bitop3_b32 v36, v36, s42, 34 bitop3:0x56
	v_bitop3_b32 v49, v49, s42, 59 bitop3:0x56
	v_bitop3_b32 v41, v41, s42, 43 bitop3:0x56
	v_bitop3_b32 v45, v45, s42, 51 bitop3:0x56
	v_bitop3_b32 v35, v35, s42, 33 bitop3:0x56
	v_bitop3_b32 v46, v46, s42, 56 bitop3:0x56
	v_max_i32_e32 v128, v37, v48
	v_max_i32_e32 v129, v38, v42
	v_max_i32_e32 v131, v34, v47
	v_max_i32_e32 v134, v39, v40
	v_min_i32_e32 v146, v43, v44
	v_min_i32_e32 v148, v36, v49
	v_min_i32_e32 v150, v41, v45
	v_min_i32_e32 v151, v35, v46
	v_min_i32_e32 v39, v39, v40
	v_min_i32_e32 v34, v34, v47
	v_min_i32_e32 v38, v38, v42
	v_min_i32_e32 v37, v37, v48
	v_max_i32_e32 v35, v35, v46
	v_max_i32_e32 v41, v41, v45
	v_max_i32_e32 v36, v36, v49
	v_max_i32_e32 v43, v43, v44
	v_min_i32_e32 v130, v128, v129
	v_min_i32_e32 v138, v131, v134
	v_max_i32_e32 v149, v146, v148
	v_max_i32_e32 v154, v150, v151
	v_max_i32_e32 v40, v39, v34
	v_max_i32_e32 v42, v38, v37
	v_min_i32_e32 v45, v35, v41
	v_min_i32_e32 v44, v36, v43
	v_min_i32_e32 v150, v150, v151
	v_min_i32_e32 v34, v39, v34
	v_min_i32_e32 v37, v38, v37
	v_min_i32_e32 v38, v146, v148
	v_max_i32_e32 v131, v131, v134
	v_max_i32_e32 v35, v35, v41
	v_max_i32_e32 v36, v36, v43
	v_max_i32_e32 v43, v128, v129
	v_min_i32_e32 v140, v130, v138
	v_min_i32_e32 v155, v149, v154
	v_max_i32_e32 v47, v40, v42
	v_max_i32_e32 v46, v45, v44
	v_min_i32_e32 v40, v40, v42
	v_min_i32_e32 v42, v45, v44
	v_max_i32_e32 v45, v130, v138
	v_max_i32_e32 v130, v149, v154
	v_min_i32_e32 v39, v150, v34
	v_min_i32_e32 v146, v37, v38
	v_max_i32_e32 v34, v150, v34
	v_max_i32_e32 v37, v37, v38
	v_min_i32_e32 v41, v131, v35
	v_min_i32_e32 v128, v36, v43
	v_max_i32_e32 v35, v131, v35
	v_max_i32_e32 v36, v36, v43
	v_min_i32_e32 v48, v47, v46
	v_max_i32_e32 v44, v40, v42
	v_min_i32_e32 v138, v45, v130
	v_min_i32_e32 v40, v40, v42
	v_min_i32_e32 v42, v140, v155
	v_max_i32_e32 v148, v39, v146
	v_min_i32_e32 v38, v34, v37
	v_min_i32_e32 v129, v41, v128
	v_max_i32_e32 v41, v41, v128
	v_min_i32_e32 v43, v35, v36
	v_max_i32_e32 v45, v45, v130
	v_max_i32_e32 v46, v47, v46
	v_max_i32_e32 v161, v140, v155
	v_max_i32_e32 v140, v40, v42
	v_max_i32_e32 v150, v148, v38
	v_max_i32_e32 v34, v34, v37
	v_min_i32_e32 v128, v41, v43
	v_min_i32_e32 v47, v45, v46
	v_min_i32_e32 v49, v161, v48
	v_min_i32_e32 v149, v44, v138
	v_max_i32_e32 v151, v140, v150
	v_min_i32_e32 v37, v129, v34
	v_max_i32_e32 v34, v129, v34
	v_min_i32_e32 v129, v128, v47
	v_max_i32_e32 v48, v161, v48
	v_max_i32_e32 v44, v44, v138
	v_max_i32_e32 v154, v49, v149
	v_max_i32_e32 v134, v151, v37
	v_min_i32_e32 v130, v34, v129
	v_min_i32_e32 v131, v48, v44
	v_min_i32_e32 v49, v49, v149
	v_min_i32_e32 v37, v151, v37
	v_max_i32_e32 v34, v34, v129
	v_max_i32_e32 v44, v48, v44
	v_min_i32_e32 v40, v40, v42
	v_min_i32_e32 v38, v148, v38
	v_max_i32_e32 v41, v41, v43
	v_max_i32_e32 v43, v45, v46
	v_max_i32_e32 v155, v154, v134
	v_min_i32_e32 v138, v130, v131
	v_min_i32_e32 v134, v154, v134
	v_max_i32_e32 v149, v49, v37
	v_min_i32_e32 v48, v34, v44
	v_max_i32_e32 v129, v130, v131
	v_max_i32_e32 v42, v40, v38
	v_min_i32_e32 v140, v140, v150
	v_max_i32_e32 v34, v34, v44
	v_max_i32_e32 v44, v128, v47
	v_min_i32_e32 v45, v41, v43
	v_min_i32_e32 v161, v155, v138
	v_max_i32_e32 v151, v134, v149
	v_min_i32_e32 v130, v48, v129
	v_max_i32_e32 v131, v155, v138
	v_max_i32_e32 v148, v42, v140
	v_min_i32_e32 v37, v49, v37
	v_min_i32_e32 v46, v44, v45
	v_min_i32_e32 v154, v161, v151
	v_min_i32_e32 v138, v130, v131
	v_min_i32_e32 v49, v148, v37
	v_min_i32_e32 v134, v134, v149
	v_min_i32_e32 v47, v34, v46
	v_min_i32_e32 v42, v42, v140
	v_min_i32_e32 v38, v40, v38
	v_min_i32_e32 v39, v39, v146
	v_max3_i32 v39, v144, v145, v39
	v_max3_i32 v38, v143, v124, v38
	v_max3_i32 v40, v147, v125, v42
	v_max3_i32 v42, v142, v126, v49
	v_max3_i32 v37, v127, v148, v37
	v_max3_i32 v49, v156, v157, v134
	v_max3_i32 v124, v158, v159, v154
	v_max3_i32 v125, v160, v161, v151
	v_max3_i32 v126, v137, v152, v138
	v_max3_i32 v127, v153, v130, v131
	v_max3_i32 v48, v82, v48, v129
	v_max3_i32 v47, v141, v132, v47
	v_max3_i32 v34, v135, v34, v46
	v_max3_i32 v44, v139, v44, v45
	v_max3_i32 v41, v136, v41, v43
	v_max3_i32 v35, v133, v35, v36
	v_max_i32_e32 v36, v39, v126
	v_min_i32_e32 v39, v39, v126
	v_max_i32_e32 v43, v38, v127
	v_min_i32_e32 v38, v38, v127
	v_max_i32_e32 v45, v40, v48
	v_min_i32_e32 v40, v40, v48
	v_max_i32_e32 v46, v42, v47
	v_min_i32_e32 v42, v42, v47
	v_max_i32_e32 v47, v37, v34
	v_min_i32_e32 v34, v37, v34
	v_max_i32_e32 v37, v49, v44
	v_min_i32_e32 v44, v49, v44
	v_max_i32_e32 v48, v124, v41
	v_min_i32_e32 v41, v124, v41
	v_max_i32_e32 v49, v125, v35
	v_min_i32_e32 v35, v125, v35
	ds_read_b128 v[124:127], v94 offset:27648
	ds_read_b128 v[128:131], v94 offset:27680
	v_max_i32_e32 v82, v36, v47
	v_min_i32_e32 v132, v36, v47
	v_max_i32_e32 v36, v43, v37
	v_min_i32_e32 v133, v43, v37
	v_max_i32_e32 v37, v45, v48
	v_max_i32_e32 v43, v46, v49
	v_min_i32_e32 v134, v45, v48
	v_min_i32_e32 v135, v46, v49
	v_max_i32_e32 v136, v39, v34
	v_min_i32_e32 v137, v39, v34
	v_max_i32_e32 v138, v38, v44
	v_min_i32_e32 v139, v38, v44
	v_max_i32_e32 v140, v40, v41
	v_min_i32_e32 v141, v40, v41
	v_max_i32_e32 v142, v42, v35
	v_min_i32_e32 v143, v42, v35
	v_max_i32_e32 v144, v82, v37
	v_min_i32_e32 v82, v82, v37
	v_max_i32_e32 v145, v36, v43
	v_min_i32_e32 v146, v36, v43
	s_waitcnt lgkmcnt(1)
; #define LAS __attribute__((address_space(3)))
; #define MFMA32(a, b, c) __builtin_amdgcn_mfma_f32_32x32x16_bf16((a), (b), (c), 0, 0, 0)
; #define CE_(a, b) ce_desc(v[a], v[b])
; __device__ __forceinline__ void sort16_desc(int (&v)[16]) {
;     ...
;     CE_(0,13); CE_(1,12); CE_(2,15); CE_(3,14); CE_(4,8); CE_(5,6); CE_(7,11); CE_(9,10);
;     CE_(0,5); CE_(1,7); CE_(2,9); CE_(3,4); CE_(6,13); CE_(8,14); CE_(10,15); CE_(11,12);
;     CE_(0,1); CE_(2,3); CE_(4,5); CE_(6,8); CE_(7,9); CE_(10,11); CE_(12,13); CE_(14,15);
;     CE_(0,2); CE_(1,3); CE_(4,10); CE_(5,11); CE_(6,7); CE_(8,9); CE_(12,14); CE_(13,15);
;     CE_(1,2); CE_(3,12); CE_(4,6); CE_(5,7); CE_(8,10); CE_(9,11); CE_(13,14);
;     CE_(1,4); CE_(2,6); CE_(5,8); CE_(7,10); CE_(9,13); CE_(11,14);
;     CE_(2,4); CE_(3,6); CE_(9,12); CE_(11,13);
;     CE_(3,5); CE_(6,8); CE_(7,9); CE_(10,12);
;     CE_(3,4); CE_(5,6); CE_(7,8); CE_(9,10); CE_(11,12);
;     CE_(6,7); CE_(8,9);
;     ...
; }
; __device__ __forceinline__ void merge16_desc(int (&a)[16], const int (&b)[16]) {
; #pragma unroll
;     for (int i = 0; i < 16; ++i) a[i] = a[i] > b[15 - i] ? a[i] : b[15 - i];
; #pragma unroll
;     for (int j = 8; j > 0; j >>= 1)
; #pragma unroll
;         for (int i = 0; i < 16; ++i) { const int l = i ^ j; if (l > i) ce_desc(a[i], a[l]); }
; }
; __device__ __forceinline__ void route_task(int task, int tl0, const bf16* QP  , const LAS bf16* KHL, LAS unsigned short* EL, LAS float* GL, int lane) {
;     ...
;         for (int kt = 0; kt < 4; ++kt) {
;             f32x16 X;
; #pragma unroll
;             for (int i = 0; i < 16; ++i) X[i] = 8.f;
;             const LAS bf16* khp = KHL + (half * 128 + 32 * kt + r) * 72 + 8 * hi;
; #pragma unroll
;             for (int ks = 0; ks < 4; ++ks) {
;                 const bf16x8 kh = lds8(khp + 16 * ks);
;                 X = MFMA32(kh, qa[half][ks], X);
;             }
;             int grp[16];
; #pragma unroll
;             for (int i = 0; i < 16; ++i) grp[i] = (int)((__float_as_uint(X[i]) | 127u) - (unsigned)(32 * kt + (i & 3) + 8 * (i >> 2)));
;             sort16_desc(grp);
;             if (kt == 0) {
; #pragma unroll
;                 for (int i = 0; i < 16; ++i) cur[i] = grp[i];
;             } else merge16_desc(cur, grp);
	v_mfma_f32_32x32x16_bf16 v[34:49], v[124:127], v[62:65], v[18:33]
	ds_read_b128 v[124:127], v94 offset:27712
	v_max_i32_e32 v147, v132, v134
	v_min_i32_e32 v132, v132, v134
	v_max_i32_e32 v134, v133, v135
	v_min_i32_e32 v133, v133, v135
	v_max_i32_e32 v135, v136, v140
	v_min_i32_e32 v136, v136, v140
	s_waitcnt lgkmcnt(1)
	v_mfma_f32_32x32x16_bf16 v[34:49], v[128:131], v[58:61], v[34:49]
	ds_read_b128 v[128:131], v94 offset:27744
	v_max_i32_e32 v140, v138, v142
	v_min_i32_e32 v138, v138, v142
	v_max_i32_e32 v142, v137, v141
	v_min_i32_e32 v137, v137, v141
	v_max_i32_e32 v141, v139, v143
	v_min_i32_e32 v139, v139, v143
	s_waitcnt lgkmcnt(1)
	v_mfma_f32_32x32x16_bf16 v[34:49], v[124:127], v[54:57], v[34:49]
	v_min_i32_e32 v143, v144, v145
	v_min_i32_e32 v124, v82, v146
	v_min_i32_e32 v127, v135, v140
	v_min_i32_e32 v125, v147, v134
	v_min_i32_e32 v126, v132, v133
	v_min_i32_e32 v149, v142, v141
	v_min_i32_e32 v148, v136, v138
	s_waitcnt lgkmcnt(0)
	v_mfma_f32_32x32x16_bf16 v[34:49], v[128:131], v[50:53], v[34:49]
	v_min_i32_e32 v150, v137, v139
	s_nop 10
	v_and_or_b32 v37, v37, s43, 60
	v_and_or_b32 v48, v48, s43, 37
	v_and_or_b32 v38, v38, s43, 55
	v_and_or_b32 v42, v42, s43, 47
	v_bitop3_b32 v34, v34, s42, 64 bitop3:0x56
	v_and_or_b32 v47, v47, s43, 38
	v_and_or_b32 v39, v39, s43, 54
	v_and_or_b32 v40, v40, s43, 53
	v_and_or_b32 v43, v43, s43, 46
	v_and_or_b32 v44, v44, s43, 45
	v_and_or_b32 v36, v36, s43, 61
	v_and_or_b32 v49, v49, s43, 36
	v_and_or_b32 v41, v41, s43, 52
	v_and_or_b32 v45, v45, s43, 44
	v_and_or_b32 v35, v35, s43, 62
	v_and_or_b32 v46, v46, s43, 39
	v_max_i32_e32 v128, v37, v48
	v_max_i32_e32 v129, v38, v42
	v_max_i32_e32 v131, v34, v47
	v_max_i32_e32 v151, v39, v40
	v_min_i32_e32 v154, v43, v44
	v_min_i32_e32 v155, v36, v49
	v_min_i32_e32 v157, v41, v45
	v_min_i32_e32 v158, v35, v46
	v_min_i32_e32 v39, v39, v40
	v_min_i32_e32 v34, v34, v47
	v_min_i32_e32 v38, v38, v42
	v_min_i32_e32 v37, v37, v48
	v_max_i32_e32 v35, v35, v46
	v_max_i32_e32 v41, v41, v45
	v_max_i32_e32 v36, v36, v49
	v_max_i32_e32 v43, v43, v44
	v_min_i32_e32 v130, v128, v129
	v_min_i32_e32 v152, v131, v151
	v_max_i32_e32 v156, v154, v155
	v_max_i32_e32 v159, v157, v158
	v_max_i32_e32 v40, v39, v34
	v_max_i32_e32 v42, v38, v37
	v_min_i32_e32 v45, v35, v41
	v_min_i32_e32 v44, v36, v43
	v_min_i32_e32 v157, v157, v158
	v_min_i32_e32 v34, v39, v34
	v_min_i32_e32 v37, v38, v37
	v_min_i32_e32 v38, v154, v155
	v_max_i32_e32 v131, v131, v151
	v_max_i32_e32 v35, v35, v41
	v_max_i32_e32 v36, v36, v43
	v_max_i32_e32 v43, v128, v129
	v_min_i32_e32 v153, v130, v152
	v_min_i32_e32 v160, v156, v159
	v_max_i32_e32 v47, v40, v42
	v_max_i32_e32 v46, v45, v44
	v_min_i32_e32 v40, v40, v42
	v_min_i32_e32 v42, v45, v44
	v_max_i32_e32 v45, v130, v152
	v_max_i32_e32 v130, v156, v159
	v_min_i32_e32 v39, v157, v34
	v_min_i32_e32 v154, v37, v38
	v_max_i32_e32 v34, v157, v34
	v_max_i32_e32 v37, v37, v38
	v_min_i32_e32 v41, v131, v35
	v_min_i32_e32 v128, v36, v43
	v_max_i32_e32 v35, v131, v35
	v_max_i32_e32 v36, v36, v43
	v_min_i32_e32 v48, v47, v46
	v_max_i32_e32 v44, v40, v42
	v_min_i32_e32 v152, v45, v130
	v_min_i32_e32 v40, v40, v42
	v_min_i32_e32 v42, v153, v160
	v_max_i32_e32 v155, v39, v154
	v_min_i32_e32 v38, v34, v37
	v_min_i32_e32 v129, v41, v128
	v_max_i32_e32 v41, v41, v128
	v_min_i32_e32 v43, v35, v36
	v_max_i32_e32 v45, v45, v130
	v_max_i32_e32 v46, v47, v46
	v_max_i32_e32 v161, v153, v160
	v_max_i32_e32 v153, v40, v42
	v_max_i32_e32 v157, v155, v38
	v_max_i32_e32 v34, v34, v37
	v_min_i32_e32 v128, v41, v43
	v_min_i32_e32 v47, v45, v46
	v_min_i32_e32 v49, v161, v48
	v_min_i32_e32 v156, v44, v152
	v_max_i32_e32 v158, v153, v157
	v_min_i32_e32 v37, v129, v34
	v_max_i32_e32 v34, v129, v34
	v_min_i32_e32 v129, v128, v47
	v_max_i32_e32 v48, v161, v48
	v_max_i32_e32 v44, v44, v152
	v_min_i32_e32 v40, v40, v42
	v_min_i32_e32 v38, v155, v38
	v_max_i32_e32 v159, v49, v156
	v_max_i32_e32 v151, v158, v37
	v_min_i32_e32 v130, v34, v129
	v_min_i32_e32 v131, v48, v44
	v_min_i32_e32 v49, v49, v156
	v_min_i32_e32 v37, v158, v37
	v_max_i32_e32 v34, v34, v129
	v_max_i32_e32 v44, v48, v44
	v_max_i32_e32 v42, v40, v38
	v_min_i32_e32 v153, v153, v157
	v_max_i32_e32 v160, v159, v151
	v_min_i32_e32 v152, v130, v131
	v_max_i32_e32 v156, v49, v37
	v_min_i32_e32 v48, v34, v44
	v_max_i32_e32 v129, v130, v131
	v_max_i32_e32 v155, v42, v153
	v_min_i32_e32 v37, v49, v37
	v_min_i32_e32 v151, v159, v151
	v_min_i32_e32 v130, v48, v129
	v_max_i32_e32 v131, v160, v152
	v_min_i32_e32 v49, v155, v37
	v_max_i32_e32 v41, v41, v43
	v_max_i32_e32 v43, v45, v46
	v_min_i32_e32 v42, v42, v153
	v_min_i32_e32 v38, v40, v38
	v_min_i32_e32 v161, v160, v152
	v_max_i32_e32 v158, v151, v156
	v_min_i32_e32 v151, v151, v156
	v_max_i32_e32 v34, v34, v44
	v_max_i32_e32 v44, v128, v47
	v_min_i32_e32 v45, v41, v43
	v_max_i32_e32 v40, v41, v43
	v_max_i32_e32 v38, v143, v38
	v_max3_i32 v41, v82, v146, v42
	v_max_i32_e32 v42, v124, v49
	v_max3_i32 v124, v127, v130, v131
	v_min_i32_e32 v46, v44, v45
	v_max_i32_e32 v43, v125, v151
	v_max3_i32 v49, v126, v161, v158
	v_max3_i32 v44, v149, v44, v45
	v_max_i32_e32 v45, v38, v124
	v_min_i32_e32 v38, v38, v124
	ds_read_b128 v[124:127], v98
	v_min_i32_e32 v159, v161, v158
	v_min_i32_e32 v152, v130, v131
	v_max_i32_e32 v37, v155, v37
	v_max_i32_e32 v48, v48, v129
	v_min_i32_e32 v47, v34, v46
	v_max_i32_e32 v34, v34, v46
	v_min_i32_e32 v39, v39, v154
	v_max3_i32 v39, v144, v145, v39
	v_max3_i32 v37, v147, v134, v37
	v_max3_i32 v46, v132, v133, v159
	v_max3_i32 v82, v135, v140, v152
	v_max3_i32 v48, v136, v138, v48
	v_max_i32_e32 v47, v148, v47
	v_max3_i32 v34, v142, v141, v34
	v_max3_i32 v40, v137, v139, v40
	v_max3_i32 v35, v150, v35, v36
	v_max_i32_e32 v36, v39, v82
	v_min_i32_e32 v39, v39, v82
	v_max_i32_e32 v82, v41, v48
	v_min_i32_e32 v41, v41, v48
	v_max_i32_e32 v48, v42, v47
	v_min_i32_e32 v42, v42, v47
	v_max_i32_e32 v47, v37, v34
	v_min_i32_e32 v34, v37, v34
	v_max_i32_e32 v37, v43, v44
	v_min_i32_e32 v43, v43, v44
	v_max_i32_e32 v44, v46, v40
	v_min_i32_e32 v40, v46, v40
	v_max_i32_e32 v46, v49, v35
	v_min_i32_e32 v35, v49, v35
	v_max_i32_e32 v49, v36, v47
	v_min_i32_e32 v132, v36, v47
	v_max_i32_e32 v36, v45, v37
	v_min_i32_e32 v133, v45, v37
	v_max_i32_e32 v37, v82, v44
	v_min_i32_e32 v82, v82, v44
	v_max_i32_e32 v44, v48, v46
	ds_read_b128 v[128:131], v98 offset:32
	v_min_i32_e32 v134, v48, v46
	v_max_i32_e32 v135, v39, v34
	v_min_i32_e32 v136, v39, v34
	v_max_i32_e32 v137, v38, v43
	v_min_i32_e32 v138, v38, v43
	v_max_i32_e32 v139, v41, v40
	v_min_i32_e32 v140, v41, v40
	v_max_i32_e32 v141, v42, v35
	v_min_i32_e32 v142, v42, v35
	v_max_i32_e32 v143, v49, v37
	v_min_i32_e32 v144, v49, v37
	v_max_i32_e32 v145, v36, v44
	v_min_i32_e32 v146, v36, v44
	s_waitcnt lgkmcnt(1)
; #define LAS __attribute__((address_space(3)))
; #define MFMA32(a, b, c) __builtin_amdgcn_mfma_f32_32x32x16_bf16((a), (b), (c), 0, 0, 0)
; #define CE_(a, b) ce_desc(v[a], v[b])
; __device__ __forceinline__ void sort16_desc(int (&v)[16]) {
;     ...
;     CE_(0,13); CE_(1,12); CE_(2,15); CE_(3,14); CE_(4,8); CE_(5,6); CE_(7,11); CE_(9,10);
;     CE_(0,5); CE_(1,7); CE_(2,9); CE_(3,4); CE_(6,13); CE_(8,14); CE_(10,15); CE_(11,12);
;     CE_(0,1); CE_(2,3); CE_(4,5); CE_(6,8); CE_(7,9); CE_(10,11); CE_(12,13); CE_(14,15);
;     CE_(0,2); CE_(1,3); CE_(4,10); CE_(5,11); CE_(6,7); CE_(8,9); CE_(12,14); CE_(13,15);
;     CE_(1,2); CE_(3,12); CE_(4,6); CE_(5,7); CE_(8,10); CE_(9,11); CE_(13,14);
;     CE_(1,4); CE_(2,6); CE_(5,8); CE_(7,10); CE_(9,13); CE_(11,14);
;     CE_(2,4); CE_(3,6); CE_(9,12); CE_(11,13);
;     CE_(3,5); CE_(6,8); CE_(7,9); CE_(10,12);
;     CE_(3,4); CE_(5,6); CE_(7,8); CE_(9,10); CE_(11,12);
;     CE_(6,7); CE_(8,9);
;     ...
; }
; __device__ __forceinline__ void merge16_desc(int (&a)[16], const int (&b)[16]) {
; #pragma unroll
;     for (int i = 0; i < 16; ++i) a[i] = a[i] > b[15 - i] ? a[i] : b[15 - i];
; #pragma unroll
;     for (int j = 8; j > 0; j >>= 1)
; #pragma unroll
;         for (int i = 0; i < 16; ++i) { const int l = i ^ j; if (l > i) ce_desc(a[i], a[l]); }
; }
; __device__ __forceinline__ void route_task(int task, int tl0, const bf16* QP  , const LAS bf16* KHL, LAS unsigned short* EL, LAS float* GL, int lane) {
;     ...
;         for (int kt = 0; kt < 4; ++kt) {
;             f32x16 X;
; #pragma unroll
;             for (int i = 0; i < 16; ++i) X[i] = 8.f;
;             const LAS bf16* khp = KHL + (half * 128 + 32 * kt + r) * 72 + 8 * hi;
; #pragma unroll
;             for (int ks = 0; ks < 4; ++ks) {
;                 const bf16x8 kh = lds8(khp + 16 * ks);
;                 X = MFMA32(kh, qa[half][ks], X);
;             }
;             int grp[16];
; #pragma unroll
;             for (int i = 0; i < 16; ++i) grp[i] = (int)((__float_as_uint(X[i]) | 127u) - (unsigned)(32 * kt + (i & 3) + 8 * (i >> 2)));
;             sort16_desc(grp);
;             if (kt == 0) {
; #pragma unroll
;                 for (int i = 0; i < 16; ++i) cur[i] = grp[i];
;             } else merge16_desc(cur, grp);
	v_mfma_f32_32x32x16_bf16 v[34:49], v[124:127], v[62:65], v[18:33]
	v_max_i32_e32 v147, v132, v82
	s_nop 5
	ds_read_b128 v[18:21], v98 offset:64
	ds_read_b128 v[22:25], v98 offset:96
	s_waitcnt lgkmcnt(2)
	v_mfma_f32_32x32x16_bf16 v[34:49], v[128:131], v[58:61], v[34:49]
	v_min_i32_e32 v26, v132, v82
	v_max_i32_e32 v27, v133, v134
	v_min_i32_e32 v30, v135, v139
	v_min_i32_e32 v32, v137, v141
	v_max_i32_e32 v33, v136, v140
	v_max_i32_e32 v59, v138, v142
	v_min_i32_e32 v28, v133, v134
	s_waitcnt lgkmcnt(1)
	v_mfma_f32_32x32x16_bf16 v[34:49], v[18:21], v[54:57], v[34:49]
	v_min_i32_e32 v19, v147, v27
	v_min_i32_e32 v54, v30, v32
	v_min_i32_e32 v55, v33, v59
	v_max_i32_e32 v29, v135, v139
	v_max_i32_e32 v31, v137, v141
	v_min_i32_e32 v58, v136, v140
	v_min_i32_e32 v60, v138, v142
	s_waitcnt lgkmcnt(0)
	v_mfma_f32_32x32x16_bf16 v[34:49], v[22:25], v[50:53], v[34:49]
	v_min_i32_e32 v18, v144, v146
	v_min_i32_e32 v61, v143, v145
	v_min_i32_e32 v20, v26, v28
	v_min_i32_e32 v21, v29, v31
	v_min_i32_e32 v56, v58, v60
	s_nop 6
	v_or_b32_e32 v22, 0x7f, v41
	v_or_b32_e32 v23, 0x7f, v45
	v_or_b32_e32 v25, 0x7f, v35
	v_or_b32_e32 v35, 0x7f, v46
	v_and_or_b32 v39, v39, s43, 22
	v_and_or_b32 v40, v40, s43, 21
	v_and_or_b32 v34, v34, s43, 31
	v_and_or_b32 v47, v47, s43, 6
	v_and_or_b32 v38, v38, s43, 23
	v_and_or_b32 v42, v42, s43, 15
	v_and_or_b32 v37, v37, s43, 28
	v_and_or_b32 v48, v48, s43, 5
	v_and_or_b32 v43, v43, s43, 14
	v_and_or_b32 v44, v44, s43, 13
	v_and_or_b32 v36, v36, s43, 29
	v_and_or_b32 v49, v49, s43, 4
	v_add_u32_e32 v22, 0xffffff95, v22
	v_add_u32_e32 v23, 0xffffff8d, v23
	v_add_u32_e32 v25, 0xffffff9f, v25
	v_add_u32_e32 v35, 0xffffff88, v35
	v_min_i32_e32 v24, v22, v23
	v_min_i32_e32 v41, v25, v35
	v_min_i32_e32 v46, v39, v40
	v_min_i32_e32 v50, v34, v47
	v_min_i32_e32 v53, v38, v42
	v_min_i32_e32 v57, v37, v48
	v_min_i32_e32 v63, v43, v44
	v_min_i32_e32 v64, v36, v49
	v_max_i32_e32 v34, v34, v47
	v_max_i32_e32 v39, v39, v40
	v_max_i32_e32 v25, v25, v35
	v_max_i32_e32 v22, v22, v23
	v_max_i32_e32 v36, v36, v49
	v_max_i32_e32 v43, v43, v44
	v_max_i32_e32 v37, v37, v48
	v_max_i32_e32 v38, v38, v42
	v_min_i32_e32 v45, v24, v41
	v_min_i32_e32 v51, v46, v50
	v_max_i32_e32 v40, v34, v39
	v_max_i32_e32 v23, v25, v22
	v_max_i32_e32 v44, v36, v43
	v_max_i32_e32 v42, v37, v38
	v_min_i32_e32 v37, v37, v38
	v_min_i32_e32 v34, v34, v39
	v_max_i32_e32 v39, v63, v64
	v_max_i32_e32 v24, v24, v41
	v_max_i32_e32 v46, v46, v50
	v_max_i32_e32 v50, v53, v57
	v_min_i32_e32 v22, v25, v22
	v_min_i32_e32 v25, v36, v43
	v_min_i32_e32 v62, v53, v57
	v_min_i32_e32 v65, v63, v64
	v_min_i32_e32 v35, v40, v23
	v_min_i32_e32 v47, v44, v42
	v_max_i32_e32 v23, v40, v23
	v_max_i32_e32 v40, v44, v42
	v_max_i32_e32 v38, v37, v34
	v_max_i32_e32 v41, v39, v24
	v_max_i32_e32 v53, v46, v50
	v_max_i32_e32 v36, v22, v25
	v_min_i32_e32 v46, v46, v50
	v_min_i32_e32 v22, v22, v25
	v_min_i32_e32 v52, v45, v51
	v_min_i32_e32 v82, v62, v65
	v_min_i32_e32 v48, v35, v47
	v_max_i32_e32 v45, v45, v51
	v_max_i32_e32 v49, v62, v65
	v_max_i32_e32 v35, v35, v47
	v_min_i32_e32 v42, v23, v40
	v_max_i32_e32 v47, v38, v41
	v_max_i32_e32 v43, v53, v36
	v_min_i32_e32 v34, v37, v34
	v_min_i32_e32 v24, v39, v24
	v_max_i32_e32 v25, v46, v22
	v_min_i32_e32 v38, v38, v41
	v_max_i32_e32 v51, v45, v49
	v_min_i32_e32 v44, v35, v42
	v_min_i32_e32 v57, v47, v43
	v_max_i32_e32 v37, v34, v24
	v_min_i32_e32 v36, v53, v36
	v_max_i32_e32 v41, v25, v38
	v_min_i32_e32 v25, v25, v38
	v_min_i32_e32 v22, v46, v22
	v_min_i32_e32 v24, v34, v24
	v_max_i32_e32 v38, v52, v82
	v_min_i32_e32 v45, v45, v49
	v_max_i32_e32 v62, v48, v51
	v_min_i32_e32 v63, v44, v57
	v_max_i32_e32 v39, v37, v36
	v_max_i32_e32 v34, v22, v24
	v_max_i32_e32 v46, v38, v45
	v_max_i32_e32 v64, v62, v63
	v_max_i32_e32 v50, v39, v41
	v_min_i32_e32 v62, v62, v63
	v_min_i32_e32 v39, v39, v41
	v_min_i32_e32 v36, v37, v36
	v_max_i32_e32 v49, v34, v46
	v_min_i32_e32 v48, v48, v51
	v_min_i32_e32 v22, v22, v24
	v_min_i32_e32 v24, v38, v45
	v_min_i32_e32 v53, v64, v50
	v_max_i32_e32 v41, v62, v39
	v_max_i32_e32 v37, v36, v25
	v_max_i32_e32 v51, v49, v48
	v_max_i32_e32 v38, v22, v24
	v_min_i32_e32 v34, v34, v46
	v_min_i32_e32 v25, v36, v25
	v_min_i32_e32 v36, v49, v48
	v_min_i32_e32 v124, v52, v82
	v_max_i32_e32 v52, v37, v51
	v_min_i32_e32 v39, v62, v39
	v_max_i32_e32 v45, v38, v34
	v_min_i32_e32 v46, v25, v36
	v_max_i32_e32 v35, v35, v42
	v_max_i32_e32 v42, v47, v43
	v_min_i32_e32 v34, v38, v34
	v_max_i32_e32 v38, v53, v41
	v_min_i32_e32 v37, v37, v51
	v_max_i32_e32 v25, v25, v36
	v_max_i32_e32 v48, v45, v46
	v_max_i32_e32 v44, v44, v57
	v_min_i32_e32 v43, v35, v42
	v_max3_i32 v30, v30, v32, v38
	v_min_i32_e32 v38, v52, v39
	v_max_i32_e32 v36, v37, v25
	v_min_i32_e32 v25, v37, v25
	v_min_i32_e32 v63, v53, v41
	v_max_i32_e32 v62, v52, v39
	v_max3_i32 v27, v147, v27, v48
	v_max_i32_e32 v48, v64, v50
	v_min_i32_e32 v47, v44, v43
	v_min_i32_e32 v39, v38, v36
	v_max_i32_e32 v19, v19, v25
	v_max3_i32 v25, v55, v44, v43
	v_min_i32_e32 v43, v45, v46
	v_min_i32_e32 v65, v63, v62
	v_max_i32_e32 v49, v48, v47
	v_max3_i32 v26, v26, v28, v39
	v_max_i32_e32 v28, v35, v42
	v_min_i32_e32 v22, v22, v24
	v_max_i32_e32 v18, v18, v43
	v_min_i32_e32 v43, v48, v47
	v_max3_i32 v124, v143, v145, v124
	v_max3_i32 v29, v29, v31, v65
	v_max3_i32 v33, v33, v59, v49
	v_max3_i32 v34, v144, v146, v34
	v_max3_i32 v28, v58, v60, v28
	v_max_i32_e32 v22, v61, v22
	v_max3_i32 v21, v21, v63, v62
	v_max_i32_e32 v43, v54, v43
	v_max3_i32 v20, v20, v38, v36
	v_max3_i32 v23, v56, v23, v40
	v_min_i32_e32 v31, v124, v29
	v_min_i32_e32 v49, v27, v33
	v_min_i32_e32 v32, v34, v30
	v_min_i32_e32 v35, v26, v28
; __device__ __forceinline__ void route_task(int task, int tl0, const bf16* QP  , const LAS bf16* KHL, LAS unsigned short* EL, LAS float* GL, int lane) {
;     ...
;         { const unsigned h4 = 4u * (unsigned)hi;
; #pragma unroll
;           for (int i = 0; i < 16; ++i) cur[i] -= (int)h4; }
;         int oth[16];
; #pragma unroll
;         for (int i = 0; i < 16; ++i) oth[i] = __shfl_xor(cur[i], 32);
;         merge16_desc(cur, oth);
; #pragma unroll
;         for (int i = 0; i < 16; ++i) top[half][i] = cur[i];
;     }
;     unsigned P1[4], P2[4];
; #pragma unroll
;     for (int q = 0; q < 4; ++q) { P1[q] = 0u; P2[q] = 0u;
; #pragma unroll
;         for (int s = 0; s < 4; ++s) { P1[q] |= (127u - ((unsigned)top[0][4 * q + s] & 127u)) << (8 * s); P2[q] |= (127u - ((unsigned)top[1][4 * q + s] & 127u)) << (8 * s); } }
	v_min_i32_e32 v24, v22, v21
	v_min_i32_e32 v37, v19, v25
	v_min_i32_e32 v44, v18, v43
	v_min_i32_e32 v36, v20, v23
	v_max_i32_e32 v29, v124, v29
	v_max_i32_e32 v27, v27, v33
	v_max_i32_e32 v30, v34, v30
	v_max_i32_e32 v26, v26, v28
	v_max_i32_e32 v21, v22, v21
	v_max_i32_e32 v19, v19, v25
	v_max_i32_e32 v18, v18, v43
	v_max_i32_e32 v20, v20, v23
	v_max_i32_e32 v33, v29, v27
	v_max_i32_e32 v28, v30, v26
	v_max_i32_e32 v22, v21, v19
	v_max_i32_e32 v23, v18, v20
	v_max_i32_e32 v34, v33, v28
	v_max_i32_e32 v25, v22, v23
	v_min_i32_e32 v28, v33, v28
	v_min_i32_e32 v22, v22, v23
	v_min_i32_e32 v27, v29, v27
	v_min_i32_e32 v26, v30, v26
	v_min_i32_e32 v19, v21, v19
	v_min_i32_e32 v18, v18, v20
	v_max_i32_e32 v23, v28, v22
	v_min_i32_e32 v22, v28, v22
	v_max_i32_e32 v28, v27, v26
	v_max_i32_e32 v20, v19, v18
	v_min_i32_e32 v26, v27, v26
	v_min_i32_e32 v18, v19, v18
	v_min_i32_e32 v42, v24, v37
	v_max_i32_e32 v19, v26, v18
	v_min_i32_e32 v18, v26, v18
	v_max_i32_e32 v26, v31, v49
	v_max_i32_e32 v27, v32, v35
	v_max_i32_e32 v24, v24, v37
	v_max_i32_e32 v29, v44, v36
	v_min_i32_e32 v50, v31, v49
	v_min_i32_e32 v39, v32, v35
	v_min_i32_e32 v38, v44, v36
	v_max_i32_e32 v21, v28, v20
	v_min_i32_e32 v20, v28, v20
	v_max_i32_e32 v28, v26, v27
	v_max_i32_e32 v30, v24, v29
	v_min_i32_e32 v26, v26, v27
	v_min_i32_e32 v24, v24, v29
	v_min_i32_e32 v41, v50, v39
	v_min_i32_e32 v40, v42, v38
	v_max_i32_e32 v27, v26, v24
	v_min_i32_e32 v24, v26, v24
	v_max_i32_e32 v26, v50, v39
	v_max_i32_e32 v29, v42, v38
	v_min_i32_e32 v45, v41, v40
	v_max_i32_e32 v43, v34, v25
	v_min_i32_e32 v25, v34, v25
	v_max_i32_e32 v31, v28, v30
	v_min_i32_e32 v28, v28, v30
	v_max_i32_e32 v30, v26, v29
	v_min_i32_e32 v26, v26, v29
	v_max_i32_e32 v29, v41, v40
	v_sub_u32_e32 v32, v43, v87
	v_sub_u32_e32 v25, v25, v87
	v_sub_u32_e32 v23, v23, v87
	v_sub_u32_e32 v22, v22, v87
	v_sub_u32_e32 v21, v21, v87
	v_sub_u32_e32 v20, v20, v87
	v_sub_u32_e32 v19, v19, v87
	v_sub_u32_e32 v18, v18, v87
	v_sub_u32_e32 v31, v31, v87
	v_sub_u32_e32 v28, v28, v87
	v_sub_u32_e32 v27, v27, v87
	v_sub_u32_e32 v24, v24, v87
	v_sub_u32_e32 v30, v30, v87
	v_sub_u32_e32 v26, v26, v87
	v_sub_u32_e32 v29, v29, v87
	v_sub_u32_e32 v33, v45, v87
	ds_bpermute_b32 v34, v123, v32
	ds_bpermute_b32 v35, v123, v25
	ds_bpermute_b32 v36, v123, v23
	ds_bpermute_b32 v37, v123, v22
	ds_bpermute_b32 v38, v123, v21
	ds_bpermute_b32 v39, v123, v20
	ds_bpermute_b32 v40, v123, v19
	ds_bpermute_b32 v41, v123, v18
	ds_bpermute_b32 v42, v123, v31
	ds_bpermute_b32 v43, v123, v28
	ds_bpermute_b32 v44, v123, v27
	ds_bpermute_b32 v45, v123, v33
	ds_bpermute_b32 v46, v123, v29
	ds_bpermute_b32 v47, v123, v26
	ds_bpermute_b32 v48, v123, v30
	ds_bpermute_b32 v49, v123, v24
	s_waitcnt lgkmcnt(4)
	v_max_i32_e32 v32, v32, v45
	s_waitcnt lgkmcnt(3)
	v_max_i32_e32 v25, v25, v46
	s_waitcnt lgkmcnt(2)
	v_max_i32_e32 v23, v23, v47
	s_waitcnt lgkmcnt(1)
	v_max_i32_e32 v22, v22, v48
	s_waitcnt lgkmcnt(0)
	v_max_i32_e32 v21, v21, v49
	v_max_i32_e32 v20, v20, v44
	v_max_i32_e32 v19, v19, v43
	v_max_i32_e32 v18, v18, v42
	v_max_i32_e32 v31, v31, v41
	v_max_i32_e32 v28, v28, v40
	v_max_i32_e32 v27, v27, v39
	v_max_i32_e32 v24, v24, v38
	v_max_i32_e32 v30, v30, v37
	v_max_i32_e32 v26, v26, v36
	v_max_i32_e32 v29, v29, v35
	v_max_i32_e32 v33, v33, v34
	v_max_i32_e32 v34, v32, v31
	v_min_i32_e32 v31, v32, v31
	v_max_i32_e32 v32, v25, v28
	v_min_i32_e32 v25, v25, v28
	v_max_i32_e32 v28, v23, v27
	v_min_i32_e32 v23, v23, v27
	v_max_i32_e32 v27, v22, v24
	v_min_i32_e32 v22, v22, v24
	v_max_i32_e32 v24, v21, v30
	v_min_i32_e32 v21, v21, v30
	v_max_i32_e32 v30, v20, v26
	v_min_i32_e32 v20, v20, v26
	v_max_i32_e32 v26, v19, v29
	v_min_i32_e32 v19, v19, v29
	v_max_i32_e32 v29, v18, v33
	v_min_i32_e32 v18, v18, v33
	v_max_i32_e32 v33, v34, v24
	v_min_i32_e32 v24, v34, v24
	v_max_i32_e32 v34, v32, v30
	v_min_i32_e32 v30, v32, v30
	v_max_i32_e32 v32, v28, v26
	v_min_i32_e32 v26, v28, v26
	v_max_i32_e32 v28, v27, v29
	v_min_i32_e32 v27, v27, v29
	v_max_i32_e32 v29, v31, v21
	v_min_i32_e32 v21, v31, v21
	v_max_i32_e32 v31, v25, v20
	v_min_i32_e32 v20, v25, v20
	v_max_i32_e32 v25, v23, v19
	v_min_i32_e32 v19, v23, v19
	v_max_i32_e32 v23, v22, v18
	v_min_i32_e32 v18, v22, v18
	v_max_i32_e32 v22, v33, v32
	v_min_i32_e32 v32, v33, v32
	v_max_i32_e32 v33, v34, v28
	v_min_i32_e32 v28, v34, v28
	v_max_i32_e32 v34, v24, v26
	v_min_i32_e32 v24, v24, v26
	v_max_i32_e32 v35, v30, v27
	v_min_i32_e32 v27, v30, v27
	v_max_i32_e32 v30, v29, v25
	v_min_i32_e32 v25, v29, v25
	v_max_i32_e32 v29, v31, v23
	v_min_i32_e32 v23, v31, v23
	v_max_i32_e32 v31, v21, v19
	v_min_i32_e32 v19, v21, v19
	v_max_i32_e32 v21, v20, v18
	v_min_i32_e32 v18, v20, v18
	v_max_i32_e32 v26, v22, v33
	v_min_i32_e32 v33, v22, v33
	v_lshlrev_b32_e32 v20, 8, v81
	v_lshlrev_b32_e32 v22, 16, v80
	v_max_i32_e32 v36, v32, v28
	v_max_i32_e32 v40, v19, v18
	v_min_i32_e32 v41, v19, v18
	v_and_b32_e32 v18, 0x7f, v79
	v_and_b32_e32 v20, 0x7f00, v20
	v_and_b32_e32 v22, 0x7f0000, v22
	v_max_i32_e32 v39, v31, v21
	v_min_i32_e32 v31, v31, v21
	v_lshlrev_b32_e32 v21, 8, v33
	v_or3_b32 v18, v20, v18, v22
	v_lshlrev_b32_e32 v20, 16, v36
	v_and_b32_e32 v19, 0x7f, v26
	v_and_b32_e32 v21, 0x7f00, v21
	v_and_b32_e32 v20, 0x7f0000, v20
	v_or3_b32 v20, v21, v19, v20
	v_lshlrev_b32_e32 v19, 24, v78
	v_min_i32_e32 v28, v32, v28
	v_and_b32_e32 v19, 0x7f000000, v19
	v_bitop3_b32 v19, v18, s68, v19 bitop3:0x36
	v_lshlrev_b32_e32 v18, 24, v28
	v_max_i32_e32 v32, v34, v35
	v_min_i32_e32 v34, v34, v35
	v_max_i32_e32 v35, v24, v27
	v_min_i32_e32 v27, v24, v27
	v_and_b32_e32 v18, 0x7f000000, v18
	v_lshlrev_b32_e32 v22, 8, v76
	v_lshlrev_b32_e32 v24, 16, v75
; __device__ __forceinline__ void route_task(int task, int tl0, const bf16* QP  , const LAS bf16* KHL, LAS unsigned short* EL, LAS float* GL, int lane) {
;     ...
;     unsigned P1[4], P2[4];
; #pragma unroll
;     for (int q = 0; q < 4; ++q) { P1[q] = 0u; P2[q] = 0u;
; #pragma unroll
;         for (int s = 0; s < 4; ++s) { P1[q] |= (127u - ((unsigned)top[0][4 * q + s] & 127u)) << (8 * s); P2[q] |= (127u - ((unsigned)top[1][4 * q + s] & 127u)) << (8 * s); } }
;     int bk[16];
;     {
;         int hi2 = hi; asm volatile("" : "+v"(hi2));
;         const bool h1 = hi2 != 0;
;         constexpr int A1[16] = {1, 1, 1, 1, 1, 1, 1, 1, 2, 2, 2, 2, 2, 3, 3, 3}, B1[16] = {0, 1, 2, 3, 4, 5, 6, 7, 0, 1, 2, 3, 4, 0, 1, 2};
; #pragma unroll
;         for (int i = 0; i < 16; ++i) { const float ta = __int_as_float(h1 ? top[0][A1[i]] : top[0][0]), tb = __int_as_float(h1 ? top[1][B1[i]] : top[1][i]); const unsigned code = h1 ? (unsigned)(A1[i] * 16 + B1[i]) : (unsigned)i;
;             bk[i] = (int)((__float_as_uint(ta + tb) | 255u) - code); }
;         sort16_desc(bk);
	v_bitop3_b32 v18, v20, s68, v18 bitop3:0x36
	v_and_b32_e32 v20, 0x7f, v77
	v_and_b32_e32 v22, 0x7f00, v22
	v_and_b32_e32 v24, 0x7f0000, v24
	v_max_i32_e32 v37, v30, v29
	v_min_i32_e32 v29, v30, v29
	v_max_i32_e32 v30, v25, v23
	v_min_i32_e32 v38, v25, v23
	v_lshlrev_b32_e32 v23, 8, v34
	v_or3_b32 v20, v22, v20, v24
	v_lshlrev_b32_e32 v22, 16, v35
	v_and_b32_e32 v21, 0x7f, v32
	v_and_b32_e32 v23, 0x7f00, v23
	v_and_b32_e32 v22, 0x7f0000, v22
	v_or3_b32 v22, v23, v21, v22
	v_lshlrev_b32_e32 v21, 24, v73
	v_and_b32_e32 v21, 0x7f000000, v21
	v_bitop3_b32 v21, v20, s68, v21 bitop3:0x36
	v_lshlrev_b32_e32 v20, 24, v27
	v_and_b32_e32 v20, 0x7f000000, v20
	v_lshlrev_b32_e32 v24, 8, v74
	v_lshlrev_b32_e32 v42, 16, v72
	v_bitop3_b32 v20, v22, s68, v20 bitop3:0x36
	v_and_b32_e32 v22, 0x7f, v71
	v_and_b32_e32 v24, 0x7f00, v24
	v_and_b32_e32 v42, 0x7f0000, v42
	v_lshlrev_b32_e32 v25, 8, v29
	v_or3_b32 v22, v24, v22, v42
	v_lshlrev_b32_e32 v24, 16, v30
	v_and_b32_e32 v23, 0x7f, v37
	v_and_b32_e32 v25, 0x7f00, v25
	v_and_b32_e32 v24, 0x7f0000, v24
	v_or3_b32 v24, v25, v23, v24
	v_lshlrev_b32_e32 v23, 24, v70
	v_and_b32_e32 v23, 0x7f000000, v23
	v_bitop3_b32 v23, v22, s68, v23 bitop3:0x36
	v_lshlrev_b32_e32 v22, 24, v38
	v_and_b32_e32 v22, 0x7f000000, v22
	v_lshlrev_b32_e32 v42, 8, v68
	v_lshlrev_b32_e32 v44, 16, v67
	v_bitop3_b32 v22, v24, s68, v22 bitop3:0x36
	v_and_b32_e32 v24, 0x7f, v69
	v_and_b32_e32 v42, 0x7f00, v42
	v_and_b32_e32 v44, 0x7f0000, v44
	v_lshlrev_b32_e32 v43, 8, v31
	v_or3_b32 v24, v42, v24, v44
	v_lshlrev_b32_e32 v42, 16, v40
	v_and_b32_e32 v25, 0x7f, v39
	v_and_b32_e32 v43, 0x7f00, v43
	v_and_b32_e32 v42, 0x7f0000, v42
	v_or3_b32 v42, v43, v25, v42
	v_lshlrev_b32_e32 v25, 24, v66
	v_and_b32_e32 v25, 0x7f000000, v25
	v_bitop3_b32 v25, v24, s68, v25 bitop3:0x36
	v_lshlrev_b32_e32 v24, 24, v41
	v_and_b32_e32 v24, 0x7f000000, v24
	v_bitop3_b32 v24, v42, s68, v24 bitop3:0x36
	v_mov_b32_e32 v42, v86
	v_add_f32_e32 v62, v74, v26
	v_cmp_eq_u32_e32 vcc, 0, v42
	v_add_f32_e32 v63, v72, v26
	v_add_f32_e32 v64, v70, v26
	v_cndmask_b32_e32 v42, v81, v79, vcc
	v_add_f32_e32 v44, v42, v26
	v_cndmask_b32_e64 v43, -16, 0, vcc
	v_or_b32_e32 v44, 0xff, v44
	v_add_f32_e32 v45, v42, v33
	v_add_u32_e32 v43, v44, v43
	v_cndmask_b32_e64 v44, v99, -1, vcc
	v_or_b32_e32 v45, 0xff, v45
	v_add_f32_e32 v46, v42, v36
	v_add_u32_e32 v44, v45, v44
	v_cndmask_b32_e64 v45, v100, -2, vcc
	v_or_b32_e32 v46, 0xff, v46
	v_add_f32_e32 v47, v42, v28
	v_add_u32_e32 v45, v46, v45
	v_cndmask_b32_e64 v46, v101, -3, vcc
	v_or_b32_e32 v47, 0xff, v47
	v_add_f32_e32 v48, v42, v32
	v_add_u32_e32 v46, v47, v46
	v_cndmask_b32_e64 v47, v102, -4, vcc
	v_or_b32_e32 v48, 0xff, v48
	v_add_f32_e32 v34, v42, v34
	v_add_f32_e32 v35, v42, v35
	v_add_f32_e32 v27, v42, v27
	v_cndmask_b32_e32 v42, v80, v79, vcc
	v_cndmask_b32_e32 v32, v32, v39, vcc
	v_add_u32_e32 v47, v48, v47
	v_cndmask_b32_e64 v48, v103, -5, vcc
	v_or_b32_e32 v34, 0xff, v34
	v_add_f32_e32 v32, v42, v32
	v_add_u32_e32 v34, v34, v48
	v_cndmask_b32_e64 v48, v104, -6, vcc
	v_or_b32_e32 v35, 0xff, v35
	v_cndmask_b32_e32 v37, v26, v37, vcc
	v_cndmask_b32_e64 v39, v116, -12, vcc
	v_or_b32_e32 v32, 0xff, v32
	v_add_u32_e32 v35, v35, v48
	v_cndmask_b32_e64 v48, v105, -7, vcc
	v_or_b32_e32 v27, 0xff, v27
	v_add_f32_e32 v37, v42, v37
	v_cndmask_b32_e32 v29, v33, v29, vcc
	v_add_u32_e32 v32, v32, v39
	v_cndmask_b32_e32 v39, v78, v79, vcc
	v_cndmask_b32_e32 v31, v26, v31, vcc
	v_add_u32_e32 v27, v27, v48
	v_cndmask_b32_e64 v48, v106, -8, vcc
	v_or_b32_e32 v37, 0xff, v37
	v_add_f32_e32 v29, v42, v29
	v_cndmask_b32_e32 v30, v36, v30, vcc
	v_cndmask_b32_e32 v38, v28, v38, vcc
	v_add_f32_e32 v31, v39, v31
	v_cndmask_b32_e32 v40, v33, v40, vcc
	v_add_u32_e32 v37, v37, v48
	v_cndmask_b32_e64 v48, v107, -9, vcc
	v_or_b32_e32 v29, 0xff, v29
	v_add_f32_e32 v30, v42, v30
	v_add_f32_e32 v38, v42, v38
	v_cndmask_b32_e64 v42, v117, -13, vcc
	v_or_b32_e32 v31, 0xff, v31
	v_add_f32_e32 v40, v39, v40
	v_cndmask_b32_e32 v41, v36, v41, vcc
	v_add_u32_e32 v29, v29, v48
	v_cndmask_b32_e64 v48, v114, -10, vcc
	v_or_b32_e32 v30, 0xff, v30
	v_add_u32_e32 v31, v31, v42
	v_cndmask_b32_e64 v42, v118, -14, vcc
	v_or_b32_e32 v40, 0xff, v40
	v_add_f32_e32 v39, v39, v41
	v_add_u32_e32 v30, v30, v48
	v_cndmask_b32_e64 v48, v115, -11, vcc
	v_or_b32_e32 v38, 0xff, v38
	v_add_u32_e32 v40, v40, v42
	v_cndmask_b32_e64 v42, v119, -15, vcc
	v_or_b32_e32 v39, 0xff, v39
	v_add_u32_e32 v38, v38, v48
	v_add_u32_e32 v39, v39, v42
	v_max_i32_e32 v41, v43, v31
	v_min_i32_e32 v31, v43, v31
	v_max_i32_e32 v42, v44, v32
	v_min_i32_e32 v32, v44, v32
	v_max_i32_e32 v43, v45, v39
	v_min_i32_e32 v39, v45, v39
	v_max_i32_e32 v44, v46, v40
	v_min_i32_e32 v40, v46, v40
	v_max_i32_e32 v45, v47, v37
	v_min_i32_e32 v37, v47, v37
	v_max_i32_e32 v46, v34, v35
	v_min_i32_e32 v34, v34, v35
	v_max_i32_e32 v35, v27, v38
	v_min_i32_e32 v27, v27, v38
	v_max_i32_e32 v38, v29, v30
	v_min_i32_e32 v29, v29, v30
	v_max_i32_e32 v30, v41, v46
	v_min_i32_e32 v41, v41, v46
	v_max_i32_e32 v46, v42, v35
	v_min_i32_e32 v35, v42, v35
	v_max_i32_e32 v42, v43, v38
	v_min_i32_e32 v38, v43, v38
	v_max_i32_e32 v43, v44, v45
	v_min_i32_e32 v44, v44, v45
	v_max_i32_e32 v45, v34, v31
	v_min_i32_e32 v31, v34, v31
	v_max_i32_e32 v34, v37, v40
	v_min_i32_e32 v37, v37, v40
	v_max_i32_e32 v40, v29, v39
	v_min_i32_e32 v29, v29, v39
	v_max_i32_e32 v39, v27, v32
	v_min_i32_e32 v27, v27, v32
	v_max_i32_e32 v32, v30, v46
	v_min_i32_e32 v30, v30, v46
	v_max_i32_e32 v46, v42, v43
	v_min_i32_e32 v42, v42, v43
	v_max_i32_e32 v43, v44, v41
	v_min_i32_e32 v41, v44, v41
	v_max_i32_e32 v44, v45, v34
	v_min_i32_e32 v34, v45, v34
; #define CAND(a, b) (int)((__float_as_uint(__int_as_float(top[0][a]) + __int_as_float(top[1][b])) | 255u) - (unsigned)((a) * 16 + (b)))
; __device__ __forceinline__ void route_task(int task, int tl0, const bf16* QP  , const LAS bf16* KHL, LAS unsigned short* EL, LAS float* GL, int lane) {
;     ...
;         sort16_desc(bk);
;         int oth[16];
; #pragma unroll
;         for (int i = 0; i < 16; ++i) oth[i] = __shfl_xor(bk[i], 32);
;         merge16_desc(bk, oth);
;     }
;     ...
;     {
;         int gk[16];
;         gk[0] = CAND(3, 3); gk[1] = CAND(4, 0); gk[2] = CAND(4, 1); gk[3] = CAND(4, 2); gk[4] = CAND(5, 0); gk[5] = CAND(5, 1); gk[6] = CAND(6, 0); gk[7] = CAND(6, 1);
;         gk[8] = CAND(7, 0); gk[9] = CAND(7, 1); gk[10] = CAND(8, 0); gk[11] = CAND(9, 0); gk[12] = CAND(10, 0); gk[13] = CAND(11, 0); gk[14] = CAND(12, 0); gk[15] = CAND(13, 0);
;         sort16_desc(gk);
	v_max_i32_e32 v45, v35, v38
	v_min_i32_e32 v35, v35, v38
	v_max_i32_e32 v38, v40, v39
	v_min_i32_e32 v39, v40, v39
	v_max_i32_e32 v40, v27, v31
	v_min_i32_e32 v27, v27, v31
	v_max_i32_e32 v31, v37, v29
	v_min_i32_e32 v29, v37, v29
	v_max_i32_e32 v37, v32, v46
	v_min_i32_e32 v32, v32, v46
	v_max_i32_e32 v46, v30, v42
	v_min_i32_e32 v30, v30, v42
	v_max_i32_e32 v42, v43, v38
	v_min_i32_e32 v38, v43, v38
	v_max_i32_e32 v43, v41, v39
	v_min_i32_e32 v39, v41, v39
	v_max_i32_e32 v41, v44, v45
	v_min_i32_e32 v44, v44, v45
	v_max_i32_e32 v45, v34, v35
	v_min_i32_e32 v34, v34, v35
	v_max_i32_e32 v35, v40, v31
	v_min_i32_e32 v31, v40, v31
	v_max_i32_e32 v40, v27, v29
	v_min_i32_e32 v27, v27, v29
	v_max_i32_e32 v29, v46, v32
	v_min_i32_e32 v32, v46, v32
	v_max_i32_e32 v46, v30, v35
	v_min_i32_e32 v30, v30, v35
	v_max_i32_e32 v35, v42, v41
	v_min_i32_e32 v41, v42, v41
	v_max_i32_e32 v42, v43, v44
	v_min_i32_e32 v43, v43, v44
	v_max_i32_e32 v44, v45, v38
	v_min_i32_e32 v38, v45, v38
	v_max_i32_e32 v45, v34, v39
	v_min_i32_e32 v34, v34, v39
	v_max_i32_e32 v39, v40, v31
	v_min_i32_e32 v31, v40, v31
	v_max_i32_e32 v40, v29, v35
	v_min_i32_e32 v29, v29, v35
	v_max_i32_e32 v35, v32, v41
	v_min_i32_e32 v32, v32, v41
	v_max_i32_e32 v41, v42, v44
	v_min_i32_e32 v42, v42, v44
	v_max_i32_e32 v44, v43, v38
	v_min_i32_e32 v38, v43, v38
	v_max_i32_e32 v43, v45, v39
	v_min_i32_e32 v39, v45, v39
	v_max_i32_e32 v45, v34, v31
	v_min_i32_e32 v31, v34, v31
	v_max_i32_e32 v34, v35, v29
	v_min_i32_e32 v29, v35, v29
	v_max_i32_e32 v35, v46, v32
	v_min_i32_e32 v32, v46, v32
	v_max_i32_e32 v46, v43, v30
	v_min_i32_e32 v30, v43, v30
	v_max_i32_e32 v43, v45, v39
	v_min_i32_e32 v39, v45, v39
	v_max_i32_e32 v45, v35, v41
	v_min_i32_e32 v35, v35, v41
	v_max_i32_e32 v41, v32, v42
	v_min_i32_e32 v32, v32, v42
	v_max_i32_e32 v42, v44, v46
	v_min_i32_e32 v44, v44, v46
	v_max_i32_e32 v46, v38, v30
	v_min_i32_e32 v30, v38, v30
	v_max_i32_e32 v38, v45, v29
	v_min_i32_e32 v29, v45, v29
	v_max_i32_e32 v45, v35, v41
	v_min_i32_e32 v35, v35, v41
	v_max_i32_e32 v41, v42, v32
	v_min_i32_e32 v32, v42, v32
	v_max_i32_e32 v42, v44, v46
	v_min_i32_e32 v44, v44, v46
	v_max_i32_e32 v46, v43, v30
	v_min_i32_e32 v30, v43, v30
	v_max_i32_e32 v43, v35, v41
	v_min_i32_e32 v35, v35, v41
	v_max_i32_e32 v41, v32, v42
	v_min_i32_e32 v32, v32, v42
	ds_bpermute_b32 v54, v123, v41
	ds_bpermute_b32 v55, v123, v32
	ds_bpermute_b32 v56, v123, v44
	ds_bpermute_b32 v57, v123, v27
	ds_bpermute_b32 v58, v123, v31
	ds_bpermute_b32 v59, v123, v39
	ds_bpermute_b32 v60, v123, v30
	ds_bpermute_b32 v61, v123, v46
	ds_bpermute_b32 v42, v123, v37
	ds_bpermute_b32 v47, v123, v40
	ds_bpermute_b32 v48, v123, v34
	ds_bpermute_b32 v49, v123, v38
	ds_bpermute_b32 v50, v123, v29
	ds_bpermute_b32 v51, v123, v45
	ds_bpermute_b32 v52, v123, v43
	ds_bpermute_b32 v53, v123, v35
	s_waitcnt lgkmcnt(12)
	v_max_i32_e32 v37, v37, v57
	s_waitcnt lgkmcnt(11)
	v_max_i32_e32 v40, v40, v58
	s_waitcnt lgkmcnt(10)
	v_max_i32_e32 v34, v34, v59
	s_waitcnt lgkmcnt(9)
	v_max_i32_e32 v38, v38, v60
	s_waitcnt lgkmcnt(8)
	v_max_i32_e32 v29, v29, v61
	v_max_i32_e32 v45, v45, v56
	v_max_i32_e32 v43, v43, v55
	v_max_i32_e32 v35, v35, v54
	v_add_f32_e32 v28, v78, v28
	v_add_f32_e32 v54, v77, v26
	v_add_f32_e32 v55, v77, v33
	v_add_f32_e32 v36, v77, v36
	v_add_f32_e32 v56, v76, v26
	v_add_f32_e32 v57, v76, v33
	v_add_f32_e32 v58, v75, v26
	v_add_f32_e32 v59, v75, v33
	v_add_f32_e32 v60, v73, v26
	v_add_f32_e32 v33, v73, v33
	v_add_f32_e32 v61, v71, v26
	v_add_f32_e32 v65, v69, v26
	v_add_f32_e32 v68, v68, v26
	v_or_b32_e32 v28, 0xff, v28
	v_or_b32_e32 v54, 0xff, v54
	v_or_b32_e32 v55, 0xff, v55
	v_or_b32_e32 v36, 0xff, v36
	v_or_b32_e32 v56, 0xff, v56
	v_or_b32_e32 v57, 0xff, v57
	v_or_b32_e32 v58, 0xff, v58
	v_or_b32_e32 v59, 0xff, v59
	v_or_b32_e32 v60, 0xff, v60
	v_or_b32_e32 v33, 0xff, v33
	v_or_b32_e32 v61, 0xff, v61
	v_or_b32_e32 v62, 0xff, v62
	v_or_b32_e32 v63, 0xff, v63
	v_or_b32_e32 v64, 0xff, v64
	v_or_b32_e32 v65, 0xff, v65
	v_or_b32_e32 v68, 0xff, v68
	v_subrev_u32_e32 v28, 51, v28
	v_subrev_u32_e32 v54, 64, v54
	v_add_u32_e32 v55, 0xffffffbf, v55
	v_add_u32_e32 v36, 0xffffffbe, v36
	v_add_u32_e32 v56, 0xffffffb0, v56
	v_add_u32_e32 v57, 0xffffffaf, v57
	v_add_u32_e32 v58, 0xffffffa0, v58
	v_add_u32_e32 v59, 0xffffff9f, v59
	v_add_u32_e32 v60, 0xffffff90, v60
	v_add_u32_e32 v33, 0xffffff8f, v33
	v_add_u32_e32 v61, 0xffffff80, v61
	v_add_u32_e32 v62, 0xffffff70, v62
	v_add_u32_e32 v63, 0xffffff60, v63
	v_add_u32_e32 v64, 0xffffff50, v64
	v_add_u32_e32 v65, 0xffffff40, v65
	v_add_u32_e32 v68, 0xffffff30, v68
	v_max_i32_e32 v69, v28, v64
	v_min_i32_e32 v28, v28, v64
	v_max_i32_e32 v64, v54, v63
	v_min_i32_e32 v54, v54, v63
	v_max_i32_e32 v63, v55, v68
	v_min_i32_e32 v55, v55, v68
	v_max_i32_e32 v68, v36, v65
	v_min_i32_e32 v36, v36, v65
	v_max_i32_e32 v65, v56, v60
	v_min_i32_e32 v56, v56, v60
	v_max_i32_e32 v60, v57, v58
	v_min_i32_e32 v57, v57, v58
	v_max_i32_e32 v58, v59, v62
	v_min_i32_e32 v59, v59, v62
	v_max_i32_e32 v62, v33, v61
	v_min_i32_e32 v33, v33, v61
	v_max_i32_e32 v61, v69, v60
	v_min_i32_e32 v60, v69, v60
	v_max_i32_e32 v69, v64, v58
	v_min_i32_e32 v58, v64, v58
	v_max_i32_e32 v64, v63, v62
	v_min_i32_e32 v62, v63, v62
	v_max_i32_e32 v63, v68, v65
	v_min_i32_e32 v65, v68, v65
	v_max_i32_e32 v68, v57, v28
	v_min_i32_e32 v28, v57, v28
	v_max_i32_e32 v57, v56, v36
	v_min_i32_e32 v36, v56, v36
	v_max_i32_e32 v56, v33, v55
	v_min_i32_e32 v33, v33, v55
	v_max_i32_e32 v55, v59, v54
	v_min_i32_e32 v54, v59, v54
	v_max_i32_e32 v59, v61, v69
	v_min_i32_e32 v61, v61, v69
	v_max_i32_e32 v69, v64, v63
	v_min_i32_e32 v63, v64, v63
	v_max_i32_e32 v64, v65, v60
	v_min_i32_e32 v60, v65, v60
	v_max_i32_e32 v65, v68, v57
	v_min_i32_e32 v57, v68, v57
	v_max_i32_e32 v68, v58, v62
	v_min_i32_e32 v58, v58, v62
	v_max_i32_e32 v62, v56, v55
	v_min_i32_e32 v55, v56, v55
	v_max_i32_e32 v56, v54, v28
	v_min_i32_e32 v28, v54, v28
	v_max_i32_e32 v54, v36, v33
	v_min_i32_e32 v33, v36, v33
	v_min_i32_e32 v36, v59, v69
	v_max_i32_e32 v70, v61, v63
	v_min_i32_e32 v61, v61, v63
	v_max_i32_e32 v63, v64, v62
	v_min_i32_e32 v62, v64, v62
	v_max_i32_e32 v64, v60, v55
	v_min_i32_e32 v55, v60, v55
	v_max_i32_e32 v60, v65, v68
	v_min_i32_e32 v65, v65, v68
	v_max_i32_e32 v68, v57, v58
	v_min_i32_e32 v57, v57, v58
	v_max_i32_e32 v58, v56, v54
	v_min_i32_e32 v54, v56, v54
	v_max_i32_e32 v56, v28, v33
	v_min_i32_e32 v28, v28, v33
	v_max_i32_e32 v33, v70, v36
	v_min_i32_e32 v36, v70, v36
	v_max_i32_e32 v70, v61, v58
	v_min_i32_e32 v58, v61, v58
	v_max_i32_e32 v61, v63, v60
	v_min_i32_e32 v60, v63, v60
	v_max_i32_e32 v63, v64, v65
	v_min_i32_e32 v64, v64, v65
	v_max_i32_e32 v65, v68, v62
	v_min_i32_e32 v62, v68, v62
	v_max_i32_e32 v68, v57, v55
	v_min_i32_e32 v55, v57, v55
	v_max_i32_e32 v57, v56, v54
	s_waitcnt lgkmcnt(0)
; #define CAND(a, b) (int)((__float_as_uint(__int_as_float(top[0][a]) + __int_as_float(top[1][b])) | 255u) - (unsigned)((a) * 16 + (b)))
; __device__ __forceinline__ void route_task(int task, int tl0, const bf16* QP  , const LAS bf16* KHL, LAS unsigned short* EL, LAS float* GL, int lane) {
;     ...
;         int oth[16];
; #pragma unroll
;         for (int i = 0; i < 16; ++i) oth[i] = __shfl_xor(bk[i], 32);
;         merge16_desc(bk, oth);
;     }
;     ...
;     {
;         int gk[16];
;         gk[0] = CAND(3, 3); gk[1] = CAND(4, 0); gk[2] = CAND(4, 1); gk[3] = CAND(4, 2); gk[4] = CAND(5, 0); gk[5] = CAND(5, 1); gk[6] = CAND(6, 0); gk[7] = CAND(6, 1);
;         gk[8] = CAND(7, 0); gk[9] = CAND(7, 1); gk[10] = CAND(8, 0); gk[11] = CAND(9, 0); gk[12] = CAND(10, 0); gk[13] = CAND(11, 0); gk[14] = CAND(12, 0); gk[15] = CAND(13, 0);
;         sort16_desc(gk);
;         merge16_desc(bk, gk);
;     }
;     {
;         const int c14 = CAND(14, 0), c15 = CAND(15, 0);
;         const int n14 = max(bk[14], c14), n15 = max(min(bk[14], c14), max(bk[15], c15));
;         bk[14] = n14; bk[15] = n15;
;     }
	v_max_i32_e32 v41, v41, v53
	v_max_i32_e32 v32, v32, v52
	v_max_i32_e32 v44, v44, v51
	v_max_i32_e32 v46, v46, v50
	v_max_i32_e32 v30, v30, v49
	v_max_i32_e32 v39, v39, v48
	v_max_i32_e32 v31, v31, v47
	v_max_i32_e32 v27, v27, v42
	v_min_i32_e32 v54, v56, v54
	v_max_i32_e32 v56, v33, v61
	v_min_i32_e32 v33, v33, v61
	v_max_i32_e32 v61, v36, v60
	v_min_i32_e32 v36, v36, v60
	v_max_i32_e32 v60, v63, v65
	v_min_i32_e32 v63, v63, v65
	v_max_i32_e32 v65, v64, v62
	v_min_i32_e32 v62, v64, v62
	v_max_i32_e32 v64, v68, v57
	v_max_i32_e32 v42, v37, v41
	v_min_i32_e32 v37, v37, v41
	v_max_i32_e32 v41, v40, v32
	v_min_i32_e32 v32, v40, v32
	v_max_i32_e32 v40, v34, v44
	v_min_i32_e32 v34, v34, v44
	v_max_i32_e32 v44, v38, v46
	v_min_i32_e32 v38, v38, v46
	v_max_i32_e32 v46, v29, v30
	v_min_i32_e32 v29, v29, v30
	v_max_i32_e32 v30, v45, v39
	v_min_i32_e32 v39, v45, v39
	v_max_i32_e32 v45, v43, v31
	v_min_i32_e32 v31, v43, v31
	v_max_i32_e32 v43, v35, v27
	v_min_i32_e32 v27, v35, v27
	v_min_i32_e32 v57, v68, v57
	v_max_i32_e32 v68, v55, v54
	v_max_i32_e32 v71, v70, v36
	v_min_i32_e32 v36, v70, v36
	v_max_i32_e32 v70, v64, v58
	v_min_i32_e32 v58, v64, v58
	v_max_i32_e32 v35, v42, v46
	v_min_i32_e32 v42, v42, v46
	v_max_i32_e32 v46, v41, v30
	v_min_i32_e32 v30, v41, v30
	v_max_i32_e32 v41, v40, v45
	v_min_i32_e32 v40, v40, v45
	v_max_i32_e32 v45, v44, v43
	v_min_i32_e32 v43, v44, v43
	v_max_i32_e32 v44, v37, v29
	v_min_i32_e32 v29, v37, v29
	v_max_i32_e32 v37, v32, v39
	v_min_i32_e32 v32, v32, v39
	v_max_i32_e32 v39, v34, v31
	v_min_i32_e32 v31, v34, v31
	v_max_i32_e32 v34, v38, v27
	v_min_i32_e32 v27, v38, v27
	v_min_i32_e32 v54, v55, v54
	v_min_i32_e32 v55, v61, v33
	v_max_i32_e32 v64, v68, v57
	v_min_i32_e32 v57, v68, v57
	v_max_i32_e32 v68, v71, v60
	v_min_i32_e32 v60, v71, v60
	v_max_i32_e32 v71, v36, v63
	v_min_i32_e32 v36, v36, v63
	v_max_i32_e32 v63, v65, v70
	v_min_i32_e32 v65, v65, v70
	v_max_i32_e32 v70, v62, v58
	v_max_i32_e32 v38, v35, v41
	v_min_i32_e32 v35, v35, v41
	v_max_i32_e32 v41, v46, v45
	v_min_i32_e32 v45, v46, v45
	v_max_i32_e32 v46, v42, v40
	v_min_i32_e32 v40, v42, v40
	v_max_i32_e32 v42, v30, v43
	v_min_i32_e32 v30, v30, v43
	v_max_i32_e32 v43, v44, v39
	v_min_i32_e32 v39, v44, v39
	v_max_i32_e32 v44, v37, v34
	v_min_i32_e32 v34, v37, v34
	v_max_i32_e32 v37, v29, v31
	v_min_i32_e32 v29, v29, v31
	v_max_i32_e32 v31, v32, v27
	v_min_i32_e32 v27, v32, v27
	v_min_i32_e32 v58, v62, v58
	v_max_i32_e32 v62, v68, v55
	v_min_i32_e32 v55, v68, v55
	v_max_i32_e32 v68, v60, v71
	v_min_i32_e32 v60, v60, v71
	v_max_i32_e32 v71, v63, v36
	v_min_i32_e32 v36, v63, v36
	v_max_i32_e32 v63, v65, v70
	v_min_i32_e32 v32, v38, v41
	v_min_i32_e32 v47, v35, v45
	v_min_i32_e32 v48, v46, v42
	v_min_i32_e32 v49, v40, v30
	v_min_i32_e32 v50, v43, v44
	v_min_i32_e32 v51, v39, v34
	v_min_i32_e32 v52, v37, v31
	v_min_i32_e32 v53, v29, v27
	v_min_i32_e32 v65, v65, v70
	v_max_i32_e32 v70, v64, v58
	v_min_i32_e32 v58, v64, v58
	v_min_i32_e32 v64, v60, v71
	v_min_i32_e32 v72, v36, v63
	v_max3_i32 v28, v38, v41, v28
	v_max_i32_e32 v32, v32, v54
	v_max3_i32 v35, v35, v45, v57
	v_max_i32_e32 v38, v47, v58
	v_max3_i32 v41, v46, v42, v70
	v_max_i32_e32 v42, v48, v65
	v_max3_i32 v30, v40, v30, v72
	v_max3_i32 v36, v49, v36, v63
	v_max3_i32 v40, v43, v44, v64
	v_max3_i32 v43, v50, v60, v71
	v_max3_i32 v34, v39, v34, v68
	v_max_i32_e32 v39, v51, v55
	v_max3_i32 v31, v37, v31, v62
	v_max3_i32 v33, v52, v61, v33
	v_max3_i32 v27, v29, v27, v56
	v_max3_i32 v29, v53, v59, v69
	v_max_i32_e32 v37, v28, v40
	v_min_i32_e32 v28, v28, v40
	v_max_i32_e32 v40, v32, v43
	v_min_i32_e32 v32, v32, v43
	v_max_i32_e32 v43, v35, v34
	v_min_i32_e32 v34, v35, v34
	v_max_i32_e32 v35, v38, v39
	v_min_i32_e32 v38, v38, v39
	v_max_i32_e32 v39, v41, v31
	v_min_i32_e32 v31, v41, v31
	v_max_i32_e32 v41, v42, v33
	v_min_i32_e32 v33, v42, v33
	v_max_i32_e32 v42, v30, v27
	v_min_i32_e32 v27, v30, v27
	v_max_i32_e32 v30, v36, v29
	v_min_i32_e32 v29, v36, v29
	v_max_i32_e32 v36, v37, v39
	v_min_i32_e32 v37, v37, v39
	v_max_i32_e32 v39, v40, v41
	v_min_i32_e32 v40, v40, v41
	v_max_i32_e32 v41, v43, v42
	v_min_i32_e32 v42, v43, v42
	v_max_i32_e32 v43, v35, v30
	v_min_i32_e32 v30, v35, v30
	v_max_i32_e32 v35, v28, v31
	v_min_i32_e32 v28, v28, v31
	v_max_i32_e32 v31, v32, v33
	v_min_i32_e32 v32, v32, v33
	v_max_i32_e32 v33, v34, v27
	v_min_i32_e32 v27, v34, v27
	v_max_i32_e32 v34, v38, v29
	v_min_i32_e32 v29, v38, v29
	v_max_i32_e32 v38, v36, v41
	v_min_i32_e32 v36, v36, v41
	v_max_i32_e32 v41, v39, v43
	v_min_i32_e32 v39, v39, v43
	v_max_i32_e32 v43, v37, v42
	v_min_i32_e32 v37, v37, v42
	v_max_i32_e32 v42, v40, v30
	v_min_i32_e32 v30, v40, v30
	v_max_i32_e32 v40, v35, v33
	v_min_i32_e32 v33, v35, v33
	v_max_i32_e32 v35, v31, v34
	v_min_i32_e32 v31, v31, v34
	v_max_i32_e32 v34, v28, v27
	v_min_i32_e32 v27, v28, v27
	v_max_i32_e32 v28, v32, v29
	v_min_i32_e32 v29, v32, v29
	v_max_i32_e32 v32, v38, v41
	v_min_i32_e32 v38, v38, v41
	v_max_i32_e32 v41, v36, v39
	v_min_i32_e32 v36, v36, v39
	v_max_i32_e32 v39, v43, v42
	v_min_i32_e32 v42, v43, v42
	v_max_i32_e32 v43, v37, v30
	v_min_i32_e32 v30, v37, v30
	v_max_i32_e32 v37, v40, v35
	v_min_i32_e32 v35, v40, v35
	v_max_i32_e32 v40, v33, v31
	v_min_i32_e32 v31, v33, v31
	v_max_i32_e32 v33, v34, v28
	v_min_i32_e32 v28, v34, v28
	v_max_i32_e32 v34, v27, v29
	v_min_i32_e32 v27, v27, v29
	v_add_f32_e32 v29, v67, v26
	v_or_b32_e32 v29, 0xff, v29
	v_add_f32_e32 v26, v66, v26
	v_add_u32_e32 v29, 0xffffff20, v29
	v_or_b32_e32 v26, 0xff, v26
	v_add_u32_e32 v26, 0xffffff10, v26
	v_max_i32_e32 v44, v34, v29
	v_min_i32_e32 v29, v34, v29
	v_max3_i32 v26, v29, v27, v26
; __device__ __forceinline__ void route_task(int task, int tl0, const bf16* QP  , const LAS bf16* KHL, LAS unsigned short* EL, LAS float* GL, int lane) {
;     ...
;     int my[8];
; #pragma unroll
;     for (int i = 0; i < 8; ++i) { int lo_ = bk[i], hi_ = bk[8 + i]; asm volatile("" : "+v"(lo_), "+v"(hi_)); my[i] = hi ? hi_ : lo_; }
;     int bv[8];
; #pragma unroll
;     for (int i = 0; i < 8; ++i) {
;         const unsigned cd = 255u - ((unsigned)my[i] & 255u), ca = cd >> 4, cb = cd & 15u;
;         const unsigned wa = (ca >> 2) == 0u ? P1[0] : (ca >> 2) == 1u ? P1[1] : (ca >> 2) == 2u ? P1[2] : P1[3];
;         const unsigned wb = (cb >> 2) == 0u ? P2[0] : (cb >> 2) == 1u ? P2[1] : (cb >> 2) == 2u ? P2[2] : P2[3];
;         bv[i] = (int)((((wa >> (8u * (ca & 3u))) & 255u) << 7) | ((wb >> (8u * (cb & 3u))) & 255u));
;     }
	v_mov_b32_e32 v27, v32
	s_nop 0
	v_cndmask_b32_e64 v27, v37, v27, s[6:7]
	v_not_b32_e32 v29, v27
	v_bfe_u32 v45, v29, 6, 2
	v_cmp_eq_u32_e32 vcc, 2, v45
	v_cndmask_b32_e64 v30, v26, v30, s[6:7]
	v_bitop3_b32 v26, v27, s3, v27 bitop3:0xc
	v_cndmask_b32_e32 v46, v25, v23, vcc
	v_cmp_eq_u32_e32 vcc, 1, v45
	v_cndmask_b32_e64 v34, v35, v38, s[6:7]
	v_not_b32_e32 v35, v34
	v_cndmask_b32_e32 v45, v46, v21, vcc
	v_cmp_gt_u32_e32 vcc, 64, v26
	v_cndmask_b32_e64 v37, v40, v41, s[6:7]
	v_cndmask_b32_e64 v41, v44, v43, s[6:7]
	v_cndmask_b32_e32 v26, v45, v19, vcc
	v_bfe_u32 v45, v29, 2, 2
	v_cmp_eq_u32_e32 vcc, 2, v45
	v_bitop3_b32 v44, v27, 15, v27 bitop3:0xc
	v_bfe_u32 v47, v35, 6, 2
	v_cndmask_b32_e32 v46, v24, v22, vcc
	v_cmp_eq_u32_e32 vcc, 1, v45
	v_not_b32_e32 v38, v37
	v_bfe_u32 v49, v38, 6, 2
	v_cndmask_b32_e32 v45, v46, v20, vcc
	v_cmp_gt_u32_e32 vcc, 4, v44
	v_bitop3_b32 v46, v34, 15, v34 bitop3:0xc
	v_cndmask_b32_e64 v31, v31, v36, s[6:7]
	v_cndmask_b32_e32 v44, v45, v18, vcc
	v_cmp_eq_u32_e32 vcc, 2, v47
	v_bitop3_b32 v45, v34, s3, v34 bitop3:0xc
	v_not_b32_e32 v36, v31
	v_cndmask_b32_e32 v48, v25, v23, vcc
	v_cmp_eq_u32_e32 vcc, 1, v47
	v_bfe_u32 v51, v36, 6, 2
	v_cndmask_b32_e64 v33, v33, v39, s[6:7]
	v_cndmask_b32_e32 v47, v48, v21, vcc
	v_cmp_gt_u32_e32 vcc, 64, v45
	v_not_b32_e32 v39, v33
	v_bfe_u32 v53, v39, 6, 2
	v_cndmask_b32_e32 v45, v47, v19, vcc
	v_bfe_u32 v47, v35, 2, 2
	v_cmp_eq_u32_e32 vcc, 2, v47
	v_cndmask_b32_e64 v28, v28, v42, s[6:7]
	v_not_b32_e32 v40, v28
	v_cndmask_b32_e32 v48, v24, v22, vcc
	v_cmp_eq_u32_e32 vcc, 1, v47
	v_bfe_u32 v55, v40, 6, 2
	v_not_b32_e32 v42, v41
	v_cndmask_b32_e32 v47, v48, v20, vcc
	v_cmp_gt_u32_e32 vcc, 4, v46
	v_bitop3_b32 v48, v37, 15, v37 bitop3:0xc
	v_bfe_u32 v57, v42, 6, 2
	v_cndmask_b32_e32 v46, v47, v18, vcc
	v_cmp_eq_u32_e32 vcc, 2, v49
	v_bitop3_b32 v47, v37, s3, v37 bitop3:0xc
	v_not_b32_e32 v43, v30
	v_cndmask_b32_e32 v50, v25, v23, vcc
	v_cmp_eq_u32_e32 vcc, 1, v49
	v_bfe_u32 v59, v43, 6, 2
	s_nop 0
	v_cndmask_b32_e32 v49, v50, v21, vcc
	v_cmp_gt_u32_e32 vcc, 64, v47
	s_nop 1
	v_cndmask_b32_e32 v47, v49, v19, vcc
	v_bfe_u32 v49, v38, 2, 2
	v_cmp_eq_u32_e32 vcc, 2, v49
	s_nop 1
	v_cndmask_b32_e32 v50, v24, v22, vcc
	v_cmp_eq_u32_e32 vcc, 1, v49
	s_nop 1
	v_cndmask_b32_e32 v49, v50, v20, vcc
	v_cmp_gt_u32_e32 vcc, 4, v48
	v_bitop3_b32 v50, v31, 15, v31 bitop3:0xc
	s_nop 0
	v_cndmask_b32_e32 v48, v49, v18, vcc
	v_cmp_eq_u32_e32 vcc, 2, v51
	v_bitop3_b32 v49, v31, s3, v31 bitop3:0xc
	s_nop 0
	v_cndmask_b32_e32 v52, v25, v23, vcc
	v_cmp_eq_u32_e32 vcc, 1, v51
	s_nop 1
	v_cndmask_b32_e32 v51, v52, v21, vcc
	v_cmp_gt_u32_e32 vcc, 64, v49
	s_nop 1
	v_cndmask_b32_e32 v49, v51, v19, vcc
	v_bfe_u32 v51, v36, 2, 2
	v_cmp_eq_u32_e32 vcc, 2, v51
	s_nop 1
	v_cndmask_b32_e32 v52, v24, v22, vcc
	v_cmp_eq_u32_e32 vcc, 1, v51
	s_nop 1
	v_cndmask_b32_e32 v51, v52, v20, vcc
	v_cmp_gt_u32_e32 vcc, 4, v50
	v_bitop3_b32 v52, v33, 15, v33 bitop3:0xc
	s_nop 0
	v_cndmask_b32_e32 v50, v51, v18, vcc
	v_cmp_eq_u32_e32 vcc, 2, v53
	v_bitop3_b32 v51, v33, s3, v33 bitop3:0xc
	s_nop 0
	v_cndmask_b32_e32 v54, v25, v23, vcc
	v_cmp_eq_u32_e32 vcc, 1, v53
	s_nop 1
	v_cndmask_b32_e32 v53, v54, v21, vcc
	v_cmp_gt_u32_e32 vcc, 64, v51
	s_nop 1
	v_cndmask_b32_e32 v51, v53, v19, vcc
	v_bfe_u32 v53, v39, 2, 2
	v_cmp_eq_u32_e32 vcc, 2, v53
	s_nop 1
	v_cndmask_b32_e32 v54, v24, v22, vcc
	v_cmp_eq_u32_e32 vcc, 1, v53
	s_nop 1
	v_cndmask_b32_e32 v53, v54, v20, vcc
	v_cmp_gt_u32_e32 vcc, 4, v52
	v_bitop3_b32 v54, v28, 15, v28 bitop3:0xc
	s_nop 0
	v_cndmask_b32_e32 v52, v53, v18, vcc
	v_cmp_eq_u32_e32 vcc, 2, v55
	v_bitop3_b32 v53, v28, s3, v28 bitop3:0xc
	s_nop 0
	v_cndmask_b32_e32 v56, v25, v23, vcc
	v_cmp_eq_u32_e32 vcc, 1, v55
	s_nop 1
	v_cndmask_b32_e32 v55, v56, v21, vcc
	v_cmp_gt_u32_e32 vcc, 64, v53
	s_nop 1
	v_cndmask_b32_e32 v53, v55, v19, vcc
	v_bfe_u32 v55, v40, 2, 2
	v_cmp_eq_u32_e32 vcc, 2, v55
	s_nop 1
	v_cndmask_b32_e32 v56, v24, v22, vcc
	v_cmp_eq_u32_e32 vcc, 1, v55
	s_nop 1
	v_cndmask_b32_e32 v55, v56, v20, vcc
	v_cmp_gt_u32_e32 vcc, 4, v54
	v_bitop3_b32 v56, v41, 15, v41 bitop3:0xc
	s_nop 0
	v_cndmask_b32_e32 v54, v55, v18, vcc
	v_cmp_eq_u32_e32 vcc, 2, v57
	v_bitop3_b32 v55, v41, s3, v41 bitop3:0xc
	s_nop 0
	v_cndmask_b32_e32 v58, v25, v23, vcc
	v_cmp_eq_u32_e32 vcc, 1, v57
	s_nop 1
	v_cndmask_b32_e32 v57, v58, v21, vcc
	v_cmp_gt_u32_e32 vcc, 64, v55
	s_nop 1
	v_cndmask_b32_e32 v55, v57, v19, vcc
	v_bfe_u32 v57, v42, 2, 2
	v_cmp_eq_u32_e32 vcc, 2, v57
	s_nop 1
	v_cndmask_b32_e32 v58, v24, v22, vcc
	v_cmp_eq_u32_e32 vcc, 1, v57
	s_nop 1
	v_cndmask_b32_e32 v57, v58, v20, vcc
	v_cmp_gt_u32_e32 vcc, 4, v56
	v_bitop3_b32 v58, v30, 15, v30 bitop3:0xc
	s_nop 0
	v_cndmask_b32_e32 v56, v57, v18, vcc
	v_cmp_eq_u32_e32 vcc, 2, v59
	v_bitop3_b32 v57, v30, s3, v30 bitop3:0xc
	s_nop 0
	v_cndmask_b32_e32 v23, v25, v23, vcc
	v_cmp_eq_u32_e32 vcc, 1, v59
	v_sub_f32_e32 v25, v31, v32
	v_mul_f32_e32 v25, 0x3fb8aa3b, v25
	v_cndmask_b32_e32 v21, v23, v21, vcc
	v_cmp_gt_u32_e32 vcc, 64, v57
	v_lshrrev_b32_e32 v23, 1, v39
	v_and_b32_e32 v23, 24, v23
	v_cndmask_b32_e32 v19, v21, v19, vcc
	v_bfe_u32 v21, v43, 2, 2
	v_cmp_eq_u32_e32 vcc, 2, v21
	v_lshrrev_b32_e32 v23, v23, v51
	v_lshlrev_b32_e32 v23, 7, v23
	v_cndmask_b32_e32 v22, v24, v22, vcc
	v_cmp_eq_u32_e32 vcc, 1, v21
	v_lshrrev_b32_e32 v21, 1, v42
	v_and_b32_e32 v21, 24, v21
	v_cndmask_b32_e32 v20, v22, v20, vcc
	v_cmp_gt_u32_e32 vcc, 4, v58
	v_lshrrev_b32_e32 v21, v21, v55
	v_lshrrev_b32_e32 v22, 1, v40
	v_cndmask_b32_e32 v18, v20, v18, vcc
	v_lshlrev_b32_e32 v20, 3, v42
	v_lshlrev_b32_e32 v21, 7, v21
	v_and_b32_e32 v22, 24, v22
	v_lshrrev_b32_e32 v20, v20, v56
; #define LAS __attribute__((address_space(3)))
; __device__ __forceinline__ void peer_u_item(int p, int j, const LAS unsigned short* EL  , const unsigned char* __restrict__ XQ, const unsigned char* __restrict__ U8, LAS int* ACC  , int lane, int wave) {
;     ...
;     const int gidx = lane >> 3; const unsigned coff = (unsigned)(p * 128 + (lane & 7) * 16), toff = (unsigned)(p * (16384 * 128) + (lane & 7) * 16);
; #pragma unroll 1
;     for (int it = 0; it < 8; ++it) {
;         const int t = j * 64 + it * 8 + wave;
;         unsigned E[8];
;         { const LAS v4u* ep = (const LAS v4u*)(EL + (it * 8 + wave) * 128 + 16 * gidx); const v4u e0 = ep[0], e1 = ep[1];
;           E[0] = e0.x; E[1] = e0.y; E[2] = e0.z; E[3] = e0.w; E[4] = e1.x; E[5] = e1.y; E[6] = e1.z; E[7] = e1.w; }
;         uint4 uu[16];
; #pragma unroll
;         for (int i = 0; i < 16; ++i) uu[i] = *(const uint4*)(U8 + (size_t)(PE_ID(E, i) * 128u + toff));
;         const uint4 xh = *(const uint4*)(XQ + (size_t)t * 512 + coff), xl = *(const uint4*)(XQ + 8 * MiB + (size_t)t * 512 + coff);
; __device__ __forceinline__ void route_task(int task, int tl0, const bf16* QP  , const LAS bf16* KHL, LAS unsigned short* EL, LAS float* GL, int lane) {
;     ...
;         bv[i] = (int)((((wa >> (8u * (ca & 3u))) & 255u) << 7) | ((wb >> (8u * (cb & 3u))) & 255u));
;     }
;     float e[8], se = 0.f;
; #pragma unroll
;     for (int i = 0; i < 8; ++i) { e[i] = __expf(__int_as_float(my[i]) - __int_as_float(bk[0])); se += e[i]; }
;     se += __shfl_xor(se, 32);
;     const float inv = 1.f / se;
;     {
;         int l2 = lane; asm volatile("" : "+v"(l2));
;         const int o2 = (tl0 + ((l2 & 31) >> 3)) * 128 + (l2 & 7) * 16 + 8 * (l2 >> 5);
;         LAS v4u* ip = (LAS v4u*)(EL + o2); typedef float f4v __attribute__((ext_vector_type(4))); LAS f4v* gp = (LAS f4v*)(GL + o2);
;         ip[0] = (v4u){(unsigned)bv[0] | ((unsigned)bv[1] << 16), (unsigned)bv[2] | ((unsigned)bv[3] << 16), (unsigned)bv[4] | ((unsigned)bv[5] << 16), (unsigned)bv[6] | ((unsigned)bv[7] << 16)};
;         gp[0] = (f4v){e[0] * inv, e[1] * inv, e[2] * inv, e[3] * inv}; gp[1] = (f4v){e[4] * inv, e[5] * inv, e[6] * inv, e[7] * inv};
;     }
	v_and_b32_e32 v21, 0x7f80, v21
	v_lshrrev_b32_e32 v22, v22, v53
	v_and_or_b32 v21, v20, s3, v21
	v_lshlrev_b32_e32 v20, 3, v40
	v_lshlrev_b32_e32 v22, 7, v22
	v_lshrrev_b32_e32 v20, v20, v54
	v_and_b32_e32 v22, 0x7f80, v22
	v_and_or_b32 v20, v20, s3, v22
	v_lshlrev_b32_e32 v22, 3, v39
	v_lshrrev_b32_e32 v22, v22, v52
	v_and_b32_e32 v23, 0x7f80, v23
	v_and_or_b32 v39, v22, s3, v23
	v_lshrrev_b32_e32 v23, 1, v36
	v_and_b32_e32 v23, 24, v23
	v_lshrrev_b32_e32 v23, v23, v49
	v_lshlrev_b32_e32 v22, 3, v36
	v_lshlrev_b32_e32 v23, 7, v23
	v_lshrrev_b32_e32 v22, v22, v50
	v_and_b32_e32 v23, 0x7f80, v23
	v_and_or_b32 v36, v22, s3, v23
	v_lshrrev_b32_e32 v23, 1, v38
	v_and_b32_e32 v23, 24, v23
	v_lshrrev_b32_e32 v23, v23, v47
	v_lshlrev_b32_e32 v22, 3, v38
	v_lshlrev_b32_e32 v23, 7, v23
	v_lshrrev_b32_e32 v22, v22, v48
	v_and_b32_e32 v23, 0x7f80, v23
	v_and_or_b32 v38, v22, s3, v23
	v_lshrrev_b32_e32 v23, 1, v35
	v_and_b32_e32 v23, 24, v23
	v_lshrrev_b32_e32 v23, v23, v45
	v_lshlrev_b32_e32 v22, 3, v35
	v_lshlrev_b32_e32 v23, 7, v23
	v_lshrrev_b32_e32 v22, v22, v46
	v_and_b32_e32 v23, 0x7f80, v23
	v_and_or_b32 v35, v22, s3, v23
	v_lshrrev_b32_e32 v23, 1, v29
	v_and_b32_e32 v23, 24, v23
	v_lshrrev_b32_e32 v23, v23, v26
	v_lshlrev_b32_e32 v22, 3, v29
	v_lshlrev_b32_e32 v23, 7, v23
	v_lshrrev_b32_e32 v22, v22, v44
	v_and_b32_e32 v23, 0x7f80, v23
	v_and_or_b32 v40, v22, s3, v23
	v_sub_f32_e32 v22, v27, v32
	v_mul_f32_e32 v22, 0x3fb8aa3b, v22
	v_sub_f32_e32 v23, v34, v32
	v_exp_f32_e32 v22, v22
	v_mul_f32_e32 v23, 0x3fb8aa3b, v23
	v_sub_f32_e32 v24, v37, v32
	v_exp_f32_e32 v23, v23
	v_mul_f32_e32 v24, 0x3fb8aa3b, v24
	v_exp_f32_e32 v24, v24
	v_exp_f32_e32 v25, v25
	v_add_f32_e32 v26, 0, v22
	v_add_f32_e32 v26, v23, v26
	v_add_f32_e32 v26, v24, v26
	v_add_f32_e32 v31, v25, v26
	v_sub_f32_e32 v26, v33, v32
	v_mul_f32_e32 v26, 0x3fb8aa3b, v26
	v_sub_f32_e32 v27, v28, v32
	v_exp_f32_e32 v26, v26
	v_mul_f32_e32 v27, 0x3fb8aa3b, v27
	v_sub_f32_e32 v28, v41, v32
	v_exp_f32_e32 v27, v27
	v_mul_f32_e32 v28, 0x3fb8aa3b, v28
	v_sub_f32_e32 v29, v30, v32
	v_exp_f32_e32 v28, v28
	v_mul_f32_e32 v29, 0x3fb8aa3b, v29
	v_exp_f32_e32 v29, v29
	v_add_f32_e32 v30, v26, v31
	v_add_f32_e32 v30, v27, v30
	v_add_f32_e32 v30, v28, v30
	v_add_f32_e32 v30, v29, v30
	ds_bpermute_b32 v31, v123, v30
	v_lshrrev_b32_e32 v42, 1, v43
	v_and_b32_e32 v32, 24, v42
	v_lshrrev_b32_e32 v19, v32, v19
	v_lshlrev_b32_e32 v19, 7, v19
	s_waitcnt lgkmcnt(0)
	v_add_f32_e32 v30, v30, v31
	v_div_scale_f32 v31, s[12:13], v30, v30, 1.0
	v_rcp_f32_e32 v32, v31
	v_lshlrev_b32_e32 v33, 3, v43
	v_and_b32_e32 v19, 0x7f80, v19
	v_lshrrev_b32_e32 v18, v33, v18
	v_and_or_b32 v33, v18, s3, v19
	v_fma_f32 v18, -v31, v32, 1.0
	v_fmac_f32_e32 v32, v18, v32
	v_div_scale_f32 v18, vcc, 1.0, v30, 1.0
	v_mul_f32_e32 v19, v18, v32
	v_fma_f32 v34, -v31, v19, v18
	v_fmac_f32_e32 v19, v34, v32
	v_fma_f32 v18, -v31, v19, v18
	v_div_fmas_f32 v18, v18, v32, v19
	v_div_fixup_f32 v30, v18, v30, 1.0
	v_mov_b32_e32 v18, v1
	v_lshl_or_b32 v20, v20, 16, v39
	v_lshrrev_b32_e32 v19, 3, v18
	v_and_or_b32 v19, v19, 3, s57
	v_lshlrev_b32_e32 v31, 4, v18
	v_ashrrev_i32_e32 v18, 2, v18
	v_lshlrev_b32_e32 v19, 7, v19
	v_and_b32_e32 v31, 0x70, v31
	v_and_b32_e32 v18, -8, v18
	v_add3_u32 v18, v18, v31, v19
	v_lshl_add_u32 v31, v18, 1, s11
	v_lshl_add_u32 v32, v18, 2, s69
	v_lshl_or_b32 v18, v35, 16, v40
	v_lshl_or_b32 v19, v36, 16, v38
	v_lshl_or_b32 v21, v33, 16, v21
	ds_write_b128 v31, v[18:21]
	v_pk_mul_f32 v[20:21], v[24:25], v[30:31] op_sel_hi:[1,0]
	v_pk_mul_f32 v[18:19], v[22:23], v[30:31] op_sel_hi:[1,0]
	ds_write_b128 v32, v[18:21]
	v_pk_mul_f32 v[20:21], v[28:29], v[30:31] op_sel_hi:[1,0]
	v_pk_mul_f32 v[18:19], v[26:27], v[30:31] op_sel_hi:[1,0]
	ds_write_b128 v32, v[18:21] offset:16
	v_xor_b32_e32 v18, 4, v112
	v_cmp_lt_i32_e32 vcc, v18, v122
	s_waitcnt lgkmcnt(0)
	s_barrier
	v_cndmask_b32_e32 v18, v112, v18, vcc
	v_lshlrev_b32_e32 v30, 2, v18
	v_xor_b32_e32 v18, 2, v112
	v_cmp_lt_i32_e32 vcc, v18, v122
	s_nop 1
	v_cndmask_b32_e32 v18, v112, v18, vcc
	v_lshlrev_b32_e32 v31, 2, v18
	v_xor_b32_e32 v18, 1, v112
	v_cmp_lt_i32_e32 vcc, v18, v122
	s_nop 1
	v_cndmask_b32_e32 v18, v112, v18, vcc
	v_lshlrev_b32_e32 v32, 2, v18
	v_lshlrev_b32_e32 v56, 4, v1
	v_and_b32_e32 v56, 0x70, v56
	v_lshrrev_b32_e32 v59, 3, v1
	v_lshlrev_b32_e32 v59, 5, v59
	v_add_u32_e32 v59, s66, v59
	v_add_u32_e32 v59, -16, v59
	v_lshl_add_u32 v60, v1, 3, s64
	v_and_b32_e32 v38, 4, v1
	v_cmp_ne_u32_e64 s[10:11], 0, v38
	v_and_b32_e32 v38, 2, v1
	v_cmp_ne_u32_e64 s[12:13], 0, v38
	v_and_b32_e32 v38, 1, v1
	v_cmp_ne_u32_e64 s[14:15], 0, v38
	s_movk_i32 s94, 0x80
	s_mov_b32 s42, 0
	s_mov_b32 s43, 0
	s_mov_b32 s44, 1
	s_mov_b32 s45, 0
	s_lshl_b32 s32, s42, 11
	v_add_u32_e32 v39, s32, v59
	ds_read_b128 v[202:205], v39
	ds_read_b128 v[206:209], v39 offset:16
	s_lshl_b32 s46, s42, 3
	s_add_i32 s46, s46, s40
	s_lshl_b32 s46, s46, 9
	s_lshl_b32 s32, s43, 7
	s_add_i32 s46, s46, s32
	v_add_u32_e32 v57, s46, v56
	global_load_dwordx4 v[186:189], v57, s[34:35]
	global_load_dwordx4 v[190:193], v57, s[36:37]
	v_mov_b32_e32 v58, v56
	s_waitcnt lgkmcnt(0)
	v_and_b32_e32 v38, 0xffff, v202
	v_lshl_add_u32 v38, v38, 7, v58
	global_load_dwordx4 v[122:125], v38, s[96:97]
	v_lshrrev_b32_e32 v38, 16, v202
	v_lshl_add_u32 v38, v38, 7, v58
	global_load_dwordx4 v[126:129], v38, s[96:97]
	v_and_b32_e32 v38, 0xffff, v203
	v_lshl_add_u32 v38, v38, 7, v58
	global_load_dwordx4 v[130:133], v38, s[96:97]
	v_lshrrev_b32_e32 v38, 16, v203
	v_lshl_add_u32 v38, v38, 7, v58
	global_load_dwordx4 v[134:137], v38, s[96:97]
	v_and_b32_e32 v38, 0xffff, v204
	v_lshl_add_u32 v38, v38, 7, v58
	global_load_dwordx4 v[138:141], v38, s[96:97]
	v_lshrrev_b32_e32 v38, 16, v204
	v_lshl_add_u32 v38, v38, 7, v58
	global_load_dwordx4 v[142:145], v38, s[96:97]
	v_and_b32_e32 v38, 0xffff, v205
	v_lshl_add_u32 v38, v38, 7, v58
	global_load_dwordx4 v[146:149], v38, s[96:97]
	v_lshrrev_b32_e32 v38, 16, v205
	v_lshl_add_u32 v38, v38, 7, v58
	global_load_dwordx4 v[150:153], v38, s[96:97]
	v_and_b32_e32 v38, 0xffff, v206
	v_lshl_add_u32 v38, v38, 7, v58
	global_load_dwordx4 v[154:157], v38, s[96:97]
	v_lshrrev_b32_e32 v38, 16, v206
	v_lshl_add_u32 v38, v38, 7, v58
	global_load_dwordx4 v[158:161], v38, s[96:97]
	v_and_b32_e32 v38, 0xffff, v207
	v_lshl_add_u32 v38, v38, 7, v58
	global_load_dwordx4 v[162:165], v38, s[96:97]
	v_lshrrev_b32_e32 v38, 16, v207
	v_lshl_add_u32 v38, v38, 7, v58
	global_load_dwordx4 v[166:169], v38, s[96:97]
	v_and_b32_e32 v38, 0xffff, v208
	v_lshl_add_u32 v38, v38, 7, v58
	global_load_dwordx4 v[170:173], v38, s[96:97]
	v_lshrrev_b32_e32 v38, 16, v208
	v_lshl_add_u32 v38, v38, 7, v58
	global_load_dwordx4 v[174:177], v38, s[96:97]
	v_and_b32_e32 v38, 0xffff, v209
	v_lshl_add_u32 v38, v38, 7, v58
	global_load_dwordx4 v[178:181], v38, s[96:97]
	v_lshrrev_b32_e32 v38, 16, v209
	v_lshl_add_u32 v38, v38, 7, v58
	global_load_dwordx4 v[182:185], v38, s[96:97]
	s_mov_b32 s47, 15
